# attention-B hot path with per-accumulator MFMA chains + exp under MFMA; GEMM K-loops: k-halves of each accumulator issued back-to-back; hand-written P1 epilogue
# speedup vs baseline: 1.0196x; 1.0196x over previous
.LBB0_144:
	ds_read_b128 v[152:155], v188
	ds_read_b128 v[156:159], v188 offset:1024
	ds_read_b128 v[160:163], v188 offset:2048
	ds_read_b128 v[164:167], v188 offset:3072
	ds_read_b128 v[168:171], v189
	ds_read_b128 v[172:175], v189 offset:1024
	ds_read_b128 v[176:179], v189 offset:2048
	ds_read_b128 v[194:197], v189 offset:3072
	s_add_u32 s8, s4, 0xfffc0080
	s_addc_u32 s9, s5, -1
	s_cmp_eq_u32 s43, 12
	s_cselect_b32 s21, s7, s9
	s_cselect_b32 s20, s12, s8
	s_cselect_b32 s9, s22, s37
	s_cselect_b32 s8, s23, s36
	v_lshl_add_u64 v[230:231], s[4:5], 0, v[144:145]
	s_add_i32 m0, s15, 0xc000
	ds_read_b128 v[198:201], v190
	ds_read_b128 v[202:205], v190 offset:1024
	ds_read_b128 v[206:209], v190 offset:2048
	ds_read_b128 v[210:213], v190 offset:3072
	ds_read_b128 v[214:217], v190 offset:4096
	ds_read_b128 v[218:221], v190 offset:5120
	ds_read_b128 v[222:225], v190 offset:6144
	ds_read_b128 v[226:229], v190 offset:7168
	global_load_lds_dwordx4 v[230:231], off
	v_lshl_add_u64 v[230:231], s[4:5], 0, v[146:147]
	s_add_i32 m0, s15, 0xe000
	s_nop 0
	global_load_lds_dwordx4 v[230:231], off
	s_waitcnt vmcnt(8)
	s_waitcnt lgkmcnt(0)
	s_barrier
	s_setprio 1
	s_waitcnt lgkmcnt(0)
	v_mfma_f32_16x16x32_bf16 v[124:127], v[152:155], v[198:201], v[124:127]
	v_mfma_f32_16x16x32_bf16 v[124:127], v[156:159], v[202:205], v[124:127]
	v_mfma_f32_16x16x32_bf16 v[120:123], v[160:163], v[198:201], v[120:123]
	v_mfma_f32_16x16x32_bf16 v[120:123], v[164:167], v[202:205], v[120:123]
	v_mfma_f32_16x16x32_bf16 v[108:111], v[152:155], v[206:209], v[108:111]
	v_mfma_f32_16x16x32_bf16 v[108:111], v[156:159], v[210:213], v[108:111]
	v_mfma_f32_16x16x32_bf16 v[104:107], v[160:163], v[206:209], v[104:107]
	v_mfma_f32_16x16x32_bf16 v[104:107], v[164:167], v[210:213], v[104:107]
	v_mfma_f32_16x16x32_bf16 v[92:95], v[152:155], v[214:217], v[92:95]
	v_mfma_f32_16x16x32_bf16 v[92:95], v[156:159], v[218:221], v[92:95]
	v_mfma_f32_16x16x32_bf16 v[88:91], v[160:163], v[214:217], v[88:91]
	v_mfma_f32_16x16x32_bf16 v[88:91], v[164:167], v[218:221], v[88:91]
	v_mfma_f32_16x16x32_bf16 v[76:79], v[152:155], v[222:225], v[76:79]
	v_mfma_f32_16x16x32_bf16 v[76:79], v[156:159], v[226:229], v[76:79]
	v_mfma_f32_16x16x32_bf16 v[72:75], v[160:163], v[222:225], v[72:75]
	v_mfma_f32_16x16x32_bf16 v[72:75], v[164:167], v[226:229], v[72:75]
	s_setprio 0
	s_setprio 1
	v_mfma_f32_16x16x32_bf16 v[116:119], v[168:171], v[198:201], v[116:119]
	v_mfma_f32_16x16x32_bf16 v[116:119], v[172:175], v[202:205], v[116:119]
	v_mfma_f32_16x16x32_bf16 v[112:115], v[176:179], v[198:201], v[112:115]
	v_mfma_f32_16x16x32_bf16 v[112:115], v[194:197], v[202:205], v[112:115]
	v_mfma_f32_16x16x32_bf16 v[100:103], v[168:171], v[206:209], v[100:103]
	v_mfma_f32_16x16x32_bf16 v[100:103], v[172:175], v[210:213], v[100:103]
	v_mfma_f32_16x16x32_bf16 v[96:99], v[176:179], v[206:209], v[96:99]
	v_mfma_f32_16x16x32_bf16 v[96:99], v[194:197], v[210:213], v[96:99]
	v_mfma_f32_16x16x32_bf16 v[84:87], v[168:171], v[214:217], v[84:87]
	v_mfma_f32_16x16x32_bf16 v[84:87], v[172:175], v[218:221], v[84:87]
	v_mfma_f32_16x16x32_bf16 v[80:83], v[176:179], v[214:217], v[80:83]
	v_mfma_f32_16x16x32_bf16 v[80:83], v[194:197], v[218:221], v[80:83]
	v_mfma_f32_16x16x32_bf16 v[68:71], v[168:171], v[222:225], v[68:71]
	v_mfma_f32_16x16x32_bf16 v[68:71], v[172:175], v[226:229], v[68:71]
	v_mfma_f32_16x16x32_bf16 v[64:67], v[176:179], v[222:225], v[64:67]
	v_mfma_f32_16x16x32_bf16 v[64:67], v[194:197], v[226:229], v[64:67]
	s_setprio 0
	s_barrier
	s_add_i32 s45, s57, s26
	v_lshl_add_u64 v[230:231], s[8:9], 0, v[130:131]
	s_mov_b32 m0, s45
	ds_read_b128 v[198:201], v190 offset:16384
	ds_read_b128 v[202:205], v190 offset:17408
	ds_read_b128 v[206:209], v190 offset:18432
	ds_read_b128 v[210:213], v190 offset:19456
	ds_read_b128 v[214:217], v190 offset:20480
	ds_read_b128 v[218:221], v190 offset:21504
	ds_read_b128 v[222:225], v190 offset:22528
	ds_read_b128 v[226:229], v190 offset:23552
	global_load_lds_dwordx4 v[230:231], off
	s_add_i32 m0, s45, 0x2000
	s_add_u32 s50, s8, 0x40000
	v_lshl_add_u64 v[232:233], s[8:9], 0, v[134:135]
	s_addc_u32 s51, s9, 0
	s_add_i32 s45, s58, s26
	global_load_lds_dwordx4 v[232:233], off
	v_lshl_add_u64 v[234:235], s[50:51], 0, v[130:131]
	s_mov_b32 m0, s45
	v_lshl_add_u64 v[236:237], s[20:21], 0, v[132:133]
	global_load_lds_dwordx4 v[234:235], off
	v_lshl_add_u64 v[234:235], s[50:51], 0, v[134:135]
	s_add_i32 m0, s45, 0x2000
	s_nop 0
	global_load_lds_dwordx4 v[234:235], off
	v_lshl_add_u64 v[234:235], s[20:21], 0, v[128:129]
	s_mov_b32 m0, s15
	s_nop 0
	global_load_lds_dwordx4 v[234:235], off
	s_mov_b32 m0, s27
	s_nop 0
	global_load_lds_dwordx4 v[236:237], off
	s_waitcnt vmcnt(8)
	s_waitcnt lgkmcnt(0)
	s_barrier
	s_setprio 1
	s_waitcnt lgkmcnt(0)
	v_mfma_f32_16x16x32_bf16 v[60:63], v[152:155], v[198:201], v[60:63]
	v_mfma_f32_16x16x32_bf16 v[60:63], v[156:159], v[202:205], v[60:63]
	v_mfma_f32_16x16x32_bf16 v[56:59], v[160:163], v[198:201], v[56:59]
	v_mfma_f32_16x16x32_bf16 v[56:59], v[164:167], v[202:205], v[56:59]
	v_mfma_f32_16x16x32_bf16 v[44:47], v[152:155], v[206:209], v[44:47]
	v_mfma_f32_16x16x32_bf16 v[44:47], v[156:159], v[210:213], v[44:47]
	v_mfma_f32_16x16x32_bf16 v[40:43], v[160:163], v[206:209], v[40:43]
	v_mfma_f32_16x16x32_bf16 v[40:43], v[164:167], v[210:213], v[40:43]
	v_mfma_f32_16x16x32_bf16 v[28:31], v[152:155], v[214:217], v[28:31]
	v_mfma_f32_16x16x32_bf16 v[28:31], v[156:159], v[218:221], v[28:31]
	v_mfma_f32_16x16x32_bf16 v[24:27], v[160:163], v[214:217], v[24:27]
	v_mfma_f32_16x16x32_bf16 v[24:27], v[164:167], v[218:221], v[24:27]
	v_mfma_f32_16x16x32_bf16 v[12:15], v[152:155], v[222:225], v[12:15]
	v_mfma_f32_16x16x32_bf16 v[12:15], v[156:159], v[226:229], v[12:15]
	v_mfma_f32_16x16x32_bf16 v[8:11], v[160:163], v[222:225], v[8:11]
	v_mfma_f32_16x16x32_bf16 v[8:11], v[164:167], v[226:229], v[8:11]
	s_setprio 0
	s_setprio 1
	v_mfma_f32_16x16x32_bf16 v[52:55], v[168:171], v[198:201], v[52:55]
	v_mfma_f32_16x16x32_bf16 v[52:55], v[172:175], v[202:205], v[52:55]
	v_mfma_f32_16x16x32_bf16 v[48:51], v[176:179], v[198:201], v[48:51]
	v_mfma_f32_16x16x32_bf16 v[48:51], v[194:197], v[202:205], v[48:51]
	v_mfma_f32_16x16x32_bf16 v[36:39], v[168:171], v[206:209], v[36:39]
	v_mfma_f32_16x16x32_bf16 v[36:39], v[172:175], v[210:213], v[36:39]
	v_mfma_f32_16x16x32_bf16 v[32:35], v[176:179], v[206:209], v[32:35]
	v_mfma_f32_16x16x32_bf16 v[32:35], v[194:197], v[210:213], v[32:35]
	v_mfma_f32_16x16x32_bf16 v[20:23], v[168:171], v[214:217], v[20:23]
	v_mfma_f32_16x16x32_bf16 v[20:23], v[172:175], v[218:221], v[20:23]
	v_mfma_f32_16x16x32_bf16 v[16:19], v[176:179], v[214:217], v[16:19]
	v_mfma_f32_16x16x32_bf16 v[16:19], v[194:197], v[218:221], v[16:19]
	v_mfma_f32_16x16x32_bf16 v[4:7], v[168:171], v[222:225], v[4:7]
	v_mfma_f32_16x16x32_bf16 v[4:7], v[172:175], v[226:229], v[4:7]
	v_mfma_f32_16x16x32_bf16 v[0:3], v[176:179], v[222:225], v[0:3]
	v_mfma_f32_16x16x32_bf16 v[0:3], v[194:197], v[226:229], v[0:3]
	s_setprio 0
	s_barrier
	s_add_i32 s45, 0, 0x18000
	v_add_u32_e32 v136, s45, v180
	s_add_i32 s50, 0, 0x1c000
	ds_read_b128 v[152:155], v136
	ds_read_b128 v[156:159], v136 offset:1024
	ds_read_b128 v[160:163], v136 offset:2048
	ds_read_b128 v[164:167], v136 offset:3072
	v_add_u32_e32 v136, s50, v180
	ds_read_b128 v[168:171], v136
	ds_read_b128 v[172:175], v136 offset:1024
	ds_read_b128 v[176:179], v136 offset:2048
	ds_read_b128 v[194:197], v136 offset:3072
	s_add_u32 s20, s20, 0x40000
	s_addc_u32 s21, s21, 0
	s_mov_b32 m0, s33
	v_lshl_add_u64 v[238:239], s[20:21], 0, v[128:129]
	ds_read_b128 v[198:201], v190 offset:32768
	ds_read_b128 v[202:205], v190 offset:33792
	ds_read_b128 v[206:209], v190 offset:34816
	ds_read_b128 v[210:213], v190 offset:35840
	ds_read_b128 v[214:217], v190 offset:36864
	ds_read_b128 v[218:221], v190 offset:37888
	ds_read_b128 v[222:225], v190 offset:38912
	ds_read_b128 v[226:229], v190 offset:39936
	global_load_lds_dwordx4 v[238:239], off
	v_lshl_add_u64 v[238:239], s[20:21], 0, v[132:133]
	s_mov_b32 m0, s34
	s_nop 0
	global_load_lds_dwordx4 v[238:239], off
	s_waitcnt vmcnt(8)
	s_waitcnt lgkmcnt(0)
	s_barrier
	s_setprio 1
	s_waitcnt lgkmcnt(0)
	v_mfma_f32_16x16x32_bf16 v[124:127], v[152:155], v[198:201], v[124:127]
	v_mfma_f32_16x16x32_bf16 v[124:127], v[156:159], v[202:205], v[124:127]
	v_mfma_f32_16x16x32_bf16 v[120:123], v[160:163], v[198:201], v[120:123]
	v_mfma_f32_16x16x32_bf16 v[120:123], v[164:167], v[202:205], v[120:123]
	v_mfma_f32_16x16x32_bf16 v[108:111], v[152:155], v[206:209], v[108:111]
	v_mfma_f32_16x16x32_bf16 v[108:111], v[156:159], v[210:213], v[108:111]
	v_mfma_f32_16x16x32_bf16 v[104:107], v[160:163], v[206:209], v[104:107]
	v_mfma_f32_16x16x32_bf16 v[104:107], v[164:167], v[210:213], v[104:107]
	v_mfma_f32_16x16x32_bf16 v[92:95], v[152:155], v[214:217], v[92:95]
	v_mfma_f32_16x16x32_bf16 v[92:95], v[156:159], v[218:221], v[92:95]
	v_mfma_f32_16x16x32_bf16 v[88:91], v[160:163], v[214:217], v[88:91]
	v_mfma_f32_16x16x32_bf16 v[88:91], v[164:167], v[218:221], v[88:91]
	v_mfma_f32_16x16x32_bf16 v[76:79], v[152:155], v[222:225], v[76:79]
	v_mfma_f32_16x16x32_bf16 v[76:79], v[156:159], v[226:229], v[76:79]
	v_mfma_f32_16x16x32_bf16 v[72:75], v[160:163], v[222:225], v[72:75]
	v_mfma_f32_16x16x32_bf16 v[72:75], v[164:167], v[226:229], v[72:75]
	s_setprio 0
	s_setprio 1
	v_mfma_f32_16x16x32_bf16 v[116:119], v[168:171], v[198:201], v[116:119]
	v_mfma_f32_16x16x32_bf16 v[116:119], v[172:175], v[202:205], v[116:119]
	v_mfma_f32_16x16x32_bf16 v[112:115], v[176:179], v[198:201], v[112:115]
	v_mfma_f32_16x16x32_bf16 v[112:115], v[194:197], v[202:205], v[112:115]
	v_mfma_f32_16x16x32_bf16 v[100:103], v[168:171], v[206:209], v[100:103]
	v_mfma_f32_16x16x32_bf16 v[100:103], v[172:175], v[210:213], v[100:103]
	v_mfma_f32_16x16x32_bf16 v[96:99], v[176:179], v[206:209], v[96:99]
	v_mfma_f32_16x16x32_bf16 v[96:99], v[194:197], v[210:213], v[96:99]
	v_mfma_f32_16x16x32_bf16 v[84:87], v[168:171], v[214:217], v[84:87]
	v_mfma_f32_16x16x32_bf16 v[84:87], v[172:175], v[218:221], v[84:87]
	v_mfma_f32_16x16x32_bf16 v[80:83], v[176:179], v[214:217], v[80:83]
	v_mfma_f32_16x16x32_bf16 v[80:83], v[194:197], v[218:221], v[80:83]
	v_mfma_f32_16x16x32_bf16 v[68:71], v[168:171], v[222:225], v[68:71]
	v_mfma_f32_16x16x32_bf16 v[68:71], v[172:175], v[226:229], v[68:71]
	v_mfma_f32_16x16x32_bf16 v[64:67], v[176:179], v[222:225], v[64:67]
	v_mfma_f32_16x16x32_bf16 v[64:67], v[194:197], v[226:229], v[64:67]
	s_setprio 0
	s_barrier
	s_add_i32 s20, s45, s26
	v_lshl_add_u64 v[230:231], v[230:231], 0, s[28:29]
	s_mov_b32 m0, s20
	ds_read_b128 v[198:201], v190 offset:49152
	ds_read_b128 v[202:205], v190 offset:50176
	ds_read_b128 v[206:209], v190 offset:51200
	ds_read_b128 v[210:213], v190 offset:52224
	ds_read_b128 v[214:217], v190 offset:53248
	ds_read_b128 v[218:221], v190 offset:54272
	ds_read_b128 v[222:225], v190 offset:55296
	ds_read_b128 v[226:229], v190 offset:56320
	global_load_lds_dwordx4 v[230:231], off
	s_add_i32 m0, s20, 0x2000
	s_add_u32 s8, s8, 0x40080
	v_lshl_add_u64 v[230:231], v[232:233], 0, s[28:29]
	s_addc_u32 s9, s9, 0
	s_add_i32 s20, s50, s26
	global_load_lds_dwordx4 v[230:231], off
	v_lshl_add_u64 v[230:231], s[8:9], 0, v[130:131]
	s_mov_b32 m0, s20
	s_nop 0
	global_load_lds_dwordx4 v[230:231], off
	v_lshl_add_u64 v[230:231], s[8:9], 0, v[134:135]
	s_add_i32 m0, s20, 0x2000
	s_nop 0
	global_load_lds_dwordx4 v[230:231], off
	v_lshl_add_u64 v[230:231], v[234:235], 0, s[28:29]
	s_mov_b32 m0, s38
	s_nop 0
	global_load_lds_dwordx4 v[230:231], off
	v_lshl_add_u64 v[230:231], v[236:237], 0, s[28:29]
	s_mov_b32 m0, s39
	s_nop 0
	global_load_lds_dwordx4 v[230:231], off
	s_waitcnt vmcnt(8)
	s_waitcnt lgkmcnt(0)
	s_barrier
	s_setprio 1
	s_waitcnt lgkmcnt(0)
	v_mfma_f32_16x16x32_bf16 v[60:63], v[152:155], v[198:201], v[60:63]
	v_mfma_f32_16x16x32_bf16 v[60:63], v[156:159], v[202:205], v[60:63]
	v_mfma_f32_16x16x32_bf16 v[56:59], v[160:163], v[198:201], v[56:59]
	v_mfma_f32_16x16x32_bf16 v[56:59], v[164:167], v[202:205], v[56:59]
	v_mfma_f32_16x16x32_bf16 v[44:47], v[152:155], v[206:209], v[44:47]
	v_mfma_f32_16x16x32_bf16 v[44:47], v[156:159], v[210:213], v[44:47]
	v_mfma_f32_16x16x32_bf16 v[40:43], v[160:163], v[206:209], v[40:43]
	v_mfma_f32_16x16x32_bf16 v[40:43], v[164:167], v[210:213], v[40:43]
	v_mfma_f32_16x16x32_bf16 v[28:31], v[152:155], v[214:217], v[28:31]
	v_mfma_f32_16x16x32_bf16 v[28:31], v[156:159], v[218:221], v[28:31]
	v_mfma_f32_16x16x32_bf16 v[24:27], v[160:163], v[214:217], v[24:27]
	v_mfma_f32_16x16x32_bf16 v[24:27], v[164:167], v[218:221], v[24:27]
	v_mfma_f32_16x16x32_bf16 v[12:15], v[152:155], v[222:225], v[12:15]
	v_mfma_f32_16x16x32_bf16 v[12:15], v[156:159], v[226:229], v[12:15]
	v_mfma_f32_16x16x32_bf16 v[8:11], v[160:163], v[222:225], v[8:11]
	v_mfma_f32_16x16x32_bf16 v[8:11], v[164:167], v[226:229], v[8:11]
	s_setprio 0
	s_setprio 1
	v_mfma_f32_16x16x32_bf16 v[52:55], v[168:171], v[198:201], v[52:55]
	v_mfma_f32_16x16x32_bf16 v[52:55], v[172:175], v[202:205], v[52:55]
	v_mfma_f32_16x16x32_bf16 v[48:51], v[176:179], v[198:201], v[48:51]
	v_mfma_f32_16x16x32_bf16 v[48:51], v[194:197], v[202:205], v[48:51]
	v_mfma_f32_16x16x32_bf16 v[36:39], v[168:171], v[206:209], v[36:39]
	v_mfma_f32_16x16x32_bf16 v[36:39], v[172:175], v[210:213], v[36:39]
	v_mfma_f32_16x16x32_bf16 v[32:35], v[176:179], v[206:209], v[32:35]
	v_mfma_f32_16x16x32_bf16 v[32:35], v[194:197], v[210:213], v[32:35]
	v_mfma_f32_16x16x32_bf16 v[20:23], v[168:171], v[214:217], v[20:23]
	v_mfma_f32_16x16x32_bf16 v[20:23], v[172:175], v[218:221], v[20:23]
	v_mfma_f32_16x16x32_bf16 v[16:19], v[176:179], v[214:217], v[16:19]
	v_mfma_f32_16x16x32_bf16 v[16:19], v[194:197], v[218:221], v[16:19]
	v_mfma_f32_16x16x32_bf16 v[4:7], v[168:171], v[222:225], v[4:7]
	v_mfma_f32_16x16x32_bf16 v[4:7], v[172:175], v[226:229], v[4:7]
	v_mfma_f32_16x16x32_bf16 v[0:3], v[176:179], v[222:225], v[0:3]
	v_mfma_f32_16x16x32_bf16 v[0:3], v[194:197], v[226:229], v[0:3]
	s_setprio 0
	s_barrier
	s_add_i32 s43, s43, 2
	s_add_u32 s4, s4, 0x100
	s_addc_u32 s5, s5, 0
	s_add_u32 s36, s36, 0x100
	s_addc_u32 s37, s37, 0
	s_cmp_gt_u32 s43, 13
	s_cbranch_scc0 .LBB0_144
	s_and_b64 vcc, exec, s[30:31]
	s_cbranch_vccz .LBB0_147
	s_barrier

.LBB0_584:
	s_and_b32 s97, s22, 1
	s_mul_i32 s16, s97, 0x4800
	s_add_i32 s66, s16, 0
	s_cmp_lt_i32 s41, s37
	s_cselect_b64 s[16:17], -1, 0
	s_cmp_gt_i32 s41, s36
	s_cselect_b64 s[64:65], -1, 0
	s_or_b64 s[16:17], s[16:17], s[64:65]
	v_lshlrev_b32_e32 v0, 1, v190
	v_add_u32_e32 v2, s66, v244
	s_and_b64 vcc, exec, s[16:17]
	v_add3_u32 v234, s66, v243, v0
	v_add3_u32 v238, v2, v249, v250
	s_cbranch_vccnz .LBB0_598
	ds_read2_b64 v[180:183], v252 offset1:32
	ds_read_b128 v[172:175], v234
	ds_read_b128 v[160:163], v234 offset:32
	ds_read_b128 v[176:179], v234 offset:4608
	ds_read_b128 v[164:167], v234 offset:4640
	ds_read_b128 v[156:159], v234 offset:64
	ds_read_b128 v[152:155], v234 offset:96
	ds_read_b128 v[168:171], v234 offset:4672
	ds_read_b128 v[148:151], v234 offset:4704
	ds_read_b64_tr_b16 v[144:145], v238 offset:36864
	ds_read_b64_tr_b16 v[146:147], v238 offset:38016
	ds_read_b64_tr_b16 v[142:143], v238 offset:38080
	ds_read_b64_tr_b16 v[140:141], v238 offset:36928
	ds_read_b64_tr_b16 v[136:137], v238 offset:39168
	ds_read_b64_tr_b16 v[138:139], v238 offset:40320
	ds_read_b64_tr_b16 v[134:135], v238 offset:40384
	ds_read_b64_tr_b16 v[132:133], v238 offset:39232
	ds_read_b64_tr_b16 v[128:129], v238 offset:41472
	ds_read_b64_tr_b16 v[130:131], v238 offset:42624
	ds_read_b64_tr_b16 v[126:127], v238 offset:42688
	ds_read_b64_tr_b16 v[124:125], v238 offset:41536
	ds_read_b64_tr_b16 v[120:121], v238 offset:43776
	ds_read_b64_tr_b16 v[122:123], v238 offset:44928
	ds_read_b64_tr_b16 v[118:119], v238 offset:44992
	ds_read_b64_tr_b16 v[116:117], v238 offset:43840
	s_mov_b64 s[16:17], -1
	s_and_b64 vcc, exec, s[8:9]
	s_cbranch_vccz .LBB0_591
	s_add_i32 s16, s40, s63
	s_sub_i32 s16, s16, 63
	s_cmpk_gt_i32 s16, 0x7f
	s_mov_b64 s[16:17], -1
	s_cbranch_scc1 .LBB0_588
	v_add_u32_e32 v0, s40, v253
	v_add_u32_e32 v2, 0x5b, v0
	v_med3_i32 v3, v2, s53, v235
	v_med3_i32 v2, v2, s95, v237
	v_add_u32_e32 v4, 0x5a, v0
	v_add_u32_e32 v6, 0x59, v0
	v_add_u32_e32 v8, 0x58, v0
	v_lshl_add_u32 v3, v3, 2, s38
	v_lshl_add_u32 v2, v2, 2, s38
	v_med3_i32 v5, v4, s53, v235
	v_med3_i32 v4, v4, s95, v237
	v_med3_i32 v7, v6, s53, v235
	v_med3_i32 v6, v6, s95, v237
	v_med3_i32 v9, v8, s53, v235
	v_med3_i32 v8, v8, s95, v237
	v_lshl_add_u32 v5, v5, 2, s38
	v_lshl_add_u32 v4, v4, 2, s38
	v_lshl_add_u32 v7, v7, 2, s38
	v_lshl_add_u32 v6, v6, 2, s38
	v_lshl_add_u32 v9, v9, 2, s38
	v_lshl_add_u32 v8, v8, 2, s38
	ds_read_b32 v64, v3 offset:512
	ds_read_b32 v48, v2 offset:384
	ds_read_b32 v65, v5 offset:512
	ds_read_b32 v49, v4 offset:384
	ds_read_b32 v66, v7 offset:512
	ds_read_b32 v50, v6 offset:384
	ds_read_b32 v67, v9 offset:512
	ds_read_b32 v51, v8 offset:384
	v_add_u32_e32 v2, 0x53, v0
	v_med3_i32 v3, v2, s53, v235
	v_med3_i32 v2, v2, s95, v237
	v_add_u32_e32 v4, 0x52, v0
	v_add_u32_e32 v6, 0x51, v0
	v_add_u32_e32 v8, 0x50, v0
	v_lshl_add_u32 v3, v3, 2, s38
	v_lshl_add_u32 v2, v2, 2, s38
	v_med3_i32 v5, v4, s53, v235
	v_med3_i32 v4, v4, s95, v237
	v_med3_i32 v7, v6, s53, v235
	v_med3_i32 v6, v6, s95, v237
	v_med3_i32 v9, v8, s53, v235
	v_med3_i32 v8, v8, s95, v237
	v_lshl_add_u32 v5, v5, 2, s38
	v_lshl_add_u32 v4, v4, 2, s38
	v_lshl_add_u32 v7, v7, 2, s38
	v_lshl_add_u32 v6, v6, 2, s38
	v_lshl_add_u32 v9, v9, 2, s38
	v_lshl_add_u32 v8, v8, 2, s38
	ds_read_b32 v68, v3 offset:512
	ds_read_b32 v52, v2 offset:384
	ds_read_b32 v69, v5 offset:512
	ds_read_b32 v53, v4 offset:384
	ds_read_b32 v70, v7 offset:512
	ds_read_b32 v54, v6 offset:384
	ds_read_b32 v71, v9 offset:512
	ds_read_b32 v55, v8 offset:384
	v_add_u32_e32 v2, 0x4b, v0
	v_med3_i32 v3, v2, s53, v235
	v_med3_i32 v2, v2, s95, v237
	v_add_u32_e32 v4, 0x4a, v0
	v_add_u32_e32 v6, 0x49, v0
	v_add_u32_e32 v8, 0x48, v0
	v_lshl_add_u32 v3, v3, 2, s38
	v_lshl_add_u32 v2, v2, 2, s38
	v_med3_i32 v5, v4, s53, v235
	v_med3_i32 v4, v4, s95, v237
	v_med3_i32 v7, v6, s53, v235
	v_med3_i32 v6, v6, s95, v237
	v_med3_i32 v9, v8, s53, v235
	v_med3_i32 v8, v8, s95, v237
	v_lshl_add_u32 v5, v5, 2, s38
	v_lshl_add_u32 v4, v4, 2, s38
	v_lshl_add_u32 v7, v7, 2, s38
	v_lshl_add_u32 v6, v6, 2, s38
	v_lshl_add_u32 v9, v9, 2, s38
	v_lshl_add_u32 v8, v8, 2, s38
	ds_read_b32 v72, v3 offset:512
	ds_read_b32 v56, v2 offset:384
	ds_read_b32 v73, v5 offset:512
	ds_read_b32 v57, v4 offset:384
	ds_read_b32 v74, v7 offset:512
	ds_read_b32 v58, v6 offset:384
	ds_read_b32 v75, v9 offset:512
	ds_read_b32 v59, v8 offset:384
	v_add_u32_e32 v2, 0x43, v0
	v_med3_i32 v3, v2, s53, v235
	v_add_u32_e32 v4, 0x42, v0
	v_add_u32_e32 v6, 0x41, v0
	v_add_u32_e32 v0, 64, v0
	v_med3_i32 v2, v2, s95, v237
	v_lshl_add_u32 v3, v3, 2, s38
	v_med3_i32 v5, v4, s53, v235
	v_med3_i32 v4, v4, s95, v237
	v_med3_i32 v7, v6, s53, v235
	v_med3_i32 v6, v6, s95, v237
	v_med3_i32 v8, v0, s53, v235
	v_med3_i32 v0, v0, s95, v237
	v_lshl_add_u32 v2, v2, 2, s38
	v_lshl_add_u32 v5, v5, 2, s38
	v_lshl_add_u32 v4, v4, 2, s38
	v_lshl_add_u32 v7, v7, 2, s38
	v_lshl_add_u32 v6, v6, 2, s38
	v_lshl_add_u32 v8, v8, 2, s38
	v_lshl_add_u32 v0, v0, 2, s38
	ds_read_b32 v76, v3 offset:512
	ds_read_b32 v60, v2 offset:384
	ds_read_b32 v77, v5 offset:512
	ds_read_b32 v61, v4 offset:384
	ds_read_b32 v78, v7 offset:512
	ds_read_b32 v62, v6 offset:384
	ds_read_b32 v79, v8 offset:512
	ds_read_b32 v63, v0 offset:384
	s_mov_b64 s[16:17], 0

.LBB0_591:
	s_andn2_b64 vcc, exec, s[16:17]
	s_cbranch_vccnz .LBB0_593
	v_mov_b32_e32 v188, 0x3f803f80
	v_mov_b32_e32 v184, 0x3f803f80
	v_mov_b32_e32 v189, 0
	s_and_b64 vcc, exec, s[4:5]
	s_cbranch_vccz .LBB0_594
	s_branch .LBB0_595
.LBB0_593:
	s_waitcnt lgkmcnt(0)
	s_and_b64 vcc, exec, s[4:5]
	s_cbranch_vccnz .LBB0_595
.LBB0_594:
	s_add_i32 s16, s21, s96
	s_add_i32 s16, s16, 63
	s_cmp_gt_i32 s16, s42
	s_cselect_b64 s[16:17], -1, 0
	s_and_b64 s[16:17], s[6:7], s[16:17]
	s_andn2_b64 vcc, exec, s[16:17]
	s_cbranch_vccz .Lmy_cold1
	s_waitcnt lgkmcnt(15)
	v_mov_b32_e32 v186, v180
	v_mov_b32_e32 v187, v181
	v_mov_b32_e32 v185, v189
	s_nop 0
	v_mfma_f32_32x32x16_bf16 v[64:79], v[186:189], v[80:83], 0
	v_mfma_f32_32x32x16_bf16 v[64:79], v[172:175], v[84:87], v[64:79]
	v_mfma_f32_32x32x16_bf16 v[64:79], v[160:163], v[88:91], v[64:79]
	v_mfma_f32_32x32x16_bf16 v[64:79], v[156:159], v[92:95], v[64:79]
	v_mfma_f32_32x32x16_bf16 v[64:79], v[152:155], v[96:99], v[64:79]
	v_mfma_f32_32x32x16_bf16 v[48:63], v[182:185], v[80:83], 0
	v_mfma_f32_32x32x16_bf16 v[48:63], v[176:179], v[84:87], v[48:63]
	v_mfma_f32_32x32x16_bf16 v[48:63], v[164:167], v[88:91], v[48:63]
	ds_read_b128 v[172:175], v234 offset:9216
	ds_read_b128 v[160:163], v234 offset:9248
	ds_read_b128 v[156:159], v234 offset:9280
	ds_read_b128 v[152:155], v234 offset:9312
	s_nop 4
	v_exp_f32_e32 v64, v64
	v_exp_f32_e32 v65, v65
	v_exp_f32_e32 v66, v66
	v_mfma_f32_32x32x16_bf16 v[48:63], v[168:171], v[92:95], v[48:63]
	v_exp_f32_e32 v67, v67
	v_exp_f32_e32 v68, v68
	v_exp_f32_e32 v69, v69
	v_mfma_f32_32x32x16_bf16 v[48:63], v[148:151], v[96:99], v[48:63]
	ds_read_b128 v[176:179], v234 offset:13824
	ds_read_b128 v[164:167], v234 offset:13856
	ds_read_b128 v[168:171], v234 offset:13888
	s_or_b32 s32, s32, 2
	v_exp_f32_e32 v70, v70
	v_exp_f32_e32 v71, v71
	v_exp_f32_e32 v72, v72
	v_exp_f32_e32 v73, v73
	v_exp_f32_e32 v74, v74
	v_exp_f32_e32 v75, v75
	v_exp_f32_e32 v76, v76
	v_exp_f32_e32 v77, v77
	v_exp_f32_e32 v78, v78
	v_exp_f32_e32 v79, v79
	v_cvt_pk_bf16_f32 v2, v64, v65
	v_cvt_pk_bf16_f32 v3, v66, v67
	v_cvt_pk_bf16_f32 v4, v68, v69
	v_cvt_pk_bf16_f32 v5, v70, v71
	v_cvt_pk_bf16_f32 v6, v72, v73
	v_cvt_pk_bf16_f32 v7, v74, v75
	v_cvt_pk_bf16_f32 v8, v76, v77
	v_cvt_pk_bf16_f32 v9, v78, v79
	s_waitcnt lgkmcnt(7)
	v_mfma_f32_32x32x16_bf16 v[32:47], v[2:5], v[144:147], v[32:47]
	v_exp_f32_e32 v48, v48
	v_exp_f32_e32 v49, v49
	v_exp_f32_e32 v50, v50
	v_mfma_f32_32x32x16_bf16 v[16:31], v[2:5], v[140:143], v[16:31]
	v_exp_f32_e32 v51, v51
	v_exp_f32_e32 v52, v52
	v_exp_f32_e32 v53, v53
	v_mfma_f32_32x32x16_bf16 v[32:47], v[6:9], v[136:139], v[32:47]
	v_exp_f32_e32 v54, v54
	v_exp_f32_e32 v55, v55
	v_cvt_pk_bf16_f32 v10, v48, v49
	v_cvt_pk_bf16_f32 v11, v50, v51
	v_mfma_f32_32x32x16_bf16 v[16:31], v[6:9], v[132:135], v[16:31]
	v_cvt_pk_bf16_f32 v12, v52, v53
	v_cvt_pk_bf16_f32 v13, v54, v55
	v_exp_f32_e32 v56, v56
	v_exp_f32_e32 v57, v57
	v_mfma_f32_32x32x16_bf16 v[32:47], v[10:13], v[128:131], v[32:47]
	v_exp_f32_e32 v58, v58
	v_exp_f32_e32 v59, v59
	v_exp_f32_e32 v60, v60
	v_mfma_f32_32x32x16_bf16 v[16:31], v[10:13], v[124:127], v[16:31]
	v_exp_f32_e32 v61, v61
	v_exp_f32_e32 v62, v62
	v_exp_f32_e32 v63, v63
	v_cvt_pk_bf16_f32 v148, v56, v57
	v_cvt_pk_bf16_f32 v149, v58, v59
	v_cvt_pk_bf16_f32 v150, v60, v61
	v_cvt_pk_bf16_f32 v151, v62, v63
	v_pk_add_f32 v[2:3], v[64:65], v[66:67]
	v_pk_add_f32 v[4:5], v[68:69], v[70:71]
	v_mfma_f32_32x32x16_bf16 v[32:47], v[148:151], v[120:123], v[32:47]
	v_pk_add_f32 v[6:7], v[72:73], v[74:75]
	v_pk_add_f32 v[8:9], v[76:77], v[78:79]
	v_pk_add_f32 v[10:11], v[48:49], v[50:51]
	v_pk_add_f32 v[12:13], v[52:53], v[54:55]
	v_pk_add_f32 v[14:15], v[56:57], v[58:59]
	v_pk_add_f32 v[64:65], v[60:61], v[62:63]
	v_mfma_f32_32x32x16_bf16 v[16:31], v[148:151], v[116:119], v[16:31]
	v_pk_add_f32 v[2:3], v[2:3], v[4:5]
	v_pk_add_f32 v[6:7], v[6:7], v[8:9]
	v_pk_add_f32 v[10:11], v[10:11], v[12:13]
	v_pk_add_f32 v[14:15], v[14:15], v[64:65]
	v_pk_add_f32 v[2:3], v[2:3], v[6:7]
	v_pk_add_f32 v[10:11], v[10:11], v[14:15]
	v_pk_add_f32 v[2:3], v[2:3], v[10:11]
	v_add_f32_e32 v0, v2, v3
	v_add_f32_e32 v233, v233, v0
	s_branch .LBB0_598
.Lmy_cold1:
	s_waitcnt lgkmcnt(15)
	v_mov_b32_e32 v186, v180
	v_mov_b32_e32 v187, v181
	v_mov_b32_e32 v185, v189
	s_nop 0
	v_mfma_f32_32x32x16_bf16 v[64:79], v[186:189], v[80:83], 0
	v_mfma_f32_32x32x16_bf16 v[48:63], v[182:185], v[80:83], 0
.LBB0_595:
	s_waitcnt lgkmcnt(15)
	v_mfma_f32_32x32x16_bf16 v[64:79], v[172:175], v[84:87], v[64:79]
	s_add_i32 s16, s21, s96
	s_add_i32 s16, s16, 63
	s_cmp_gt_i32 s16, s42
	s_cselect_b64 s[16:17], -1, 0
	s_and_b64 s[16:17], s[6:7], s[16:17]
	s_andn2_b64 vcc, exec, s[16:17]
	s_waitcnt lgkmcnt(15)
	v_mfma_f32_32x32x16_bf16 v[48:63], v[176:179], v[84:87], v[48:63]
	v_mfma_f32_32x32x16_bf16 v[64:79], v[160:163], v[88:91], v[64:79]
	v_mfma_f32_32x32x16_bf16 v[48:63], v[164:167], v[88:91], v[48:63]
	v_mfma_f32_32x32x16_bf16 v[64:79], v[156:159], v[92:95], v[64:79]
	v_mfma_f32_32x32x16_bf16 v[48:63], v[168:171], v[92:95], v[48:63]
	v_mfma_f32_32x32x16_bf16 v[64:79], v[152:155], v[96:99], v[64:79]
	v_mfma_f32_32x32x16_bf16 v[48:63], v[148:151], v[96:99], v[48:63]
	ds_read_b128 v[172:175], v234 offset:9216
	ds_read_b128 v[160:163], v234 offset:9248
	ds_read_b128 v[176:179], v234 offset:13824
	ds_read_b128 v[164:167], v234 offset:13856
	ds_read_b128 v[156:159], v234 offset:9280
	ds_read_b128 v[152:155], v234 offset:9312
	ds_read_b128 v[168:171], v234 offset:13888
	s_or_b32 s32, s32, 2
	s_cbranch_vccnz .LBB0_597
	v_add_u32_e32 v0, s21, v254
	v_cmp_le_i32_e32 vcc, v0, v251
	v_add_u32_e32 v2, 33, v0
	s_nop 7
	v_cndmask_b32_e32 v48, v236, v48, vcc
	v_cmp_lt_i32_e32 vcc, v0, v232
	s_nop 1
	v_cndmask_b32_e32 v65, v236, v65, vcc
	v_cmp_le_i32_e32 vcc, v0, v232
	s_nop 1
	v_cndmask_b32_e32 v64, v236, v64, vcc
	v_cmp_le_i32_e32 vcc, v2, v232
	v_add_u32_e32 v2, 2, v0
	s_nop 0
	v_cndmask_b32_e32 v49, v236, v49, vcc
	v_cmp_le_i32_e32 vcc, v2, v232
	v_add_u32_e32 v2, 34, v0
	s_nop 0
	v_cndmask_b32_e32 v66, v236, v66, vcc
	v_cmp_le_i32_e32 vcc, v2, v232
	v_add_u32_e32 v2, 3, v0
	s_nop 0
	v_cndmask_b32_e32 v50, v236, v50, vcc
	v_cmp_le_i32_e32 vcc, v2, v232
	v_add_u32_e32 v2, 35, v0
	s_nop 0
	v_cndmask_b32_e32 v67, v236, v67, vcc
	v_cmp_le_i32_e32 vcc, v2, v232
	v_add_u32_e32 v2, 8, v0
	s_nop 0
	v_cndmask_b32_e32 v51, v236, v51, vcc
	v_cmp_le_i32_e32 vcc, v2, v232
	v_add_u32_e32 v2, 40, v0
	s_nop 0
	v_cndmask_b32_e32 v68, v236, v68, vcc
	v_cmp_le_i32_e32 vcc, v2, v232
	v_add_u32_e32 v2, 9, v0
	s_nop 0
	v_cndmask_b32_e32 v52, v236, v52, vcc
	v_cmp_le_i32_e32 vcc, v2, v232
	v_add_u32_e32 v2, 41, v0
	s_nop 0
	v_cndmask_b32_e32 v69, v236, v69, vcc
	v_cmp_le_i32_e32 vcc, v2, v232
	v_add_u32_e32 v2, 10, v0
	s_nop 0
	v_cndmask_b32_e32 v53, v236, v53, vcc
	v_cmp_le_i32_e32 vcc, v2, v232
	v_add_u32_e32 v2, 42, v0
	s_nop 0
	v_cndmask_b32_e32 v70, v236, v70, vcc
	v_cmp_le_i32_e32 vcc, v2, v232
	v_add_u32_e32 v2, 11, v0
	s_nop 0
	v_cndmask_b32_e32 v54, v236, v54, vcc
	v_cmp_le_i32_e32 vcc, v2, v232
	v_add_u32_e32 v2, 43, v0
	s_nop 0
	v_cndmask_b32_e32 v71, v236, v71, vcc
	v_cmp_le_i32_e32 vcc, v2, v232
	v_add_u32_e32 v2, 16, v0
	s_nop 0
	v_cndmask_b32_e32 v55, v236, v55, vcc
	v_cmp_le_i32_e32 vcc, v2, v232
	v_add_u32_e32 v2, 48, v0
	s_nop 0
	v_cndmask_b32_e32 v72, v236, v72, vcc
	v_cmp_le_i32_e32 vcc, v2, v232
	v_add_u32_e32 v2, 17, v0
	s_nop 0
	v_cndmask_b32_e32 v56, v236, v56, vcc
	v_cmp_le_i32_e32 vcc, v2, v232
	v_add_u32_e32 v2, 49, v0
	s_nop 0
	v_cndmask_b32_e32 v73, v236, v73, vcc
	v_cmp_le_i32_e32 vcc, v2, v232
	v_add_u32_e32 v2, 18, v0
	s_nop 0
	v_cndmask_b32_e32 v57, v236, v57, vcc
	v_cmp_le_i32_e32 vcc, v2, v232
	v_add_u32_e32 v2, 50, v0
	s_nop 0
	v_cndmask_b32_e32 v74, v236, v74, vcc
	v_cmp_le_i32_e32 vcc, v2, v232
	v_add_u32_e32 v2, 19, v0
	s_nop 0
	v_cndmask_b32_e32 v58, v236, v58, vcc
	v_cmp_le_i32_e32 vcc, v2, v232
	v_add_u32_e32 v2, 51, v0
	s_nop 0
	v_cndmask_b32_e32 v75, v236, v75, vcc
	v_cmp_le_i32_e32 vcc, v2, v232
	v_add_u32_e32 v2, 24, v0
	s_nop 0
	v_cndmask_b32_e32 v59, v236, v59, vcc
	v_cmp_le_i32_e32 vcc, v2, v232
	v_add_u32_e32 v2, 56, v0
	s_nop 0
	v_cndmask_b32_e32 v76, v236, v76, vcc
	v_cmp_le_i32_e32 vcc, v2, v232
	v_add_u32_e32 v2, 25, v0
	s_nop 0
	v_cndmask_b32_e32 v60, v236, v60, vcc
	v_cmp_le_i32_e32 vcc, v2, v232
	v_add_u32_e32 v2, 57, v0
	s_nop 0
	v_cndmask_b32_e32 v77, v236, v77, vcc
	v_cmp_le_i32_e32 vcc, v2, v232
	v_add_u32_e32 v2, 26, v0
	s_nop 0
	v_cndmask_b32_e32 v61, v236, v61, vcc
	v_cmp_le_i32_e32 vcc, v2, v232
	v_add_u32_e32 v2, 58, v0
	s_nop 0
	v_cndmask_b32_e32 v78, v236, v78, vcc
	v_cmp_le_i32_e32 vcc, v2, v232
	v_add_u32_e32 v2, 27, v0
	v_add_u32_e32 v0, 59, v0
	v_cndmask_b32_e32 v62, v236, v62, vcc
	v_cmp_le_i32_e32 vcc, v2, v232
	s_nop 1
	v_cndmask_b32_e32 v79, v236, v79, vcc
	v_cmp_le_i32_e32 vcc, v0, v232
	s_nop 1
	v_cndmask_b32_e32 v63, v236, v63, vcc
.LBB0_597:
	s_nop 9
	v_exp_f32_e32 v64, v64
	v_exp_f32_e32 v148, v48
	v_exp_f32_e32 v0, v65
	v_exp_f32_e32 v10, v49
	v_exp_f32_e32 v65, v50
	v_add_f32_e32 v11, v148, v64
	v_exp_f32_e32 v12, v51
	v_pk_add_f32 v[2:3], v[10:11], v[0:1]
	v_exp_f32_e32 v11, v66
	v_pk_add_f32 v[4:5], v[2:3], v[2:3] op_sel_hi:[0,1]
	v_exp_f32_e32 v4, v67
	v_exp_f32_e32 v14, v53
	v_add_f32_e32 v13, v65, v11
	v_exp_f32_e32 v48, v55
	v_pk_add_f32 v[2:3], v[12:13], v[4:5]
	v_exp_f32_e32 v5, v68
	v_pk_add_f32 v[6:7], v[2:3], v[2:3] op_sel_hi:[0,1]
	v_exp_f32_e32 v13, v52
	v_exp_f32_e32 v6, v69
	v_exp_f32_e32 v66, v56
	v_exp_f32_e32 v52, v57
	v_add_f32_e32 v15, v13, v5
	v_pk_add_f32 v[2:3], v[14:15], v[6:7]
	v_exp_f32_e32 v7, v70
	v_pk_add_f32 v[8:9], v[2:3], v[2:3] op_sel_hi:[0,1]
	v_exp_f32_e32 v15, v54
	v_exp_f32_e32 v8, v71
	v_exp_f32_e32 v56, v59
	v_add_f32_e32 v49, v15, v7
	v_pk_add_f32 v[2:3], v[48:49], v[8:9]
	v_exp_f32_e32 v49, v72
	v_pk_add_f32 v[50:51], v[2:3], v[2:3] op_sel_hi:[0,1]
	v_exp_f32_e32 v50, v73
	v_add_f32_e32 v53, v66, v49
	v_pk_add_f32 v[2:3], v[52:53], v[50:51]
	s_nop 0
	v_pk_add_f32 v[54:55], v[2:3], v[2:3] op_sel_hi:[0,1]
	v_exp_f32_e32 v51, v74
	v_exp_f32_e32 v53, v58
	v_exp_f32_e32 v54, v75
	v_cvt_pk_bf16_f32 v2, v64, v0
	v_cvt_pk_bf16_f32 v3, v11, v4
	v_add_f32_e32 v57, v53, v51
	v_pk_add_f32 v[58:59], v[56:57], v[54:55]
	v_cvt_pk_bf16_f32 v4, v5, v6
	v_cvt_pk_bf16_f32 v5, v7, v8
	v_pk_add_f32 v[8:9], v[58:59], v[58:59] op_sel_hi:[0,1]
	v_exp_f32_e32 v0, v76
	v_exp_f32_e32 v11, v60
	v_exp_f32_e32 v8, v77
	v_exp_f32_e32 v58, v61
	v_exp_f32_e32 v55, v78
	v_add_f32_e32 v59, v11, v0
	s_waitcnt lgkmcnt(0)
	v_mfma_f32_32x32x16_bf16 v[32:47], v[2:5], v[144:147], v[32:47]
	v_add_f32_e64 v6, v58, v8
	v_add_f32_e64 v7, v59, v9
	v_cvt_pk_bf16_f32 v8, v0, v8
	v_add_f32_e64 v60, v6, v6
	v_add_f32_e64 v61, v6, v7
	v_exp_f32_e32 v60, v79
	v_cvt_pk_bf16_f32 v6, v49, v50
	v_cvt_pk_bf16_f32 v7, v51, v54
	v_exp_f32_e32 v0, v62
	v_mfma_f32_32x32x16_bf16 v[16:31], v[2:5], v[140:143], v[16:31]
	v_cvt_pk_bf16_f32 v9, v55, v60
	v_cvt_pk_bf16_f32 v2, v148, v10
	v_cvt_pk_bf16_f32 v3, v65, v12
	v_cvt_pk_bf16_f32 v4, v13, v14
	v_cvt_pk_bf16_f32 v5, v15, v48
	v_exp_f32_e32 v10, v63
	v_mfma_f32_32x32x16_bf16 v[32:47], v[6:9], v[136:139], v[32:47]
	v_mfma_f32_32x32x16_bf16 v[16:31], v[6:9], v[132:135], v[16:31]
	v_cvt_pk_bf16_f32 v6, v66, v52
	v_cvt_pk_bf16_f32 v7, v53, v56
	v_cvt_pk_bf16_f32 v8, v11, v58
	v_cvt_pk_bf16_f32 v9, v0, v10
	v_add_f32_e32 v11, v0, v55
	v_mfma_f32_32x32x16_bf16 v[32:47], v[2:5], v[128:131], v[32:47]
	v_mfma_f32_32x32x16_bf16 v[16:31], v[2:5], v[124:127], v[16:31]
	v_add_f32_e64 v2, v10, v60
	v_add_f32_e64 v3, v11, v61
	v_add_f32_e32 v0, v2, v3
	v_add_f32_e32 v233, v233, v0
	v_mfma_f32_32x32x16_bf16 v[32:47], v[6:9], v[120:123], v[32:47]
	v_mfma_f32_32x32x16_bf16 v[16:31], v[6:9], v[116:119], v[16:31]
.LBB0_598:
	s_add_i32 s16, s41, 1
	s_cmp_lt_i32 s16, s37
	s_cselect_b64 s[16:17], -1, 0
	s_cmp_ge_i32 s41, s36
	s_cselect_b64 s[64:65], -1, 0
	s_or_b64 s[16:17], s[64:65], s[16:17]
	s_and_b64 vcc, exec, s[16:17]
	s_cbranch_vccnz .LBB0_612
	ds_read2_b64 v[180:183], v252 offset0:64 offset1:96
	s_bitcmp1_b32 s32, 1
	s_cbranch_scc1 .Lmy_k2skip
	ds_read_b128 v[172:175], v234 offset:9216
	ds_read_b128 v[160:163], v234 offset:9248
	ds_read_b128 v[176:179], v234 offset:13824
	ds_read_b128 v[164:167], v234 offset:13856
	ds_read_b128 v[156:159], v234 offset:9280
	ds_read_b128 v[152:155], v234 offset:9312
	ds_read_b128 v[168:171], v234 offset:13888
.Lmy_k2skip:
	ds_read_b128 v[148:151], v234 offset:13920
	ds_read_b64_tr_b16 v[144:145], v238 offset:46080
	ds_read_b64_tr_b16 v[146:147], v238 offset:47232
	ds_read_b64_tr_b16 v[142:143], v238 offset:47296
	ds_read_b64_tr_b16 v[140:141], v238 offset:46144
	ds_read_b64_tr_b16 v[136:137], v238 offset:48384
	ds_read_b64_tr_b16 v[138:139], v238 offset:49536
	ds_read_b64_tr_b16 v[134:135], v238 offset:49600
	ds_read_b64_tr_b16 v[132:133], v238 offset:48448
	ds_read_b64_tr_b16 v[128:129], v238 offset:50688
	ds_read_b64_tr_b16 v[130:131], v238 offset:51840
	ds_read_b64_tr_b16 v[126:127], v238 offset:51904
	ds_read_b64_tr_b16 v[124:125], v238 offset:50752
	ds_read_b64_tr_b16 v[120:121], v238 offset:52992
	ds_read_b64_tr_b16 v[122:123], v238 offset:54144
	ds_read_b64_tr_b16 v[118:119], v238 offset:54208
	ds_read_b64_tr_b16 v[116:117], v238 offset:53056
	s_mov_b64 s[16:17], -1
	s_and_b64 vcc, exec, s[8:9]
	s_cbranch_vccz .LBB0_605
	s_add_i32 s16, s40, s63
	s_addk_i32 s16, 0xff81
	s_cmpk_gt_i32 s16, 0x7f
	s_mov_b64 s[16:17], -1
	s_cbranch_scc1 .LBB0_602
	v_add_u32_e32 v0, s40, v253
	v_add_u32_e32 v2, 27, v0
	v_med3_i32 v3, v2, s53, v235
	v_med3_i32 v2, v2, s95, v237
	v_add_u32_e32 v4, 26, v0
	v_add_u32_e32 v6, 25, v0
	v_add_u32_e32 v8, 24, v0
	v_lshl_add_u32 v3, v3, 2, s38
	v_lshl_add_u32 v2, v2, 2, s38
	v_med3_i32 v5, v4, s53, v235
	v_med3_i32 v4, v4, s95, v237
	v_med3_i32 v7, v6, s53, v235
	v_med3_i32 v6, v6, s95, v237
	v_med3_i32 v9, v8, s53, v235
	v_med3_i32 v8, v8, s95, v237
	v_lshl_add_u32 v5, v5, 2, s38
	v_lshl_add_u32 v4, v4, 2, s38
	v_lshl_add_u32 v7, v7, 2, s38
	v_lshl_add_u32 v6, v6, 2, s38
	v_lshl_add_u32 v9, v9, 2, s38
	v_lshl_add_u32 v8, v8, 2, s38
	ds_read_b32 v64, v3 offset:512
	ds_read_b32 v48, v2 offset:384
	ds_read_b32 v65, v5 offset:512
	ds_read_b32 v49, v4 offset:384
	ds_read_b32 v66, v7 offset:512
	ds_read_b32 v50, v6 offset:384
	ds_read_b32 v67, v9 offset:512
	ds_read_b32 v51, v8 offset:384
	v_add_u32_e32 v2, 19, v0
	v_med3_i32 v3, v2, s53, v235
	v_med3_i32 v2, v2, s95, v237
	v_add_u32_e32 v4, 18, v0
	v_add_u32_e32 v6, 17, v0
	v_add_u32_e32 v8, 16, v0
	v_lshl_add_u32 v3, v3, 2, s38
	v_lshl_add_u32 v2, v2, 2, s38
	v_med3_i32 v5, v4, s53, v235
	v_med3_i32 v4, v4, s95, v237
	v_med3_i32 v7, v6, s53, v235
	v_med3_i32 v6, v6, s95, v237
	v_med3_i32 v9, v8, s53, v235
	v_med3_i32 v8, v8, s95, v237
	v_lshl_add_u32 v5, v5, 2, s38
	v_lshl_add_u32 v4, v4, 2, s38
	v_lshl_add_u32 v7, v7, 2, s38
	v_lshl_add_u32 v6, v6, 2, s38
	v_lshl_add_u32 v9, v9, 2, s38
	v_lshl_add_u32 v8, v8, 2, s38
	ds_read_b32 v68, v3 offset:512
	ds_read_b32 v52, v2 offset:384
	ds_read_b32 v69, v5 offset:512
	ds_read_b32 v53, v4 offset:384
	ds_read_b32 v70, v7 offset:512
	ds_read_b32 v54, v6 offset:384
	ds_read_b32 v71, v9 offset:512
	ds_read_b32 v55, v8 offset:384
	v_add_u32_e32 v2, 11, v0
	v_med3_i32 v3, v2, s53, v235
	v_med3_i32 v2, v2, s95, v237
	v_add_u32_e32 v4, 10, v0
	v_add_u32_e32 v6, 9, v0
	v_add_u32_e32 v8, 8, v0
	v_lshl_add_u32 v3, v3, 2, s38
	v_lshl_add_u32 v2, v2, 2, s38
	v_med3_i32 v5, v4, s53, v235
	v_med3_i32 v4, v4, s95, v237
	v_med3_i32 v7, v6, s53, v235
	v_med3_i32 v6, v6, s95, v237
	v_med3_i32 v9, v8, s53, v235
	v_med3_i32 v8, v8, s95, v237
	v_lshl_add_u32 v5, v5, 2, s38
	v_lshl_add_u32 v4, v4, 2, s38
	v_lshl_add_u32 v7, v7, 2, s38
	v_lshl_add_u32 v6, v6, 2, s38
	v_lshl_add_u32 v9, v9, 2, s38
	v_lshl_add_u32 v8, v8, 2, s38
	ds_read_b32 v72, v3 offset:512
	ds_read_b32 v56, v2 offset:384
	ds_read_b32 v73, v5 offset:512
	ds_read_b32 v57, v4 offset:384
	ds_read_b32 v74, v7 offset:512
	ds_read_b32 v58, v6 offset:384
	ds_read_b32 v75, v9 offset:512
	ds_read_b32 v59, v8 offset:384
	v_add_u32_e32 v2, 3, v0
	v_med3_i32 v3, v2, s53, v235
	v_add_u32_e32 v4, 2, v0
	v_add_u32_e32 v6, 1, v0
	v_med3_i32 v2, v2, s95, v237
	v_lshl_add_u32 v3, v3, 2, s38
	v_med3_i32 v5, v4, s53, v235
	v_med3_i32 v4, v4, s95, v237
	v_med3_i32 v7, v6, s53, v235
	v_med3_i32 v6, v6, s95, v237
	v_med3_i32 v8, v0, s53, v235
	v_med3_i32 v0, v0, s95, v237
	v_lshl_add_u32 v2, v2, 2, s38
	v_lshl_add_u32 v5, v5, 2, s38
	v_lshl_add_u32 v4, v4, 2, s38
	v_lshl_add_u32 v7, v7, 2, s38
	v_lshl_add_u32 v6, v6, 2, s38
	v_lshl_add_u32 v8, v8, 2, s38
	v_lshl_add_u32 v0, v0, 2, s38
	ds_read_b32 v76, v3 offset:512
	ds_read_b32 v60, v2 offset:384
	ds_read_b32 v77, v5 offset:512
	ds_read_b32 v61, v4 offset:384
	ds_read_b32 v78, v7 offset:512
	ds_read_b32 v62, v6 offset:384
	ds_read_b32 v79, v8 offset:512
	ds_read_b32 v63, v0 offset:384
	s_mov_b64 s[16:17], 0

.LBB0_608:
	s_add_i32 s16, s21, s96
	s_addk_i32 s16, 0x7f
	s_cmp_gt_i32 s16, s42
	s_cselect_b64 s[16:17], -1, 0
	s_and_b64 s[16:17], s[6:7], s[16:17]
	s_andn2_b64 vcc, exec, s[16:17]
	s_cbranch_vccz .Lmy_cold2
	s_waitcnt lgkmcnt(15)
	v_mov_b32_e32 v186, v180
	v_mov_b32_e32 v187, v181
	v_mov_b32_e32 v185, v189
	s_nop 0
	v_mfma_f32_32x32x16_bf16 v[64:79], v[186:189], v[80:83], 0
	v_mfma_f32_32x32x16_bf16 v[64:79], v[172:175], v[84:87], v[64:79]
	v_mfma_f32_32x32x16_bf16 v[64:79], v[160:163], v[88:91], v[64:79]
	v_mfma_f32_32x32x16_bf16 v[64:79], v[156:159], v[92:95], v[64:79]
	v_mfma_f32_32x32x16_bf16 v[64:79], v[152:155], v[96:99], v[64:79]
	v_mfma_f32_32x32x16_bf16 v[48:63], v[182:185], v[80:83], 0
	v_mfma_f32_32x32x16_bf16 v[48:63], v[176:179], v[84:87], v[48:63]
	v_mfma_f32_32x32x16_bf16 v[48:63], v[164:167], v[88:91], v[48:63]
	s_nop 8
	v_exp_f32_e32 v64, v64
	v_exp_f32_e32 v65, v65
	v_exp_f32_e32 v66, v66
	v_mfma_f32_32x32x16_bf16 v[48:63], v[168:171], v[92:95], v[48:63]
	v_exp_f32_e32 v67, v67
	v_exp_f32_e32 v68, v68
	v_exp_f32_e32 v69, v69
	v_mfma_f32_32x32x16_bf16 v[48:63], v[148:151], v[96:99], v[48:63]
	v_exp_f32_e32 v70, v70
	v_exp_f32_e32 v71, v71
	v_exp_f32_e32 v72, v72
	v_exp_f32_e32 v73, v73
	v_exp_f32_e32 v74, v74
	v_exp_f32_e32 v75, v75
	v_exp_f32_e32 v76, v76
	v_exp_f32_e32 v77, v77
	v_exp_f32_e32 v78, v78
	v_exp_f32_e32 v79, v79
	v_cvt_pk_bf16_f32 v2, v64, v65
	v_cvt_pk_bf16_f32 v3, v66, v67
	v_cvt_pk_bf16_f32 v4, v68, v69
	v_cvt_pk_bf16_f32 v5, v70, v71
	v_cvt_pk_bf16_f32 v6, v72, v73
	v_cvt_pk_bf16_f32 v7, v74, v75
	v_cvt_pk_bf16_f32 v8, v76, v77
	v_cvt_pk_bf16_f32 v9, v78, v79
	s_waitcnt lgkmcnt(0)
	v_mfma_f32_32x32x16_bf16 v[32:47], v[2:5], v[144:147], v[32:47]
	v_exp_f32_e32 v48, v48
	v_exp_f32_e32 v49, v49
	v_exp_f32_e32 v50, v50
	v_mfma_f32_32x32x16_bf16 v[16:31], v[2:5], v[140:143], v[16:31]
	v_exp_f32_e32 v51, v51
	v_exp_f32_e32 v52, v52
	v_exp_f32_e32 v53, v53
	v_mfma_f32_32x32x16_bf16 v[32:47], v[6:9], v[136:139], v[32:47]
	v_exp_f32_e32 v54, v54
	v_exp_f32_e32 v55, v55
	v_cvt_pk_bf16_f32 v10, v48, v49
	v_cvt_pk_bf16_f32 v11, v50, v51
	v_mfma_f32_32x32x16_bf16 v[16:31], v[6:9], v[132:135], v[16:31]
	v_cvt_pk_bf16_f32 v12, v52, v53
	v_cvt_pk_bf16_f32 v13, v54, v55
	v_exp_f32_e32 v56, v56
	v_exp_f32_e32 v57, v57
	v_mfma_f32_32x32x16_bf16 v[32:47], v[10:13], v[128:131], v[32:47]
	v_exp_f32_e32 v58, v58
	v_exp_f32_e32 v59, v59
	v_exp_f32_e32 v60, v60
	v_mfma_f32_32x32x16_bf16 v[16:31], v[10:13], v[124:127], v[16:31]
	v_exp_f32_e32 v61, v61
	v_exp_f32_e32 v62, v62
	v_exp_f32_e32 v63, v63
	v_cvt_pk_bf16_f32 v148, v56, v57
	v_cvt_pk_bf16_f32 v149, v58, v59
	v_cvt_pk_bf16_f32 v150, v60, v61
	v_cvt_pk_bf16_f32 v151, v62, v63
	v_pk_add_f32 v[2:3], v[64:65], v[66:67]
	v_pk_add_f32 v[4:5], v[68:69], v[70:71]
	v_mfma_f32_32x32x16_bf16 v[32:47], v[148:151], v[120:123], v[32:47]
	v_pk_add_f32 v[6:7], v[72:73], v[74:75]
	v_pk_add_f32 v[8:9], v[76:77], v[78:79]
	v_pk_add_f32 v[10:11], v[48:49], v[50:51]
	v_pk_add_f32 v[12:13], v[52:53], v[54:55]
	v_pk_add_f32 v[14:15], v[56:57], v[58:59]
	v_pk_add_f32 v[64:65], v[60:61], v[62:63]
	v_mfma_f32_32x32x16_bf16 v[16:31], v[148:151], v[116:119], v[16:31]
	v_pk_add_f32 v[2:3], v[2:3], v[4:5]
	v_pk_add_f32 v[6:7], v[6:7], v[8:9]
	v_pk_add_f32 v[10:11], v[10:11], v[12:13]
	v_pk_add_f32 v[14:15], v[14:15], v[64:65]
	v_pk_add_f32 v[2:3], v[2:3], v[6:7]
	v_pk_add_f32 v[10:11], v[10:11], v[14:15]
	v_pk_add_f32 v[2:3], v[2:3], v[10:11]
	v_add_f32_e32 v0, v2, v3
	v_add_f32_e32 v233, v233, v0
	s_branch .LBB0_612

.LBB0_609:
	s_waitcnt lgkmcnt(15)
	v_mfma_f32_32x32x16_bf16 v[64:79], v[172:175], v[84:87], v[64:79]
	s_add_i32 s16, s21, s96
	s_addk_i32 s16, 0x7f
	s_cmp_gt_i32 s16, s42
	s_cselect_b64 s[16:17], -1, 0
	s_and_b64 s[16:17], s[6:7], s[16:17]
	s_andn2_b64 vcc, exec, s[16:17]
	s_waitcnt lgkmcnt(15)
	v_mfma_f32_32x32x16_bf16 v[48:63], v[176:179], v[84:87], v[48:63]
	v_mfma_f32_32x32x16_bf16 v[64:79], v[160:163], v[88:91], v[64:79]
	v_mfma_f32_32x32x16_bf16 v[48:63], v[164:167], v[88:91], v[48:63]
	v_mfma_f32_32x32x16_bf16 v[64:79], v[156:159], v[92:95], v[64:79]
	v_mfma_f32_32x32x16_bf16 v[48:63], v[168:171], v[92:95], v[48:63]
	v_mfma_f32_32x32x16_bf16 v[64:79], v[152:155], v[96:99], v[64:79]
	v_mfma_f32_32x32x16_bf16 v[48:63], v[148:151], v[96:99], v[48:63]
	s_cbranch_vccnz .LBB0_611
	v_add_u32_e32 v0, s21, v254
	v_add_u32_e32 v2, 64, v0
	v_cmp_le_i32_e32 vcc, v2, v251
	s_nop 7
	v_cndmask_b32_e32 v48, v236, v48, vcc
	v_cmp_lt_i32_e32 vcc, v2, v232
	s_nop 1
	v_cndmask_b32_e32 v65, v236, v65, vcc
	v_cmp_le_i32_e32 vcc, v2, v232
	v_add_u32_e32 v2, 0x61, v0
	s_nop 0
	v_cndmask_b32_e32 v64, v236, v64, vcc
	v_cmp_le_i32_e32 vcc, v2, v232
	v_add_u32_e32 v2, 0x42, v0
	s_nop 0
	v_cndmask_b32_e32 v49, v236, v49, vcc
	v_cmp_le_i32_e32 vcc, v2, v232
	v_add_u32_e32 v2, 0x62, v0
	s_nop 0
	v_cndmask_b32_e32 v66, v236, v66, vcc
	v_cmp_le_i32_e32 vcc, v2, v232
	v_add_u32_e32 v2, 0x43, v0
	s_nop 0
	v_cndmask_b32_e32 v50, v236, v50, vcc
	v_cmp_le_i32_e32 vcc, v2, v232
	v_add_u32_e32 v2, 0x63, v0
	s_nop 0
	v_cndmask_b32_e32 v67, v236, v67, vcc
	v_cmp_le_i32_e32 vcc, v2, v232
	v_add_u32_e32 v2, 0x48, v0
	s_nop 0
	v_cndmask_b32_e32 v51, v236, v51, vcc
	v_cmp_le_i32_e32 vcc, v2, v232
	v_add_u32_e32 v2, 0x68, v0
	s_nop 0
	v_cndmask_b32_e32 v68, v236, v68, vcc
	v_cmp_le_i32_e32 vcc, v2, v232
	v_add_u32_e32 v2, 0x49, v0
	s_nop 0
	v_cndmask_b32_e32 v52, v236, v52, vcc
	v_cmp_le_i32_e32 vcc, v2, v232
	v_add_u32_e32 v2, 0x69, v0
	s_nop 0
	v_cndmask_b32_e32 v69, v236, v69, vcc
	v_cmp_le_i32_e32 vcc, v2, v232
	v_add_u32_e32 v2, 0x4a, v0
	s_nop 0
	v_cndmask_b32_e32 v53, v236, v53, vcc
	v_cmp_le_i32_e32 vcc, v2, v232
	v_add_u32_e32 v2, 0x6a, v0
	s_nop 0
	v_cndmask_b32_e32 v70, v236, v70, vcc
	v_cmp_le_i32_e32 vcc, v2, v232
	v_add_u32_e32 v2, 0x4b, v0
	s_nop 0
	v_cndmask_b32_e32 v54, v236, v54, vcc
	v_cmp_le_i32_e32 vcc, v2, v232
	v_add_u32_e32 v2, 0x6b, v0
	s_nop 0
	v_cndmask_b32_e32 v71, v236, v71, vcc
	v_cmp_le_i32_e32 vcc, v2, v232
	v_add_u32_e32 v2, 0x50, v0
	s_nop 0
	v_cndmask_b32_e32 v55, v236, v55, vcc
	v_cmp_le_i32_e32 vcc, v2, v232
	v_add_u32_e32 v2, 0x70, v0
	s_nop 0
	v_cndmask_b32_e32 v72, v236, v72, vcc
	v_cmp_le_i32_e32 vcc, v2, v232
	v_add_u32_e32 v2, 0x51, v0
	s_nop 0
	v_cndmask_b32_e32 v56, v236, v56, vcc
	v_cmp_le_i32_e32 vcc, v2, v232
	v_add_u32_e32 v2, 0x71, v0
	s_nop 0
	v_cndmask_b32_e32 v73, v236, v73, vcc
	v_cmp_le_i32_e32 vcc, v2, v232
	v_add_u32_e32 v2, 0x52, v0
	s_nop 0
	v_cndmask_b32_e32 v57, v236, v57, vcc
	v_cmp_le_i32_e32 vcc, v2, v232
	v_add_u32_e32 v2, 0x72, v0
	s_nop 0
	v_cndmask_b32_e32 v74, v236, v74, vcc
	v_cmp_le_i32_e32 vcc, v2, v232
	v_add_u32_e32 v2, 0x53, v0
	s_nop 0
	v_cndmask_b32_e32 v58, v236, v58, vcc
	v_cmp_le_i32_e32 vcc, v2, v232
	v_add_u32_e32 v2, 0x73, v0
	s_nop 0
	v_cndmask_b32_e32 v75, v236, v75, vcc
	v_cmp_le_i32_e32 vcc, v2, v232
	v_add_u32_e32 v2, 0x58, v0
	s_nop 0
	v_cndmask_b32_e32 v59, v236, v59, vcc
	v_cmp_le_i32_e32 vcc, v2, v232
	v_add_u32_e32 v2, 0x78, v0
	s_nop 0
	v_cndmask_b32_e32 v76, v236, v76, vcc
	v_cmp_le_i32_e32 vcc, v2, v232
	v_add_u32_e32 v2, 0x59, v0
	s_nop 0
	v_cndmask_b32_e32 v60, v236, v60, vcc
	v_cmp_le_i32_e32 vcc, v2, v232
	v_add_u32_e32 v2, 0x79, v0
	s_nop 0
	v_cndmask_b32_e32 v77, v236, v77, vcc
	v_cmp_le_i32_e32 vcc, v2, v232
	v_add_u32_e32 v2, 0x5a, v0
	s_nop 0
	v_cndmask_b32_e32 v61, v236, v61, vcc
	v_cmp_le_i32_e32 vcc, v2, v232
	v_add_u32_e32 v2, 0x7a, v0
	s_nop 0
	v_cndmask_b32_e32 v78, v236, v78, vcc
	v_cmp_le_i32_e32 vcc, v2, v232
	v_add_u32_e32 v2, 0x5b, v0
	v_add_u32_e32 v0, 0x7b, v0
	v_cndmask_b32_e32 v62, v236, v62, vcc
	v_cmp_le_i32_e32 vcc, v2, v232
	s_nop 1
	v_cndmask_b32_e32 v79, v236, v79, vcc
	v_cmp_le_i32_e32 vcc, v0, v232
	s_nop 1
	v_cndmask_b32_e32 v63, v236, v63, vcc

.LBB0_612:
	s_andn2_b64 vcc, exec, s[14:15]
	s_cbranch_vccnz .LBB0_581
	s_xor_b32 s14, s97, 1
	s_mulk_i32 s14, 0x4800
	v_add_u32_e32 v0, s14, v242
	s_bitcmp0_b32 s32, 0
	s_cbranch_scc1 .Lkvb_w0
	s_waitcnt vmcnt(4)
	s_branch .Lkvb_w1

.LBB0_685:
	ds_read_b128 v[144:147], v151
	ds_read_b128 v[156:159], v151 offset:1024
	ds_read_b128 v[160:163], v151 offset:2048
	ds_read_b128 v[164:167], v151 offset:3072
	ds_read_b128 v[168:171], v152
	ds_read_b128 v[172:175], v152 offset:1024
	ds_read_b128 v[176:179], v152 offset:2048
	ds_read_b128 v[180:183], v152 offset:3072
	s_add_u32 s40, s20, 0xfffc0080
	s_addc_u32 s41, s21, -1
	s_cmp_eq_u32 s54, 12
	s_cselect_b32 s43, s23, s41
	s_cselect_b32 s42, s39, s40
	s_cselect_b32 s41, s19, s53
	s_cselect_b32 s40, s51, s52
	v_lshl_add_u64 v[216:217], s[20:21], 0, v[136:137]
	s_add_i32 m0, s27, 0xc000
	ds_read_b128 v[184:187], v153
	ds_read_b128 v[188:191], v153 offset:1024
	ds_read_b128 v[192:195], v153 offset:2048
	ds_read_b128 v[196:199], v153 offset:3072
	ds_read_b128 v[200:203], v153 offset:4096
	ds_read_b128 v[204:207], v153 offset:5120
	ds_read_b128 v[208:211], v153 offset:6144
	ds_read_b128 v[212:215], v153 offset:7168
	global_load_lds_dwordx4 v[216:217], off
	v_lshl_add_u64 v[216:217], s[20:21], 0, v[138:139]
	s_add_i32 m0, s27, 0xe000
	s_nop 0
	global_load_lds_dwordx4 v[216:217], off
	s_waitcnt vmcnt(8)
	s_waitcnt lgkmcnt(0)
	s_barrier
	s_setprio 1
	s_waitcnt lgkmcnt(0)
	v_mfma_f32_16x16x32_bf16 v[124:127], v[144:147], v[184:187], v[124:127]
	v_mfma_f32_16x16x32_bf16 v[124:127], v[156:159], v[188:191], v[124:127]
	v_mfma_f32_16x16x32_bf16 v[120:123], v[160:163], v[184:187], v[120:123]
	v_mfma_f32_16x16x32_bf16 v[120:123], v[164:167], v[188:191], v[120:123]
	v_mfma_f32_16x16x32_bf16 v[108:111], v[144:147], v[192:195], v[108:111]
	v_mfma_f32_16x16x32_bf16 v[108:111], v[156:159], v[196:199], v[108:111]
	v_mfma_f32_16x16x32_bf16 v[104:107], v[160:163], v[192:195], v[104:107]
	v_mfma_f32_16x16x32_bf16 v[104:107], v[164:167], v[196:199], v[104:107]
	v_mfma_f32_16x16x32_bf16 v[92:95], v[144:147], v[200:203], v[92:95]
	v_mfma_f32_16x16x32_bf16 v[92:95], v[156:159], v[204:207], v[92:95]
	v_mfma_f32_16x16x32_bf16 v[88:91], v[160:163], v[200:203], v[88:91]
	v_mfma_f32_16x16x32_bf16 v[88:91], v[164:167], v[204:207], v[88:91]
	v_mfma_f32_16x16x32_bf16 v[76:79], v[144:147], v[208:211], v[76:79]
	v_mfma_f32_16x16x32_bf16 v[76:79], v[156:159], v[212:215], v[76:79]
	v_mfma_f32_16x16x32_bf16 v[72:75], v[160:163], v[208:211], v[72:75]
	v_mfma_f32_16x16x32_bf16 v[72:75], v[164:167], v[212:215], v[72:75]
	s_setprio 0
	s_setprio 1
	v_mfma_f32_16x16x32_bf16 v[116:119], v[168:171], v[184:187], v[116:119]
	v_mfma_f32_16x16x32_bf16 v[116:119], v[172:175], v[188:191], v[116:119]
	v_mfma_f32_16x16x32_bf16 v[112:115], v[176:179], v[184:187], v[112:115]
	v_mfma_f32_16x16x32_bf16 v[112:115], v[180:183], v[188:191], v[112:115]
	v_mfma_f32_16x16x32_bf16 v[100:103], v[168:171], v[192:195], v[100:103]
	v_mfma_f32_16x16x32_bf16 v[100:103], v[172:175], v[196:199], v[100:103]
	v_mfma_f32_16x16x32_bf16 v[96:99], v[176:179], v[192:195], v[96:99]
	v_mfma_f32_16x16x32_bf16 v[96:99], v[180:183], v[196:199], v[96:99]
	v_mfma_f32_16x16x32_bf16 v[84:87], v[168:171], v[200:203], v[84:87]
	v_mfma_f32_16x16x32_bf16 v[84:87], v[172:175], v[204:207], v[84:87]
	v_mfma_f32_16x16x32_bf16 v[80:83], v[176:179], v[200:203], v[80:83]
	v_mfma_f32_16x16x32_bf16 v[80:83], v[180:183], v[204:207], v[80:83]
	v_mfma_f32_16x16x32_bf16 v[68:71], v[168:171], v[208:211], v[68:71]
	v_mfma_f32_16x16x32_bf16 v[68:71], v[172:175], v[212:215], v[68:71]
	v_mfma_f32_16x16x32_bf16 v[64:67], v[176:179], v[208:211], v[64:67]
	v_mfma_f32_16x16x32_bf16 v[64:67], v[180:183], v[212:215], v[64:67]
	s_setprio 0
	s_barrier
	s_add_i32 s55, s48, s26
	v_lshl_add_u64 v[216:217], s[40:41], 0, v[130:131]
	s_mov_b32 m0, s55
	ds_read_b128 v[184:187], v153 offset:16384
	ds_read_b128 v[188:191], v153 offset:17408
	ds_read_b128 v[192:195], v153 offset:18432
	ds_read_b128 v[196:199], v153 offset:19456
	ds_read_b128 v[200:203], v153 offset:20480
	ds_read_b128 v[204:207], v153 offset:21504
	ds_read_b128 v[208:211], v153 offset:22528
	ds_read_b128 v[212:215], v153 offset:23552
	global_load_lds_dwordx4 v[216:217], off
	s_add_i32 m0, s55, 0x2000
	s_add_u32 s56, s40, 0x40000
	v_lshl_add_u64 v[218:219], s[40:41], 0, v[134:135]
	s_addc_u32 s57, s41, 0
	s_add_i32 s55, s49, s26
	global_load_lds_dwordx4 v[218:219], off
	v_lshl_add_u64 v[220:221], s[56:57], 0, v[130:131]
	s_mov_b32 m0, s55
	v_lshl_add_u64 v[222:223], s[42:43], 0, v[132:133]
	global_load_lds_dwordx4 v[220:221], off
	v_lshl_add_u64 v[220:221], s[56:57], 0, v[134:135]
	s_add_i32 m0, s55, 0x2000
	s_nop 0
	global_load_lds_dwordx4 v[220:221], off
	v_lshl_add_u64 v[220:221], s[42:43], 0, v[128:129]
	s_mov_b32 m0, s27
	s_nop 0
	global_load_lds_dwordx4 v[220:221], off
	s_mov_b32 m0, s33
	s_nop 0
	global_load_lds_dwordx4 v[222:223], off
	s_waitcnt vmcnt(8)
	s_waitcnt lgkmcnt(0)
	s_barrier
	s_setprio 1
	s_waitcnt lgkmcnt(0)
	v_mfma_f32_16x16x32_bf16 v[60:63], v[144:147], v[184:187], v[60:63]
	v_mfma_f32_16x16x32_bf16 v[60:63], v[156:159], v[188:191], v[60:63]
	v_mfma_f32_16x16x32_bf16 v[56:59], v[160:163], v[184:187], v[56:59]
	v_mfma_f32_16x16x32_bf16 v[56:59], v[164:167], v[188:191], v[56:59]
	v_mfma_f32_16x16x32_bf16 v[44:47], v[144:147], v[192:195], v[44:47]
	v_mfma_f32_16x16x32_bf16 v[44:47], v[156:159], v[196:199], v[44:47]
	v_mfma_f32_16x16x32_bf16 v[40:43], v[160:163], v[192:195], v[40:43]
	v_mfma_f32_16x16x32_bf16 v[40:43], v[164:167], v[196:199], v[40:43]
	v_mfma_f32_16x16x32_bf16 v[28:31], v[144:147], v[200:203], v[28:31]
	v_mfma_f32_16x16x32_bf16 v[28:31], v[156:159], v[204:207], v[28:31]
	v_mfma_f32_16x16x32_bf16 v[24:27], v[160:163], v[200:203], v[24:27]
	v_mfma_f32_16x16x32_bf16 v[24:27], v[164:167], v[204:207], v[24:27]
	v_mfma_f32_16x16x32_bf16 v[12:15], v[144:147], v[208:211], v[12:15]
	v_mfma_f32_16x16x32_bf16 v[12:15], v[156:159], v[212:215], v[12:15]
	v_mfma_f32_16x16x32_bf16 v[8:11], v[160:163], v[208:211], v[8:11]
	v_mfma_f32_16x16x32_bf16 v[8:11], v[164:167], v[212:215], v[8:11]
	s_setprio 0
	s_setprio 1
	v_mfma_f32_16x16x32_bf16 v[52:55], v[168:171], v[184:187], v[52:55]
	v_mfma_f32_16x16x32_bf16 v[52:55], v[172:175], v[188:191], v[52:55]
	v_mfma_f32_16x16x32_bf16 v[48:51], v[176:179], v[184:187], v[48:51]
	v_mfma_f32_16x16x32_bf16 v[48:51], v[180:183], v[188:191], v[48:51]
	v_mfma_f32_16x16x32_bf16 v[36:39], v[168:171], v[192:195], v[36:39]
	v_mfma_f32_16x16x32_bf16 v[36:39], v[172:175], v[196:199], v[36:39]
	v_mfma_f32_16x16x32_bf16 v[32:35], v[176:179], v[192:195], v[32:35]
	v_mfma_f32_16x16x32_bf16 v[32:35], v[180:183], v[196:199], v[32:35]
	v_mfma_f32_16x16x32_bf16 v[20:23], v[168:171], v[200:203], v[20:23]
	v_mfma_f32_16x16x32_bf16 v[20:23], v[172:175], v[204:207], v[20:23]
	v_mfma_f32_16x16x32_bf16 v[16:19], v[176:179], v[200:203], v[16:19]
	v_mfma_f32_16x16x32_bf16 v[16:19], v[180:183], v[204:207], v[16:19]
	v_mfma_f32_16x16x32_bf16 v[4:7], v[168:171], v[208:211], v[4:7]
	v_mfma_f32_16x16x32_bf16 v[4:7], v[172:175], v[212:215], v[4:7]
	v_mfma_f32_16x16x32_bf16 v[0:3], v[176:179], v[208:211], v[0:3]
	v_mfma_f32_16x16x32_bf16 v[0:3], v[180:183], v[212:215], v[0:3]
	s_setprio 0
	s_barrier
	s_add_i32 s55, 0, 0x18000
	v_add_u32_e32 v155, s55, v149
	s_add_i32 s56, 0, 0x1c000
	ds_read_b128 v[144:147], v155
	ds_read_b128 v[156:159], v155 offset:1024
	ds_read_b128 v[160:163], v155 offset:2048
	ds_read_b128 v[164:167], v155 offset:3072
	v_add_u32_e32 v155, s56, v149
	ds_read_b128 v[168:171], v155
	ds_read_b128 v[172:175], v155 offset:1024
	ds_read_b128 v[176:179], v155 offset:2048
	ds_read_b128 v[180:183], v155 offset:3072
	s_add_u32 s42, s42, 0x40000
	s_addc_u32 s43, s43, 0
	s_mov_b32 m0, s34
	v_lshl_add_u64 v[224:225], s[42:43], 0, v[128:129]
	ds_read_b128 v[184:187], v153 offset:32768
	ds_read_b128 v[188:191], v153 offset:33792
	ds_read_b128 v[192:195], v153 offset:34816
	ds_read_b128 v[196:199], v153 offset:35840
	ds_read_b128 v[200:203], v153 offset:36864
	ds_read_b128 v[204:207], v153 offset:37888
	ds_read_b128 v[208:211], v153 offset:38912
	ds_read_b128 v[212:215], v153 offset:39936
	global_load_lds_dwordx4 v[224:225], off
	v_lshl_add_u64 v[224:225], s[42:43], 0, v[132:133]
	s_mov_b32 m0, s35
	s_nop 0
	global_load_lds_dwordx4 v[224:225], off
	s_waitcnt vmcnt(8)
	s_waitcnt lgkmcnt(0)
	s_barrier
	s_setprio 1
	s_waitcnt lgkmcnt(0)
	v_mfma_f32_16x16x32_bf16 v[124:127], v[144:147], v[184:187], v[124:127]
	v_mfma_f32_16x16x32_bf16 v[124:127], v[156:159], v[188:191], v[124:127]
	v_mfma_f32_16x16x32_bf16 v[120:123], v[160:163], v[184:187], v[120:123]
	v_mfma_f32_16x16x32_bf16 v[120:123], v[164:167], v[188:191], v[120:123]
	v_mfma_f32_16x16x32_bf16 v[108:111], v[144:147], v[192:195], v[108:111]
	v_mfma_f32_16x16x32_bf16 v[108:111], v[156:159], v[196:199], v[108:111]
	v_mfma_f32_16x16x32_bf16 v[104:107], v[160:163], v[192:195], v[104:107]
	v_mfma_f32_16x16x32_bf16 v[104:107], v[164:167], v[196:199], v[104:107]
	v_mfma_f32_16x16x32_bf16 v[92:95], v[144:147], v[200:203], v[92:95]
	v_mfma_f32_16x16x32_bf16 v[92:95], v[156:159], v[204:207], v[92:95]
	v_mfma_f32_16x16x32_bf16 v[88:91], v[160:163], v[200:203], v[88:91]
	v_mfma_f32_16x16x32_bf16 v[88:91], v[164:167], v[204:207], v[88:91]
	v_mfma_f32_16x16x32_bf16 v[76:79], v[144:147], v[208:211], v[76:79]
	v_mfma_f32_16x16x32_bf16 v[76:79], v[156:159], v[212:215], v[76:79]
	v_mfma_f32_16x16x32_bf16 v[72:75], v[160:163], v[208:211], v[72:75]
	v_mfma_f32_16x16x32_bf16 v[72:75], v[164:167], v[212:215], v[72:75]
	s_setprio 0
	s_setprio 1
	v_mfma_f32_16x16x32_bf16 v[116:119], v[168:171], v[184:187], v[116:119]
	v_mfma_f32_16x16x32_bf16 v[116:119], v[172:175], v[188:191], v[116:119]
	v_mfma_f32_16x16x32_bf16 v[112:115], v[176:179], v[184:187], v[112:115]
	v_mfma_f32_16x16x32_bf16 v[112:115], v[180:183], v[188:191], v[112:115]
	v_mfma_f32_16x16x32_bf16 v[100:103], v[168:171], v[192:195], v[100:103]
	v_mfma_f32_16x16x32_bf16 v[100:103], v[172:175], v[196:199], v[100:103]
	v_mfma_f32_16x16x32_bf16 v[96:99], v[176:179], v[192:195], v[96:99]
	v_mfma_f32_16x16x32_bf16 v[96:99], v[180:183], v[196:199], v[96:99]
	v_mfma_f32_16x16x32_bf16 v[84:87], v[168:171], v[200:203], v[84:87]
	v_mfma_f32_16x16x32_bf16 v[84:87], v[172:175], v[204:207], v[84:87]
	v_mfma_f32_16x16x32_bf16 v[80:83], v[176:179], v[200:203], v[80:83]
	v_mfma_f32_16x16x32_bf16 v[80:83], v[180:183], v[204:207], v[80:83]
	v_mfma_f32_16x16x32_bf16 v[68:71], v[168:171], v[208:211], v[68:71]
	v_mfma_f32_16x16x32_bf16 v[68:71], v[172:175], v[212:215], v[68:71]
	v_mfma_f32_16x16x32_bf16 v[64:67], v[176:179], v[208:211], v[64:67]
	v_mfma_f32_16x16x32_bf16 v[64:67], v[180:183], v[212:215], v[64:67]
	s_setprio 0
	s_barrier
	s_add_i32 s42, s55, s26
	v_lshl_add_u64 v[216:217], v[216:217], 0, s[14:15]
	s_mov_b32 m0, s42
	ds_read_b128 v[184:187], v153 offset:49152
	ds_read_b128 v[188:191], v153 offset:50176
	ds_read_b128 v[192:195], v153 offset:51200
	ds_read_b128 v[196:199], v153 offset:52224
	ds_read_b128 v[200:203], v153 offset:53248
	ds_read_b128 v[204:207], v153 offset:54272
	ds_read_b128 v[208:211], v153 offset:55296
	ds_read_b128 v[212:215], v153 offset:56320
	global_load_lds_dwordx4 v[216:217], off
	s_add_i32 m0, s42, 0x2000
	s_add_u32 s40, s40, 0x40080
	v_lshl_add_u64 v[216:217], v[218:219], 0, s[14:15]
	s_addc_u32 s41, s41, 0
	s_add_i32 s42, s56, s26
	global_load_lds_dwordx4 v[216:217], off
	v_lshl_add_u64 v[216:217], s[40:41], 0, v[130:131]
	s_mov_b32 m0, s42
	s_nop 0
	global_load_lds_dwordx4 v[216:217], off
	v_lshl_add_u64 v[216:217], s[40:41], 0, v[134:135]
	s_add_i32 m0, s42, 0x2000
	s_nop 0
	global_load_lds_dwordx4 v[216:217], off
	v_lshl_add_u64 v[216:217], v[220:221], 0, s[14:15]
	s_mov_b32 m0, s37
	s_nop 0
	global_load_lds_dwordx4 v[216:217], off
	v_lshl_add_u64 v[216:217], v[222:223], 0, s[14:15]
	s_mov_b32 m0, s44
	s_nop 0
	global_load_lds_dwordx4 v[216:217], off
	s_waitcnt vmcnt(8)
	s_waitcnt lgkmcnt(0)
	s_barrier
	s_setprio 1
	s_waitcnt lgkmcnt(0)
	v_mfma_f32_16x16x32_bf16 v[60:63], v[144:147], v[184:187], v[60:63]
	v_mfma_f32_16x16x32_bf16 v[60:63], v[156:159], v[188:191], v[60:63]
	v_mfma_f32_16x16x32_bf16 v[56:59], v[160:163], v[184:187], v[56:59]
	v_mfma_f32_16x16x32_bf16 v[56:59], v[164:167], v[188:191], v[56:59]
	v_mfma_f32_16x16x32_bf16 v[44:47], v[144:147], v[192:195], v[44:47]
	v_mfma_f32_16x16x32_bf16 v[44:47], v[156:159], v[196:199], v[44:47]
	v_mfma_f32_16x16x32_bf16 v[40:43], v[160:163], v[192:195], v[40:43]
	v_mfma_f32_16x16x32_bf16 v[40:43], v[164:167], v[196:199], v[40:43]
	v_mfma_f32_16x16x32_bf16 v[28:31], v[144:147], v[200:203], v[28:31]
	v_mfma_f32_16x16x32_bf16 v[28:31], v[156:159], v[204:207], v[28:31]
	v_mfma_f32_16x16x32_bf16 v[24:27], v[160:163], v[200:203], v[24:27]
	v_mfma_f32_16x16x32_bf16 v[24:27], v[164:167], v[204:207], v[24:27]
	v_mfma_f32_16x16x32_bf16 v[12:15], v[144:147], v[208:211], v[12:15]
	v_mfma_f32_16x16x32_bf16 v[12:15], v[156:159], v[212:215], v[12:15]
	v_mfma_f32_16x16x32_bf16 v[8:11], v[160:163], v[208:211], v[8:11]
	v_mfma_f32_16x16x32_bf16 v[8:11], v[164:167], v[212:215], v[8:11]
	s_setprio 0
	s_setprio 1
	v_mfma_f32_16x16x32_bf16 v[52:55], v[168:171], v[184:187], v[52:55]
	v_mfma_f32_16x16x32_bf16 v[52:55], v[172:175], v[188:191], v[52:55]
	v_mfma_f32_16x16x32_bf16 v[48:51], v[176:179], v[184:187], v[48:51]
	v_mfma_f32_16x16x32_bf16 v[48:51], v[180:183], v[188:191], v[48:51]
	v_mfma_f32_16x16x32_bf16 v[36:39], v[168:171], v[192:195], v[36:39]
	v_mfma_f32_16x16x32_bf16 v[36:39], v[172:175], v[196:199], v[36:39]
	v_mfma_f32_16x16x32_bf16 v[32:35], v[176:179], v[192:195], v[32:35]
	v_mfma_f32_16x16x32_bf16 v[32:35], v[180:183], v[196:199], v[32:35]
	v_mfma_f32_16x16x32_bf16 v[20:23], v[168:171], v[200:203], v[20:23]
	v_mfma_f32_16x16x32_bf16 v[20:23], v[172:175], v[204:207], v[20:23]
	v_mfma_f32_16x16x32_bf16 v[16:19], v[176:179], v[200:203], v[16:19]
	v_mfma_f32_16x16x32_bf16 v[16:19], v[180:183], v[204:207], v[16:19]
	v_mfma_f32_16x16x32_bf16 v[4:7], v[168:171], v[208:211], v[4:7]
	v_mfma_f32_16x16x32_bf16 v[4:7], v[172:175], v[212:215], v[4:7]
	v_mfma_f32_16x16x32_bf16 v[0:3], v[176:179], v[208:211], v[0:3]
	v_mfma_f32_16x16x32_bf16 v[0:3], v[180:183], v[212:215], v[0:3]
	s_setprio 0
	s_barrier
	s_add_i32 s54, s54, 2
	s_add_u32 s20, s20, 0x100
	s_addc_u32 s21, s21, 0
	s_add_u32 s52, s52, 0x100
	s_addc_u32 s53, s53, 0
	s_cmp_gt_u32 s54, 13
	s_cbranch_scc0 .LBB0_685
	s_and_b64 vcc, exec, s[16:17]
	s_cbranch_vccz .LBB0_688
	s_barrier

.LBB0_793:
	ds_read_b128 v[146:149], v152
	ds_read_b128 v[156:159], v152 offset:1024
	ds_read_b128 v[160:163], v152 offset:2048
	ds_read_b128 v[164:167], v152 offset:3072
	ds_read_b128 v[168:171], v153
	ds_read_b128 v[172:175], v153 offset:1024
	ds_read_b128 v[176:179], v153 offset:2048
	ds_read_b128 v[180:183], v153 offset:3072
	s_add_u32 s38, s20, 0xfffc0080
	s_addc_u32 s39, s21, -1
	s_cmp_eq_u32 s55, 12
	s_cselect_b32 s41, s19, s39
	s_cselect_b32 s40, s51, s38
	s_cselect_b32 s39, s17, s54
	s_cselect_b32 s38, s52, s53
	v_lshl_add_u64 v[216:217], s[20:21], 0, v[136:137]
	s_add_i32 m0, s35, 0xc000
	ds_read_b128 v[184:187], v154
	ds_read_b128 v[188:191], v154 offset:1024
	ds_read_b128 v[192:195], v154 offset:2048
	ds_read_b128 v[196:199], v154 offset:3072
	ds_read_b128 v[200:203], v154 offset:4096
	ds_read_b128 v[204:207], v154 offset:5120
	ds_read_b128 v[208:211], v154 offset:6144
	ds_read_b128 v[212:215], v154 offset:7168
	global_load_lds_dwordx4 v[216:217], off
	v_lshl_add_u64 v[216:217], s[20:21], 0, v[138:139]
	s_add_i32 m0, s35, 0xe000
	s_nop 0
	global_load_lds_dwordx4 v[216:217], off
	s_waitcnt vmcnt(8)
	s_waitcnt lgkmcnt(0)
	s_barrier
	s_setprio 1
	s_waitcnt lgkmcnt(0)
	v_mfma_f32_16x16x32_bf16 v[124:127], v[146:149], v[184:187], v[124:127]
	v_mfma_f32_16x16x32_bf16 v[124:127], v[156:159], v[188:191], v[124:127]
	v_mfma_f32_16x16x32_bf16 v[120:123], v[160:163], v[184:187], v[120:123]
	v_mfma_f32_16x16x32_bf16 v[120:123], v[164:167], v[188:191], v[120:123]
	v_mfma_f32_16x16x32_bf16 v[108:111], v[146:149], v[192:195], v[108:111]
	v_mfma_f32_16x16x32_bf16 v[108:111], v[156:159], v[196:199], v[108:111]
	v_mfma_f32_16x16x32_bf16 v[104:107], v[160:163], v[192:195], v[104:107]
	v_mfma_f32_16x16x32_bf16 v[104:107], v[164:167], v[196:199], v[104:107]
	v_mfma_f32_16x16x32_bf16 v[92:95], v[146:149], v[200:203], v[92:95]
	v_mfma_f32_16x16x32_bf16 v[92:95], v[156:159], v[204:207], v[92:95]
	v_mfma_f32_16x16x32_bf16 v[88:91], v[160:163], v[200:203], v[88:91]
	v_mfma_f32_16x16x32_bf16 v[88:91], v[164:167], v[204:207], v[88:91]
	v_mfma_f32_16x16x32_bf16 v[76:79], v[146:149], v[208:211], v[76:79]
	v_mfma_f32_16x16x32_bf16 v[76:79], v[156:159], v[212:215], v[76:79]
	v_mfma_f32_16x16x32_bf16 v[72:75], v[160:163], v[208:211], v[72:75]
	v_mfma_f32_16x16x32_bf16 v[72:75], v[164:167], v[212:215], v[72:75]
	s_setprio 0
	s_setprio 1
	v_mfma_f32_16x16x32_bf16 v[116:119], v[168:171], v[184:187], v[116:119]
	v_mfma_f32_16x16x32_bf16 v[116:119], v[172:175], v[188:191], v[116:119]
	v_mfma_f32_16x16x32_bf16 v[112:115], v[176:179], v[184:187], v[112:115]
	v_mfma_f32_16x16x32_bf16 v[112:115], v[180:183], v[188:191], v[112:115]
	v_mfma_f32_16x16x32_bf16 v[100:103], v[168:171], v[192:195], v[100:103]
	v_mfma_f32_16x16x32_bf16 v[100:103], v[172:175], v[196:199], v[100:103]
	v_mfma_f32_16x16x32_bf16 v[96:99], v[176:179], v[192:195], v[96:99]
	v_mfma_f32_16x16x32_bf16 v[96:99], v[180:183], v[196:199], v[96:99]
	v_mfma_f32_16x16x32_bf16 v[84:87], v[168:171], v[200:203], v[84:87]
	v_mfma_f32_16x16x32_bf16 v[84:87], v[172:175], v[204:207], v[84:87]
	v_mfma_f32_16x16x32_bf16 v[80:83], v[176:179], v[200:203], v[80:83]
	v_mfma_f32_16x16x32_bf16 v[80:83], v[180:183], v[204:207], v[80:83]
	v_mfma_f32_16x16x32_bf16 v[68:71], v[168:171], v[208:211], v[68:71]
	v_mfma_f32_16x16x32_bf16 v[68:71], v[172:175], v[212:215], v[68:71]
	v_mfma_f32_16x16x32_bf16 v[64:67], v[176:179], v[208:211], v[64:67]
	v_mfma_f32_16x16x32_bf16 v[64:67], v[180:183], v[212:215], v[64:67]
	s_setprio 0
	s_barrier
	s_add_i32 s56, s46, s27
	v_lshl_add_u64 v[216:217], s[38:39], 0, v[132:133]
	s_mov_b32 m0, s56
	ds_read_b128 v[184:187], v154 offset:16384
	ds_read_b128 v[188:191], v154 offset:17408
	ds_read_b128 v[192:195], v154 offset:18432
	ds_read_b128 v[196:199], v154 offset:19456
	ds_read_b128 v[200:203], v154 offset:20480
	ds_read_b128 v[204:207], v154 offset:21504
	ds_read_b128 v[208:211], v154 offset:22528
	ds_read_b128 v[212:215], v154 offset:23552
	global_load_lds_dwordx4 v[216:217], off
	s_add_i32 m0, s56, 0x2000
	s_add_u32 s56, s38, 0x40000
	v_lshl_add_u64 v[218:219], s[38:39], 0, v[128:129]
	s_addc_u32 s57, s39, 0
	s_add_i32 s58, s47, s27
	global_load_lds_dwordx4 v[218:219], off
	v_lshl_add_u64 v[220:221], s[56:57], 0, v[132:133]
	s_mov_b32 m0, s58
	v_lshl_add_u64 v[222:223], s[40:41], 0, v[130:131]
	global_load_lds_dwordx4 v[220:221], off
	v_lshl_add_u64 v[220:221], s[56:57], 0, v[128:129]
	s_add_i32 m0, s58, 0x2000
	s_nop 0
	global_load_lds_dwordx4 v[220:221], off
	v_lshl_add_u64 v[220:221], s[40:41], 0, v[134:135]
	s_mov_b32 m0, s35
	s_nop 0
	global_load_lds_dwordx4 v[220:221], off
	s_mov_b32 m0, s36
	s_nop 0
	global_load_lds_dwordx4 v[222:223], off
	s_waitcnt vmcnt(8)
	s_waitcnt lgkmcnt(0)
	s_barrier
	s_setprio 1
	s_waitcnt lgkmcnt(0)
	v_mfma_f32_16x16x32_bf16 v[60:63], v[146:149], v[184:187], v[60:63]
	v_mfma_f32_16x16x32_bf16 v[60:63], v[156:159], v[188:191], v[60:63]
	v_mfma_f32_16x16x32_bf16 v[56:59], v[160:163], v[184:187], v[56:59]
	v_mfma_f32_16x16x32_bf16 v[56:59], v[164:167], v[188:191], v[56:59]
	v_mfma_f32_16x16x32_bf16 v[44:47], v[146:149], v[192:195], v[44:47]
	v_mfma_f32_16x16x32_bf16 v[44:47], v[156:159], v[196:199], v[44:47]
	v_mfma_f32_16x16x32_bf16 v[40:43], v[160:163], v[192:195], v[40:43]
	v_mfma_f32_16x16x32_bf16 v[40:43], v[164:167], v[196:199], v[40:43]
	v_mfma_f32_16x16x32_bf16 v[28:31], v[146:149], v[200:203], v[28:31]
	v_mfma_f32_16x16x32_bf16 v[28:31], v[156:159], v[204:207], v[28:31]
	v_mfma_f32_16x16x32_bf16 v[24:27], v[160:163], v[200:203], v[24:27]
	v_mfma_f32_16x16x32_bf16 v[24:27], v[164:167], v[204:207], v[24:27]
	v_mfma_f32_16x16x32_bf16 v[12:15], v[146:149], v[208:211], v[12:15]
	v_mfma_f32_16x16x32_bf16 v[12:15], v[156:159], v[212:215], v[12:15]
	v_mfma_f32_16x16x32_bf16 v[8:11], v[160:163], v[208:211], v[8:11]
	v_mfma_f32_16x16x32_bf16 v[8:11], v[164:167], v[212:215], v[8:11]
	s_setprio 0
	s_setprio 1
	v_mfma_f32_16x16x32_bf16 v[52:55], v[168:171], v[184:187], v[52:55]
	v_mfma_f32_16x16x32_bf16 v[52:55], v[172:175], v[188:191], v[52:55]
	v_mfma_f32_16x16x32_bf16 v[48:51], v[176:179], v[184:187], v[48:51]
	v_mfma_f32_16x16x32_bf16 v[48:51], v[180:183], v[188:191], v[48:51]
	v_mfma_f32_16x16x32_bf16 v[36:39], v[168:171], v[192:195], v[36:39]
	v_mfma_f32_16x16x32_bf16 v[36:39], v[172:175], v[196:199], v[36:39]
	v_mfma_f32_16x16x32_bf16 v[32:35], v[176:179], v[192:195], v[32:35]
	v_mfma_f32_16x16x32_bf16 v[32:35], v[180:183], v[196:199], v[32:35]
	v_mfma_f32_16x16x32_bf16 v[20:23], v[168:171], v[200:203], v[20:23]
	v_mfma_f32_16x16x32_bf16 v[20:23], v[172:175], v[204:207], v[20:23]
	v_mfma_f32_16x16x32_bf16 v[16:19], v[176:179], v[200:203], v[16:19]
	v_mfma_f32_16x16x32_bf16 v[16:19], v[180:183], v[204:207], v[16:19]
	v_mfma_f32_16x16x32_bf16 v[4:7], v[168:171], v[208:211], v[4:7]
	v_mfma_f32_16x16x32_bf16 v[4:7], v[172:175], v[212:215], v[4:7]
	v_mfma_f32_16x16x32_bf16 v[0:3], v[176:179], v[208:211], v[0:3]
	v_mfma_f32_16x16x32_bf16 v[0:3], v[180:183], v[212:215], v[0:3]
	s_setprio 0
	s_barrier
	s_add_i32 s56, 0, 0x18000
	s_add_i32 s57, 0, 0x1c000
	v_add_u32_e32 v164, s56, v151
	v_add_u32_e32 v180, s57, v151
	ds_read_b128 v[146:149], v164
	ds_read_b128 v[156:159], v164 offset:1024
	ds_read_b128 v[160:163], v164 offset:2048
	ds_read_b128 v[164:167], v164 offset:3072
	ds_read_b128 v[168:171], v180
	ds_read_b128 v[172:175], v180 offset:1024
	ds_read_b128 v[176:179], v180 offset:2048
	ds_read_b128 v[180:183], v180 offset:3072
	s_add_u32 s40, s40, 0x40000
	s_addc_u32 s41, s41, 0
	s_mov_b32 m0, s37
	v_lshl_add_u64 v[224:225], s[40:41], 0, v[134:135]
	ds_read_b128 v[184:187], v154 offset:32768
	ds_read_b128 v[188:191], v154 offset:33792
	ds_read_b128 v[192:195], v154 offset:34816
	ds_read_b128 v[196:199], v154 offset:35840
	ds_read_b128 v[200:203], v154 offset:36864
	ds_read_b128 v[204:207], v154 offset:37888
	ds_read_b128 v[208:211], v154 offset:38912
	ds_read_b128 v[212:215], v154 offset:39936
	global_load_lds_dwordx4 v[224:225], off
	v_lshl_add_u64 v[224:225], s[40:41], 0, v[130:131]
	s_mov_b32 m0, s42
	s_nop 0
	global_load_lds_dwordx4 v[224:225], off
	s_waitcnt vmcnt(8)
	s_waitcnt lgkmcnt(0)
	s_barrier
	s_setprio 1
	s_waitcnt lgkmcnt(0)
	v_mfma_f32_16x16x32_bf16 v[124:127], v[146:149], v[184:187], v[124:127]
	v_mfma_f32_16x16x32_bf16 v[124:127], v[156:159], v[188:191], v[124:127]
	v_mfma_f32_16x16x32_bf16 v[120:123], v[160:163], v[184:187], v[120:123]
	v_mfma_f32_16x16x32_bf16 v[120:123], v[164:167], v[188:191], v[120:123]
	v_mfma_f32_16x16x32_bf16 v[108:111], v[146:149], v[192:195], v[108:111]
	v_mfma_f32_16x16x32_bf16 v[108:111], v[156:159], v[196:199], v[108:111]
	v_mfma_f32_16x16x32_bf16 v[104:107], v[160:163], v[192:195], v[104:107]
	v_mfma_f32_16x16x32_bf16 v[104:107], v[164:167], v[196:199], v[104:107]
	v_mfma_f32_16x16x32_bf16 v[92:95], v[146:149], v[200:203], v[92:95]
	v_mfma_f32_16x16x32_bf16 v[92:95], v[156:159], v[204:207], v[92:95]
	v_mfma_f32_16x16x32_bf16 v[88:91], v[160:163], v[200:203], v[88:91]
	v_mfma_f32_16x16x32_bf16 v[88:91], v[164:167], v[204:207], v[88:91]
	v_mfma_f32_16x16x32_bf16 v[76:79], v[146:149], v[208:211], v[76:79]
	v_mfma_f32_16x16x32_bf16 v[76:79], v[156:159], v[212:215], v[76:79]
	v_mfma_f32_16x16x32_bf16 v[72:75], v[160:163], v[208:211], v[72:75]
	v_mfma_f32_16x16x32_bf16 v[72:75], v[164:167], v[212:215], v[72:75]
	s_setprio 0
	s_setprio 1
	v_mfma_f32_16x16x32_bf16 v[116:119], v[168:171], v[184:187], v[116:119]
	v_mfma_f32_16x16x32_bf16 v[116:119], v[172:175], v[188:191], v[116:119]
	v_mfma_f32_16x16x32_bf16 v[112:115], v[176:179], v[184:187], v[112:115]
	v_mfma_f32_16x16x32_bf16 v[112:115], v[180:183], v[188:191], v[112:115]
	v_mfma_f32_16x16x32_bf16 v[100:103], v[168:171], v[192:195], v[100:103]
	v_mfma_f32_16x16x32_bf16 v[100:103], v[172:175], v[196:199], v[100:103]
	v_mfma_f32_16x16x32_bf16 v[96:99], v[176:179], v[192:195], v[96:99]
	v_mfma_f32_16x16x32_bf16 v[96:99], v[180:183], v[196:199], v[96:99]
	v_mfma_f32_16x16x32_bf16 v[84:87], v[168:171], v[200:203], v[84:87]
	v_mfma_f32_16x16x32_bf16 v[84:87], v[172:175], v[204:207], v[84:87]
	v_mfma_f32_16x16x32_bf16 v[80:83], v[176:179], v[200:203], v[80:83]
	v_mfma_f32_16x16x32_bf16 v[80:83], v[180:183], v[204:207], v[80:83]
	v_mfma_f32_16x16x32_bf16 v[68:71], v[168:171], v[208:211], v[68:71]
	v_mfma_f32_16x16x32_bf16 v[68:71], v[172:175], v[212:215], v[68:71]
	v_mfma_f32_16x16x32_bf16 v[64:67], v[176:179], v[208:211], v[64:67]
	v_mfma_f32_16x16x32_bf16 v[64:67], v[180:183], v[212:215], v[64:67]
	s_setprio 0
	s_barrier
	s_add_i32 s40, s56, s27
	v_lshl_add_u64 v[216:217], v[216:217], 0, s[12:13]
	s_mov_b32 m0, s40
	ds_read_b128 v[184:187], v154 offset:49152
	ds_read_b128 v[188:191], v154 offset:50176
	ds_read_b128 v[192:195], v154 offset:51200
	ds_read_b128 v[196:199], v154 offset:52224
	ds_read_b128 v[200:203], v154 offset:53248
	ds_read_b128 v[204:207], v154 offset:54272
	ds_read_b128 v[208:211], v154 offset:55296
	ds_read_b128 v[212:215], v154 offset:56320
	global_load_lds_dwordx4 v[216:217], off
	s_add_i32 m0, s40, 0x2000
	s_add_u32 s38, s38, 0x40080
	v_lshl_add_u64 v[216:217], v[218:219], 0, s[12:13]
	s_addc_u32 s39, s39, 0
	s_add_i32 s40, s57, s27
	global_load_lds_dwordx4 v[216:217], off
	v_lshl_add_u64 v[216:217], s[38:39], 0, v[132:133]
	s_mov_b32 m0, s40
	s_nop 0
	global_load_lds_dwordx4 v[216:217], off
	v_lshl_add_u64 v[216:217], s[38:39], 0, v[128:129]
	s_add_i32 m0, s40, 0x2000
	s_nop 0
	global_load_lds_dwordx4 v[216:217], off
	v_lshl_add_u64 v[216:217], v[220:221], 0, s[12:13]
	s_mov_b32 m0, s43
	s_nop 0
	global_load_lds_dwordx4 v[216:217], off
	v_lshl_add_u64 v[216:217], v[222:223], 0, s[12:13]
	s_mov_b32 m0, s44
	s_nop 0
	global_load_lds_dwordx4 v[216:217], off
	s_waitcnt vmcnt(8)
	s_waitcnt lgkmcnt(0)
	s_barrier
	s_setprio 1
	s_waitcnt lgkmcnt(0)
	v_mfma_f32_16x16x32_bf16 v[60:63], v[146:149], v[184:187], v[60:63]
	v_mfma_f32_16x16x32_bf16 v[60:63], v[156:159], v[188:191], v[60:63]
	v_mfma_f32_16x16x32_bf16 v[56:59], v[160:163], v[184:187], v[56:59]
	v_mfma_f32_16x16x32_bf16 v[56:59], v[164:167], v[188:191], v[56:59]
	v_mfma_f32_16x16x32_bf16 v[44:47], v[146:149], v[192:195], v[44:47]
	v_mfma_f32_16x16x32_bf16 v[44:47], v[156:159], v[196:199], v[44:47]
	v_mfma_f32_16x16x32_bf16 v[40:43], v[160:163], v[192:195], v[40:43]
	v_mfma_f32_16x16x32_bf16 v[40:43], v[164:167], v[196:199], v[40:43]
	v_mfma_f32_16x16x32_bf16 v[28:31], v[146:149], v[200:203], v[28:31]
	v_mfma_f32_16x16x32_bf16 v[28:31], v[156:159], v[204:207], v[28:31]
	v_mfma_f32_16x16x32_bf16 v[24:27], v[160:163], v[200:203], v[24:27]
	v_mfma_f32_16x16x32_bf16 v[24:27], v[164:167], v[204:207], v[24:27]
	v_mfma_f32_16x16x32_bf16 v[12:15], v[146:149], v[208:211], v[12:15]
	v_mfma_f32_16x16x32_bf16 v[12:15], v[156:159], v[212:215], v[12:15]
	v_mfma_f32_16x16x32_bf16 v[8:11], v[160:163], v[208:211], v[8:11]
	v_mfma_f32_16x16x32_bf16 v[8:11], v[164:167], v[212:215], v[8:11]
	s_setprio 0
	s_setprio 1
	v_mfma_f32_16x16x32_bf16 v[52:55], v[168:171], v[184:187], v[52:55]
	v_mfma_f32_16x16x32_bf16 v[52:55], v[172:175], v[188:191], v[52:55]
	v_mfma_f32_16x16x32_bf16 v[48:51], v[176:179], v[184:187], v[48:51]
	v_mfma_f32_16x16x32_bf16 v[48:51], v[180:183], v[188:191], v[48:51]
	v_mfma_f32_16x16x32_bf16 v[36:39], v[168:171], v[192:195], v[36:39]
	v_mfma_f32_16x16x32_bf16 v[36:39], v[172:175], v[196:199], v[36:39]
	v_mfma_f32_16x16x32_bf16 v[32:35], v[176:179], v[192:195], v[32:35]
	v_mfma_f32_16x16x32_bf16 v[32:35], v[180:183], v[196:199], v[32:35]
	v_mfma_f32_16x16x32_bf16 v[20:23], v[168:171], v[200:203], v[20:23]
	v_mfma_f32_16x16x32_bf16 v[20:23], v[172:175], v[204:207], v[20:23]
	v_mfma_f32_16x16x32_bf16 v[16:19], v[176:179], v[200:203], v[16:19]
	v_mfma_f32_16x16x32_bf16 v[16:19], v[180:183], v[204:207], v[16:19]
	v_mfma_f32_16x16x32_bf16 v[4:7], v[168:171], v[208:211], v[4:7]
	v_mfma_f32_16x16x32_bf16 v[4:7], v[172:175], v[212:215], v[4:7]
	v_mfma_f32_16x16x32_bf16 v[0:3], v[176:179], v[208:211], v[0:3]
	v_mfma_f32_16x16x32_bf16 v[0:3], v[180:183], v[212:215], v[0:3]
	s_setprio 0
	s_barrier
	s_add_i32 s55, s55, 2
	s_add_u32 s20, s20, 0x100
	s_addc_u32 s21, s21, 0
	s_add_u32 s53, s53, 0x100
	s_addc_u32 s54, s54, 0
	s_cmp_gt_u32 s55, 13
	s_cbranch_scc0 .LBB0_793
	s_and_b64 vcc, exec, s[14:15]
	s_cbranch_vccz .LBB0_796
	s_barrier

.LBB0_908:
	ds_read_b128 v[144:147], v151
	ds_read_b128 v[156:159], v151 offset:1024
	ds_read_b128 v[160:163], v151 offset:2048
	ds_read_b128 v[164:167], v151 offset:3072
	ds_read_b128 v[168:171], v152
	ds_read_b128 v[172:175], v152 offset:1024
	ds_read_b128 v[176:179], v152 offset:2048
	ds_read_b128 v[180:183], v152 offset:3072
	s_add_u32 s28, s20, 0x100
	s_addc_u32 s29, s21, 0
	s_cmp_eq_u32 s55, 40
	s_cselect_b32 s39, s7, s29
	s_cselect_b32 s38, s6, s28
	s_cselect_b32 s31, s23, s54
	s_cselect_b32 s30, s22, s53
	v_lshl_add_u64 v[216:217], s[20:21], 0, v[136:137]
	s_add_i32 m0, s35, 0xc000
	ds_read_b128 v[184:187], v153
	ds_read_b128 v[188:191], v153 offset:1024
	ds_read_b128 v[192:195], v153 offset:2048
	ds_read_b128 v[196:199], v153 offset:3072
	ds_read_b128 v[200:203], v153 offset:4096
	ds_read_b128 v[204:207], v153 offset:5120
	ds_read_b128 v[208:211], v153 offset:6144
	ds_read_b128 v[212:215], v153 offset:7168
	global_load_lds_dwordx4 v[216:217], off
	v_lshl_add_u64 v[216:217], s[20:21], 0, v[138:139]
	s_add_i32 m0, s35, 0xe000
	s_nop 0
	global_load_lds_dwordx4 v[216:217], off
	s_waitcnt vmcnt(8)
	s_waitcnt lgkmcnt(0)
	s_barrier
	s_setprio 1
	s_waitcnt lgkmcnt(0)
	v_mfma_f32_16x16x32_bf16 v[124:127], v[144:147], v[184:187], v[124:127]
	v_mfma_f32_16x16x32_bf16 v[124:127], v[156:159], v[188:191], v[124:127]
	v_mfma_f32_16x16x32_bf16 v[120:123], v[160:163], v[184:187], v[120:123]
	v_mfma_f32_16x16x32_bf16 v[120:123], v[164:167], v[188:191], v[120:123]
	v_mfma_f32_16x16x32_bf16 v[108:111], v[144:147], v[192:195], v[108:111]
	v_mfma_f32_16x16x32_bf16 v[108:111], v[156:159], v[196:199], v[108:111]
	v_mfma_f32_16x16x32_bf16 v[104:107], v[160:163], v[192:195], v[104:107]
	v_mfma_f32_16x16x32_bf16 v[104:107], v[164:167], v[196:199], v[104:107]
	v_mfma_f32_16x16x32_bf16 v[92:95], v[144:147], v[200:203], v[92:95]
	v_mfma_f32_16x16x32_bf16 v[92:95], v[156:159], v[204:207], v[92:95]
	v_mfma_f32_16x16x32_bf16 v[88:91], v[160:163], v[200:203], v[88:91]
	v_mfma_f32_16x16x32_bf16 v[88:91], v[164:167], v[204:207], v[88:91]
	v_mfma_f32_16x16x32_bf16 v[76:79], v[144:147], v[208:211], v[76:79]
	v_mfma_f32_16x16x32_bf16 v[76:79], v[156:159], v[212:215], v[76:79]
	v_mfma_f32_16x16x32_bf16 v[72:75], v[160:163], v[208:211], v[72:75]
	v_mfma_f32_16x16x32_bf16 v[72:75], v[164:167], v[212:215], v[72:75]
	s_setprio 0
	s_setprio 1
	v_mfma_f32_16x16x32_bf16 v[116:119], v[168:171], v[184:187], v[116:119]
	v_mfma_f32_16x16x32_bf16 v[116:119], v[172:175], v[188:191], v[116:119]
	v_mfma_f32_16x16x32_bf16 v[112:115], v[176:179], v[184:187], v[112:115]
	v_mfma_f32_16x16x32_bf16 v[112:115], v[180:183], v[188:191], v[112:115]
	v_mfma_f32_16x16x32_bf16 v[100:103], v[168:171], v[192:195], v[100:103]
	v_mfma_f32_16x16x32_bf16 v[100:103], v[172:175], v[196:199], v[100:103]
	v_mfma_f32_16x16x32_bf16 v[96:99], v[176:179], v[192:195], v[96:99]
	v_mfma_f32_16x16x32_bf16 v[96:99], v[180:183], v[196:199], v[96:99]
	v_mfma_f32_16x16x32_bf16 v[84:87], v[168:171], v[200:203], v[84:87]
	v_mfma_f32_16x16x32_bf16 v[84:87], v[172:175], v[204:207], v[84:87]
	v_mfma_f32_16x16x32_bf16 v[80:83], v[176:179], v[200:203], v[80:83]
	v_mfma_f32_16x16x32_bf16 v[80:83], v[180:183], v[204:207], v[80:83]
	v_mfma_f32_16x16x32_bf16 v[68:71], v[168:171], v[208:211], v[68:71]
	v_mfma_f32_16x16x32_bf16 v[68:71], v[172:175], v[212:215], v[68:71]
	v_mfma_f32_16x16x32_bf16 v[64:67], v[176:179], v[208:211], v[64:67]
	v_mfma_f32_16x16x32_bf16 v[64:67], v[180:183], v[212:215], v[64:67]
	s_setprio 0
	s_barrier
	s_add_i32 s20, s47, s0
	v_lshl_add_u64 v[216:217], s[30:31], 0, v[130:131]
	s_mov_b32 m0, s20
	ds_read_b128 v[184:187], v153 offset:16384
	ds_read_b128 v[188:191], v153 offset:17408
	ds_read_b128 v[192:195], v153 offset:18432
	ds_read_b128 v[196:199], v153 offset:19456
	ds_read_b128 v[200:203], v153 offset:20480
	ds_read_b128 v[204:207], v153 offset:21504
	ds_read_b128 v[208:211], v153 offset:22528
	ds_read_b128 v[212:215], v153 offset:23552
	global_load_lds_dwordx4 v[216:217], off
	s_add_i32 m0, s20, 0x2000
	s_add_u32 s20, s30, 0xb0000
	v_lshl_add_u64 v[218:219], s[30:31], 0, v[134:135]
	s_addc_u32 s21, s31, 0
	s_add_i32 s56, s48, s0
	global_load_lds_dwordx4 v[218:219], off
	v_lshl_add_u64 v[220:221], s[20:21], 0, v[130:131]
	s_mov_b32 m0, s56
	v_lshl_add_u64 v[222:223], s[38:39], 0, v[132:133]
	global_load_lds_dwordx4 v[220:221], off
	v_lshl_add_u64 v[220:221], s[20:21], 0, v[134:135]
	s_add_i32 m0, s56, 0x2000
	s_nop 0
	global_load_lds_dwordx4 v[220:221], off
	v_lshl_add_u64 v[220:221], s[38:39], 0, v[128:129]
	s_mov_b32 m0, s35
	s_nop 0
	global_load_lds_dwordx4 v[220:221], off
	s_mov_b32 m0, s36
	s_nop 0
	global_load_lds_dwordx4 v[222:223], off
	s_waitcnt vmcnt(8)
	s_waitcnt lgkmcnt(0)
	s_barrier
	s_setprio 1
	s_waitcnt lgkmcnt(0)
	v_mfma_f32_16x16x32_bf16 v[60:63], v[144:147], v[184:187], v[60:63]
	v_mfma_f32_16x16x32_bf16 v[60:63], v[156:159], v[188:191], v[60:63]
	v_mfma_f32_16x16x32_bf16 v[56:59], v[160:163], v[184:187], v[56:59]
	v_mfma_f32_16x16x32_bf16 v[56:59], v[164:167], v[188:191], v[56:59]
	v_mfma_f32_16x16x32_bf16 v[44:47], v[144:147], v[192:195], v[44:47]
	v_mfma_f32_16x16x32_bf16 v[44:47], v[156:159], v[196:199], v[44:47]
	v_mfma_f32_16x16x32_bf16 v[40:43], v[160:163], v[192:195], v[40:43]
	v_mfma_f32_16x16x32_bf16 v[40:43], v[164:167], v[196:199], v[40:43]
	v_mfma_f32_16x16x32_bf16 v[28:31], v[144:147], v[200:203], v[28:31]
	v_mfma_f32_16x16x32_bf16 v[28:31], v[156:159], v[204:207], v[28:31]
	v_mfma_f32_16x16x32_bf16 v[24:27], v[160:163], v[200:203], v[24:27]
	v_mfma_f32_16x16x32_bf16 v[24:27], v[164:167], v[204:207], v[24:27]
	v_mfma_f32_16x16x32_bf16 v[12:15], v[144:147], v[208:211], v[12:15]
	v_mfma_f32_16x16x32_bf16 v[12:15], v[156:159], v[212:215], v[12:15]
	v_mfma_f32_16x16x32_bf16 v[8:11], v[160:163], v[208:211], v[8:11]
	v_mfma_f32_16x16x32_bf16 v[8:11], v[164:167], v[212:215], v[8:11]
	s_setprio 0
	s_setprio 1
	v_mfma_f32_16x16x32_bf16 v[52:55], v[168:171], v[184:187], v[52:55]
	v_mfma_f32_16x16x32_bf16 v[52:55], v[172:175], v[188:191], v[52:55]
	v_mfma_f32_16x16x32_bf16 v[48:51], v[176:179], v[184:187], v[48:51]
	v_mfma_f32_16x16x32_bf16 v[48:51], v[180:183], v[188:191], v[48:51]
	v_mfma_f32_16x16x32_bf16 v[36:39], v[168:171], v[192:195], v[36:39]
	v_mfma_f32_16x16x32_bf16 v[36:39], v[172:175], v[196:199], v[36:39]
	v_mfma_f32_16x16x32_bf16 v[32:35], v[176:179], v[192:195], v[32:35]
	v_mfma_f32_16x16x32_bf16 v[32:35], v[180:183], v[196:199], v[32:35]
	v_mfma_f32_16x16x32_bf16 v[20:23], v[168:171], v[200:203], v[20:23]
	v_mfma_f32_16x16x32_bf16 v[20:23], v[172:175], v[204:207], v[20:23]
	v_mfma_f32_16x16x32_bf16 v[16:19], v[176:179], v[200:203], v[16:19]
	v_mfma_f32_16x16x32_bf16 v[16:19], v[180:183], v[204:207], v[16:19]
	v_mfma_f32_16x16x32_bf16 v[4:7], v[168:171], v[208:211], v[4:7]
	v_mfma_f32_16x16x32_bf16 v[4:7], v[172:175], v[212:215], v[4:7]
	v_mfma_f32_16x16x32_bf16 v[0:3], v[176:179], v[208:211], v[0:3]
	v_mfma_f32_16x16x32_bf16 v[0:3], v[180:183], v[212:215], v[0:3]
	s_setprio 0
	s_barrier
	s_add_i32 s56, 0, 0x18000
	v_add_u32_e32 v155, s56, v149
	s_add_i32 s57, 0, 0x1c000
	ds_read_b128 v[144:147], v155
	ds_read_b128 v[156:159], v155 offset:1024
	ds_read_b128 v[160:163], v155 offset:2048
	ds_read_b128 v[164:167], v155 offset:3072
	v_add_u32_e32 v155, s57, v149
	ds_read_b128 v[168:171], v155
	ds_read_b128 v[172:175], v155 offset:1024
	ds_read_b128 v[176:179], v155 offset:2048
	ds_read_b128 v[180:183], v155 offset:3072
	s_add_u32 s20, s38, 0xb0000
	s_addc_u32 s21, s39, 0
	s_mov_b32 m0, s37
	v_lshl_add_u64 v[224:225], s[20:21], 0, v[128:129]
	ds_read_b128 v[184:187], v153 offset:32768
	ds_read_b128 v[188:191], v153 offset:33792
	ds_read_b128 v[192:195], v153 offset:34816
	ds_read_b128 v[196:199], v153 offset:35840
	ds_read_b128 v[200:203], v153 offset:36864
	ds_read_b128 v[204:207], v153 offset:37888
	ds_read_b128 v[208:211], v153 offset:38912
	ds_read_b128 v[212:215], v153 offset:39936
	global_load_lds_dwordx4 v[224:225], off
	v_lshl_add_u64 v[224:225], s[20:21], 0, v[132:133]
	s_mov_b32 m0, s40
	s_nop 0
	global_load_lds_dwordx4 v[224:225], off
	s_waitcnt vmcnt(8)
	s_waitcnt lgkmcnt(0)
	s_barrier
	s_setprio 1
	s_waitcnt lgkmcnt(0)
	v_mfma_f32_16x16x32_bf16 v[124:127], v[144:147], v[184:187], v[124:127]
	v_mfma_f32_16x16x32_bf16 v[124:127], v[156:159], v[188:191], v[124:127]
	v_mfma_f32_16x16x32_bf16 v[120:123], v[160:163], v[184:187], v[120:123]
	v_mfma_f32_16x16x32_bf16 v[120:123], v[164:167], v[188:191], v[120:123]
	v_mfma_f32_16x16x32_bf16 v[108:111], v[144:147], v[192:195], v[108:111]
	v_mfma_f32_16x16x32_bf16 v[108:111], v[156:159], v[196:199], v[108:111]
	v_mfma_f32_16x16x32_bf16 v[104:107], v[160:163], v[192:195], v[104:107]
	v_mfma_f32_16x16x32_bf16 v[104:107], v[164:167], v[196:199], v[104:107]
	v_mfma_f32_16x16x32_bf16 v[92:95], v[144:147], v[200:203], v[92:95]
	v_mfma_f32_16x16x32_bf16 v[92:95], v[156:159], v[204:207], v[92:95]
	v_mfma_f32_16x16x32_bf16 v[88:91], v[160:163], v[200:203], v[88:91]
	v_mfma_f32_16x16x32_bf16 v[88:91], v[164:167], v[204:207], v[88:91]
	v_mfma_f32_16x16x32_bf16 v[76:79], v[144:147], v[208:211], v[76:79]
	v_mfma_f32_16x16x32_bf16 v[76:79], v[156:159], v[212:215], v[76:79]
	v_mfma_f32_16x16x32_bf16 v[72:75], v[160:163], v[208:211], v[72:75]
	v_mfma_f32_16x16x32_bf16 v[72:75], v[164:167], v[212:215], v[72:75]
	s_setprio 0
	s_setprio 1
	v_mfma_f32_16x16x32_bf16 v[116:119], v[168:171], v[184:187], v[116:119]
	v_mfma_f32_16x16x32_bf16 v[116:119], v[172:175], v[188:191], v[116:119]
	v_mfma_f32_16x16x32_bf16 v[112:115], v[176:179], v[184:187], v[112:115]
	v_mfma_f32_16x16x32_bf16 v[112:115], v[180:183], v[188:191], v[112:115]
	v_mfma_f32_16x16x32_bf16 v[100:103], v[168:171], v[192:195], v[100:103]
	v_mfma_f32_16x16x32_bf16 v[100:103], v[172:175], v[196:199], v[100:103]
	v_mfma_f32_16x16x32_bf16 v[96:99], v[176:179], v[192:195], v[96:99]
	v_mfma_f32_16x16x32_bf16 v[96:99], v[180:183], v[196:199], v[96:99]
	v_mfma_f32_16x16x32_bf16 v[84:87], v[168:171], v[200:203], v[84:87]
	v_mfma_f32_16x16x32_bf16 v[84:87], v[172:175], v[204:207], v[84:87]
	v_mfma_f32_16x16x32_bf16 v[80:83], v[176:179], v[200:203], v[80:83]
	v_mfma_f32_16x16x32_bf16 v[80:83], v[180:183], v[204:207], v[80:83]
	v_mfma_f32_16x16x32_bf16 v[68:71], v[168:171], v[208:211], v[68:71]
	v_mfma_f32_16x16x32_bf16 v[68:71], v[172:175], v[212:215], v[68:71]
	v_mfma_f32_16x16x32_bf16 v[64:67], v[176:179], v[208:211], v[64:67]
	v_mfma_f32_16x16x32_bf16 v[64:67], v[180:183], v[212:215], v[64:67]
	s_setprio 0
	s_barrier
	s_add_i32 s20, s56, s0
	v_lshl_add_u64 v[216:217], v[216:217], 0, s[16:17]
	s_mov_b32 m0, s20
	ds_read_b128 v[184:187], v153 offset:49152
	ds_read_b128 v[188:191], v153 offset:50176
	ds_read_b128 v[192:195], v153 offset:51200
	ds_read_b128 v[196:199], v153 offset:52224
	ds_read_b128 v[200:203], v153 offset:53248
	ds_read_b128 v[204:207], v153 offset:54272
	ds_read_b128 v[208:211], v153 offset:55296
	ds_read_b128 v[212:215], v153 offset:56320
	global_load_lds_dwordx4 v[216:217], off
	s_add_i32 m0, s20, 0x2000
	s_add_u32 s20, s30, 0xb0080
	v_lshl_add_u64 v[216:217], v[218:219], 0, s[16:17]
	s_addc_u32 s21, s31, 0
	s_add_i32 s30, s57, s0
	global_load_lds_dwordx4 v[216:217], off
	v_lshl_add_u64 v[216:217], s[20:21], 0, v[130:131]
	s_mov_b32 m0, s30
	s_nop 0
	global_load_lds_dwordx4 v[216:217], off
	v_lshl_add_u64 v[216:217], s[20:21], 0, v[134:135]
	s_add_i32 m0, s30, 0x2000
	s_nop 0
	global_load_lds_dwordx4 v[216:217], off
	v_lshl_add_u64 v[216:217], v[220:221], 0, s[16:17]
	s_mov_b32 m0, s42
	s_nop 0
	global_load_lds_dwordx4 v[216:217], off
	v_lshl_add_u64 v[216:217], v[222:223], 0, s[16:17]
	s_mov_b32 m0, s43
	s_nop 0
	global_load_lds_dwordx4 v[216:217], off
	s_waitcnt vmcnt(8)
	s_waitcnt lgkmcnt(0)
	s_barrier
	s_setprio 1
	s_waitcnt lgkmcnt(0)
	v_mfma_f32_16x16x32_bf16 v[60:63], v[144:147], v[184:187], v[60:63]
	v_mfma_f32_16x16x32_bf16 v[60:63], v[156:159], v[188:191], v[60:63]
	v_mfma_f32_16x16x32_bf16 v[56:59], v[160:163], v[184:187], v[56:59]
	v_mfma_f32_16x16x32_bf16 v[56:59], v[164:167], v[188:191], v[56:59]
	v_mfma_f32_16x16x32_bf16 v[44:47], v[144:147], v[192:195], v[44:47]
	v_mfma_f32_16x16x32_bf16 v[44:47], v[156:159], v[196:199], v[44:47]
	v_mfma_f32_16x16x32_bf16 v[40:43], v[160:163], v[192:195], v[40:43]
	v_mfma_f32_16x16x32_bf16 v[40:43], v[164:167], v[196:199], v[40:43]
	v_mfma_f32_16x16x32_bf16 v[28:31], v[144:147], v[200:203], v[28:31]
	v_mfma_f32_16x16x32_bf16 v[28:31], v[156:159], v[204:207], v[28:31]
	v_mfma_f32_16x16x32_bf16 v[24:27], v[160:163], v[200:203], v[24:27]
	v_mfma_f32_16x16x32_bf16 v[24:27], v[164:167], v[204:207], v[24:27]
	v_mfma_f32_16x16x32_bf16 v[12:15], v[144:147], v[208:211], v[12:15]
	v_mfma_f32_16x16x32_bf16 v[12:15], v[156:159], v[212:215], v[12:15]
	v_mfma_f32_16x16x32_bf16 v[8:11], v[160:163], v[208:211], v[8:11]
	v_mfma_f32_16x16x32_bf16 v[8:11], v[164:167], v[212:215], v[8:11]
	s_setprio 0
	s_setprio 1
	v_mfma_f32_16x16x32_bf16 v[52:55], v[168:171], v[184:187], v[52:55]
	v_mfma_f32_16x16x32_bf16 v[52:55], v[172:175], v[188:191], v[52:55]
	v_mfma_f32_16x16x32_bf16 v[48:51], v[176:179], v[184:187], v[48:51]
	v_mfma_f32_16x16x32_bf16 v[48:51], v[180:183], v[188:191], v[48:51]
	v_mfma_f32_16x16x32_bf16 v[36:39], v[168:171], v[192:195], v[36:39]
	v_mfma_f32_16x16x32_bf16 v[36:39], v[172:175], v[196:199], v[36:39]
	v_mfma_f32_16x16x32_bf16 v[32:35], v[176:179], v[192:195], v[32:35]
	v_mfma_f32_16x16x32_bf16 v[32:35], v[180:183], v[196:199], v[32:35]
	v_mfma_f32_16x16x32_bf16 v[20:23], v[168:171], v[200:203], v[20:23]
	v_mfma_f32_16x16x32_bf16 v[20:23], v[172:175], v[204:207], v[20:23]
	v_mfma_f32_16x16x32_bf16 v[16:19], v[176:179], v[200:203], v[16:19]
	v_mfma_f32_16x16x32_bf16 v[16:19], v[180:183], v[204:207], v[16:19]
	v_mfma_f32_16x16x32_bf16 v[4:7], v[168:171], v[208:211], v[4:7]
	v_mfma_f32_16x16x32_bf16 v[4:7], v[172:175], v[212:215], v[4:7]
	v_mfma_f32_16x16x32_bf16 v[0:3], v[176:179], v[208:211], v[0:3]
	v_mfma_f32_16x16x32_bf16 v[0:3], v[180:183], v[212:215], v[0:3]
	s_setprio 0
	s_barrier
	s_add_i32 s55, s55, 2
	s_add_u32 s53, s53, 0x100
	s_addc_u32 s54, s54, 0
	s_cmp_gt_u32 s55, 41
	s_mov_b64 s[20:21], s[28:29]
	s_cbranch_scc0 .LBB0_908
	s_and_b64 vcc, exec, s[18:19]
	s_cbranch_vccz .LBB0_911
	s_barrier

.LBB0_942:
	ds_read_b128 v[0:3], v143
	ds_read_b128 v[4:7], v143 offset:1024
	ds_read_b128 v[8:11], v143 offset:2048
	ds_read_b128 v[12:15], v143 offset:3072
	ds_read_b128 v[16:19], v144
	ds_read_b128 v[20:23], v144 offset:1024
	ds_read_b128 v[24:27], v144 offset:2048
	ds_read_b128 v[28:31], v144 offset:3072
	s_ashr_i32 s23, s22, 31
	s_lshl_b64 s[28:29], s[22:23], 17
	s_add_u32 s28, s26, s28
	s_addc_u32 s29, s27, s29
	s_and_b64 s[30:31], s[2:3], exec
	s_cselect_b32 s45, s29, s39
	s_cselect_b32 s44, s28, s38
	s_ashr_i32 s21, s20, 31
	s_lshl_b64 s[30:31], s[20:21], 17
	s_add_u32 s30, s33, s30
	s_addc_u32 s31, s34, s31
	s_and_b64 s[42:43], s[2:3], exec
	s_cselect_b32 s43, s31, s41
	s_cselect_b32 s42, s30, s40
	s_add_u32 s56, s38, 0x10080
	s_addc_u32 s57, s39, 0
	s_mov_b32 m0, s24
	v_lshl_add_u64 v[64:65], s[56:57], 0, v[134:135]
	ds_read_b128 v[32:35], v145
	ds_read_b128 v[36:39], v145 offset:1024
	ds_read_b128 v[40:43], v145 offset:2048
	ds_read_b128 v[44:47], v145 offset:3072
	ds_read_b128 v[48:51], v145 offset:4096
	ds_read_b128 v[52:55], v145 offset:5120
	ds_read_b128 v[56:59], v145 offset:6144
	ds_read_b128 v[60:63], v145 offset:7168
	global_load_lds_dwordx4 v[64:65], off
	v_lshl_add_u64 v[64:65], s[56:57], 0, v[130:131]
	s_mov_b32 m0, s49
	s_nop 0
	global_load_lds_dwordx4 v[64:65], off
	s_waitcnt vmcnt(8)
	s_waitcnt lgkmcnt(0)
	s_barrier
	s_setprio 1
	s_waitcnt lgkmcnt(0)
	v_mfma_f32_16x16x32_bf16 v[64:67], v[0:3], v[32:35], 0
	v_mfma_f32_16x16x32_bf16 v[64:67], v[4:7], v[36:39], v[64:67]
	v_mfma_f32_16x16x32_bf16 v[68:71], v[8:11], v[32:35], 0
	v_mfma_f32_16x16x32_bf16 v[68:71], v[12:15], v[36:39], v[68:71]
	v_mfma_f32_16x16x32_bf16 v[72:75], v[0:3], v[40:43], 0
	v_mfma_f32_16x16x32_bf16 v[72:75], v[4:7], v[44:47], v[72:75]
	v_mfma_f32_16x16x32_bf16 v[76:79], v[8:11], v[40:43], 0
	v_mfma_f32_16x16x32_bf16 v[76:79], v[12:15], v[44:47], v[76:79]
	v_mfma_f32_16x16x32_bf16 v[80:83], v[0:3], v[48:51], 0
	v_mfma_f32_16x16x32_bf16 v[80:83], v[4:7], v[52:55], v[80:83]
	v_mfma_f32_16x16x32_bf16 v[84:87], v[8:11], v[48:51], 0
	v_mfma_f32_16x16x32_bf16 v[84:87], v[12:15], v[52:55], v[84:87]
	v_mfma_f32_16x16x32_bf16 v[88:91], v[0:3], v[56:59], 0
	v_mfma_f32_16x16x32_bf16 v[88:91], v[4:7], v[60:63], v[88:91]
	v_mfma_f32_16x16x32_bf16 v[92:95], v[8:11], v[56:59], 0
	v_mfma_f32_16x16x32_bf16 v[92:95], v[12:15], v[60:63], v[92:95]
	s_setprio 0
	s_setprio 1
	v_mfma_f32_16x16x32_bf16 v[96:99], v[16:19], v[32:35], 0
	v_mfma_f32_16x16x32_bf16 v[96:99], v[20:23], v[36:39], v[96:99]
	v_mfma_f32_16x16x32_bf16 v[32:35], v[24:27], v[32:35], 0
	v_mfma_f32_16x16x32_bf16 v[32:35], v[28:31], v[36:39], v[32:35]
	v_mfma_f32_16x16x32_bf16 v[36:39], v[16:19], v[40:43], 0
	v_mfma_f32_16x16x32_bf16 v[36:39], v[20:23], v[44:47], v[36:39]
	v_mfma_f32_16x16x32_bf16 v[40:43], v[24:27], v[40:43], 0
	v_mfma_f32_16x16x32_bf16 v[40:43], v[28:31], v[44:47], v[40:43]
	v_mfma_f32_16x16x32_bf16 v[44:47], v[16:19], v[48:51], 0
	v_mfma_f32_16x16x32_bf16 v[44:47], v[20:23], v[52:55], v[44:47]
	v_mfma_f32_16x16x32_bf16 v[48:51], v[24:27], v[48:51], 0
	v_mfma_f32_16x16x32_bf16 v[48:51], v[28:31], v[52:55], v[48:51]
	v_mfma_f32_16x16x32_bf16 v[52:55], v[16:19], v[56:59], 0
	v_mfma_f32_16x16x32_bf16 v[52:55], v[20:23], v[60:63], v[52:55]
	v_mfma_f32_16x16x32_bf16 v[56:59], v[24:27], v[56:59], 0
	v_mfma_f32_16x16x32_bf16 v[56:59], v[28:31], v[60:63], v[56:59]
	s_setprio 0
	s_barrier
	v_lshl_add_u64 v[210:211], s[40:41], 0, v[132:133]
	s_mov_b32 m0, s50
	v_lshl_add_u64 v[146:147], v[210:211], 0, s[14:15]
	v_lshl_add_u64 v[212:213], s[40:41], 0, v[128:129]
	s_add_u32 s56, s40, 0x10100
	ds_read_b128 v[60:63], v145 offset:16384
	ds_read_b128 v[100:103], v145 offset:17408
	ds_read_b128 v[104:107], v145 offset:18432
	ds_read_b128 v[108:111], v145 offset:19456
	ds_read_b128 v[112:115], v145 offset:20480
	ds_read_b128 v[116:119], v145 offset:21504
	ds_read_b128 v[120:123], v145 offset:22528
	ds_read_b128 v[124:127], v145 offset:23552
	global_load_lds_dwordx4 v[146:147], off
	v_lshl_add_u64 v[146:147], v[212:213], 0, s[14:15]
	s_mov_b32 m0, s51
	s_addc_u32 s57, s41, 0
	global_load_lds_dwordx4 v[146:147], off
	v_lshl_add_u64 v[146:147], s[56:57], 0, v[132:133]
	s_mov_b32 m0, s52
	v_lshl_add_u64 v[214:215], s[38:39], 0, v[134:135]
	global_load_lds_dwordx4 v[146:147], off
	v_lshl_add_u64 v[146:147], s[56:57], 0, v[128:129]
	s_mov_b32 m0, s53
	v_lshl_add_u64 v[216:217], s[38:39], 0, v[130:131]
	global_load_lds_dwordx4 v[146:147], off
	v_lshl_add_u64 v[146:147], v[214:215], 0, s[14:15]
	s_mov_b32 m0, s19
	s_nop 0
	global_load_lds_dwordx4 v[146:147], off
	v_lshl_add_u64 v[146:147], v[216:217], 0, s[14:15]
	s_mov_b32 m0, s36
	s_nop 0
	global_load_lds_dwordx4 v[146:147], off
	s_waitcnt vmcnt(8)
	s_waitcnt lgkmcnt(0)
	s_barrier
	s_setprio 1
	s_waitcnt lgkmcnt(0)
	v_mfma_f32_16x16x32_bf16 v[146:149], v[0:3], v[60:63], 0
	v_mfma_f32_16x16x32_bf16 v[146:149], v[4:7], v[100:103], v[146:149]
	v_mfma_f32_16x16x32_bf16 v[154:157], v[0:3], v[104:107], 0
	v_mfma_f32_16x16x32_bf16 v[154:157], v[4:7], v[108:111], v[154:157]
	v_mfma_f32_16x16x32_bf16 v[162:165], v[0:3], v[112:115], 0
	v_mfma_f32_16x16x32_bf16 v[162:165], v[4:7], v[116:119], v[162:165]
	v_mfma_f32_16x16x32_bf16 v[0:3], v[0:3], v[120:123], 0
	v_mfma_f32_16x16x32_bf16 v[0:3], v[4:7], v[124:127], v[0:3]
	v_mfma_f32_16x16x32_bf16 v[4:7], v[8:11], v[120:123], 0
	v_mfma_f32_16x16x32_bf16 v[4:7], v[12:15], v[124:127], v[4:7]
	v_mfma_f32_16x16x32_bf16 v[150:153], v[8:11], v[60:63], 0
	v_mfma_f32_16x16x32_bf16 v[150:153], v[12:15], v[100:103], v[150:153]
	v_mfma_f32_16x16x32_bf16 v[158:161], v[8:11], v[104:107], 0
	v_mfma_f32_16x16x32_bf16 v[158:161], v[12:15], v[108:111], v[158:161]
	v_mfma_f32_16x16x32_bf16 v[166:169], v[8:11], v[112:115], 0
	v_mfma_f32_16x16x32_bf16 v[166:169], v[12:15], v[116:119], v[166:169]
	s_setprio 0
	s_setprio 1
	v_mfma_f32_16x16x32_bf16 v[8:11], v[16:19], v[60:63], 0
	v_mfma_f32_16x16x32_bf16 v[8:11], v[20:23], v[100:103], v[8:11]
	v_mfma_f32_16x16x32_bf16 v[12:15], v[24:27], v[60:63], 0
	v_mfma_f32_16x16x32_bf16 v[12:15], v[28:31], v[100:103], v[12:15]
	v_mfma_f32_16x16x32_bf16 v[60:63], v[16:19], v[104:107], 0
	v_mfma_f32_16x16x32_bf16 v[60:63], v[20:23], v[108:111], v[60:63]
	v_mfma_f32_16x16x32_bf16 v[100:103], v[24:27], v[104:107], 0
	v_mfma_f32_16x16x32_bf16 v[100:103], v[28:31], v[108:111], v[100:103]
	v_mfma_f32_16x16x32_bf16 v[104:107], v[16:19], v[112:115], 0
	v_mfma_f32_16x16x32_bf16 v[104:107], v[20:23], v[116:119], v[104:107]
	v_mfma_f32_16x16x32_bf16 v[16:19], v[16:19], v[120:123], 0
	v_mfma_f32_16x16x32_bf16 v[16:19], v[20:23], v[124:127], v[16:19]
	v_mfma_f32_16x16x32_bf16 v[108:111], v[24:27], v[112:115], 0
	v_mfma_f32_16x16x32_bf16 v[108:111], v[28:31], v[116:119], v[108:111]
	v_mfma_f32_16x16x32_bf16 v[20:23], v[24:27], v[120:123], 0
	v_mfma_f32_16x16x32_bf16 v[20:23], v[28:31], v[124:127], v[20:23]
	s_setprio 0
	s_barrier
	s_add_i32 s55, 0, 0x18000
	s_add_i32 s23, 0, 0x1c000
	v_add_u32_e32 v220, s55, v141
	v_add_u32_e32 v222, s23, v141
	ds_read_b128 v[24:27], v220
	ds_read_b128 v[28:31], v220 offset:1024
	ds_read_b128 v[112:115], v220 offset:2048
	ds_read_b128 v[116:119], v220 offset:3072
	ds_read_b128 v[120:123], v222
	ds_read_b128 v[124:127], v222 offset:1024
	ds_read_b128 v[170:173], v222 offset:2048
	ds_read_b128 v[174:177], v222 offset:3072
	s_add_u32 s56, s38, 0x10100
	s_addc_u32 s57, s39, 0
	s_mov_b32 m0, s37
	v_lshl_add_u64 v[218:219], s[56:57], 0, v[134:135]
	ds_read_b128 v[178:181], v145 offset:32768
	ds_read_b128 v[182:185], v145 offset:33792
	ds_read_b128 v[186:189], v145 offset:34816
	ds_read_b128 v[190:193], v145 offset:35840
	ds_read_b128 v[194:197], v145 offset:36864
	ds_read_b128 v[198:201], v145 offset:37888
	ds_read_b128 v[202:205], v145 offset:38912
	ds_read_b128 v[206:209], v145 offset:39936
	global_load_lds_dwordx4 v[218:219], off
	v_lshl_add_u64 v[218:219], s[56:57], 0, v[130:131]
	s_mov_b32 m0, s46
	s_nop 0
	global_load_lds_dwordx4 v[218:219], off
	s_waitcnt vmcnt(8)
	s_waitcnt lgkmcnt(0)
	s_barrier
	s_setprio 1
	s_waitcnt lgkmcnt(0)
	v_mfma_f32_16x16x32_bf16 v[64:67], v[24:27], v[178:181], v[64:67]
	v_mfma_f32_16x16x32_bf16 v[64:67], v[28:31], v[182:185], v[64:67]
	v_mfma_f32_16x16x32_bf16 v[68:71], v[112:115], v[178:181], v[68:71]
	v_mfma_f32_16x16x32_bf16 v[68:71], v[116:119], v[182:185], v[68:71]
	v_mfma_f32_16x16x32_bf16 v[72:75], v[24:27], v[186:189], v[72:75]
	v_mfma_f32_16x16x32_bf16 v[72:75], v[28:31], v[190:193], v[72:75]
	v_mfma_f32_16x16x32_bf16 v[76:79], v[112:115], v[186:189], v[76:79]
	v_mfma_f32_16x16x32_bf16 v[76:79], v[116:119], v[190:193], v[76:79]
	v_mfma_f32_16x16x32_bf16 v[80:83], v[24:27], v[194:197], v[80:83]
	v_mfma_f32_16x16x32_bf16 v[80:83], v[28:31], v[198:201], v[80:83]
	v_mfma_f32_16x16x32_bf16 v[84:87], v[112:115], v[194:197], v[84:87]
	v_mfma_f32_16x16x32_bf16 v[84:87], v[116:119], v[198:201], v[84:87]
	v_mfma_f32_16x16x32_bf16 v[88:91], v[24:27], v[202:205], v[88:91]
	v_mfma_f32_16x16x32_bf16 v[88:91], v[28:31], v[206:209], v[88:91]
	v_mfma_f32_16x16x32_bf16 v[92:95], v[112:115], v[202:205], v[92:95]
	v_mfma_f32_16x16x32_bf16 v[92:95], v[116:119], v[206:209], v[92:95]
	s_setprio 0
	s_setprio 1
	v_mfma_f32_16x16x32_bf16 v[96:99], v[120:123], v[178:181], v[96:99]
	v_mfma_f32_16x16x32_bf16 v[96:99], v[124:127], v[182:185], v[96:99]
	v_mfma_f32_16x16x32_bf16 v[32:35], v[170:173], v[178:181], v[32:35]
	v_mfma_f32_16x16x32_bf16 v[32:35], v[174:177], v[182:185], v[32:35]
	v_mfma_f32_16x16x32_bf16 v[36:39], v[120:123], v[186:189], v[36:39]
	v_mfma_f32_16x16x32_bf16 v[36:39], v[124:127], v[190:193], v[36:39]
	v_mfma_f32_16x16x32_bf16 v[40:43], v[170:173], v[186:189], v[40:43]
	v_mfma_f32_16x16x32_bf16 v[40:43], v[174:177], v[190:193], v[40:43]
	v_mfma_f32_16x16x32_bf16 v[44:47], v[120:123], v[194:197], v[44:47]
	v_mfma_f32_16x16x32_bf16 v[44:47], v[124:127], v[198:201], v[44:47]
	v_mfma_f32_16x16x32_bf16 v[48:51], v[170:173], v[194:197], v[48:51]
	v_mfma_f32_16x16x32_bf16 v[48:51], v[174:177], v[198:201], v[48:51]
	v_mfma_f32_16x16x32_bf16 v[52:55], v[120:123], v[202:205], v[52:55]
	v_mfma_f32_16x16x32_bf16 v[52:55], v[124:127], v[206:209], v[52:55]
	v_mfma_f32_16x16x32_bf16 v[56:59], v[170:173], v[202:205], v[56:59]
	v_mfma_f32_16x16x32_bf16 v[56:59], v[174:177], v[206:209], v[56:59]
	s_setprio 0
	s_barrier
	s_add_i32 s55, s55, s0
	s_add_i32 s21, s55, 0x2000
	v_lshl_add_u64 v[210:211], v[210:211], 0, s[16:17]
	s_mov_b32 m0, s55
	s_add_u32 s40, s40, 0x10180
	ds_read_b128 v[178:181], v145 offset:49152
	ds_read_b128 v[182:185], v145 offset:50176
	ds_read_b128 v[186:189], v145 offset:51200
	ds_read_b128 v[190:193], v145 offset:52224
	ds_read_b128 v[194:197], v145 offset:53248
	ds_read_b128 v[198:201], v145 offset:54272
	ds_read_b128 v[202:205], v145 offset:55296
	ds_read_b128 v[206:209], v145 offset:56320
	global_load_lds_dwordx4 v[210:211], off
	v_lshl_add_u64 v[210:211], v[212:213], 0, s[16:17]
	s_mov_b32 m0, s21
	s_addc_u32 s41, s41, 0
	s_add_i32 s23, s23, s0
	global_load_lds_dwordx4 v[210:211], off
	v_lshl_add_u64 v[210:211], s[40:41], 0, v[132:133]
	s_mov_b32 m0, s23
	s_nop 0
	global_load_lds_dwordx4 v[210:211], off
	v_lshl_add_u64 v[210:211], s[40:41], 0, v[128:129]
	s_add_i32 s40, s23, 0x2000
	s_mov_b32 m0, s40
	s_nop 0
	global_load_lds_dwordx4 v[210:211], off
	v_lshl_add_u64 v[210:211], v[214:215], 0, s[16:17]
	s_mov_b32 m0, s47
	s_nop 0
	global_load_lds_dwordx4 v[210:211], off
	v_lshl_add_u64 v[210:211], v[216:217], 0, s[16:17]
	s_mov_b32 m0, s48
	s_nop 0
	global_load_lds_dwordx4 v[210:211], off
	s_waitcnt vmcnt(8)
	s_waitcnt lgkmcnt(0)
	s_barrier
	s_setprio 1
	s_waitcnt lgkmcnt(0)
	v_mfma_f32_16x16x32_bf16 v[0:3], v[24:27], v[202:205], v[0:3]
	v_mfma_f32_16x16x32_bf16 v[0:3], v[28:31], v[206:209], v[0:3]
	v_mfma_f32_16x16x32_bf16 v[4:7], v[112:115], v[202:205], v[4:7]
	v_mfma_f32_16x16x32_bf16 v[4:7], v[116:119], v[206:209], v[4:7]
	v_mfma_f32_16x16x32_bf16 v[146:149], v[24:27], v[178:181], v[146:149]
	v_mfma_f32_16x16x32_bf16 v[146:149], v[28:31], v[182:185], v[146:149]
	v_mfma_f32_16x16x32_bf16 v[150:153], v[112:115], v[178:181], v[150:153]
	v_mfma_f32_16x16x32_bf16 v[150:153], v[116:119], v[182:185], v[150:153]
	v_mfma_f32_16x16x32_bf16 v[154:157], v[24:27], v[186:189], v[154:157]
	v_mfma_f32_16x16x32_bf16 v[154:157], v[28:31], v[190:193], v[154:157]
	v_mfma_f32_16x16x32_bf16 v[158:161], v[112:115], v[186:189], v[158:161]
	v_mfma_f32_16x16x32_bf16 v[158:161], v[116:119], v[190:193], v[158:161]
	v_mfma_f32_16x16x32_bf16 v[162:165], v[24:27], v[194:197], v[162:165]
	v_mfma_f32_16x16x32_bf16 v[162:165], v[28:31], v[198:201], v[162:165]
	v_mfma_f32_16x16x32_bf16 v[166:169], v[112:115], v[194:197], v[166:169]
	v_mfma_f32_16x16x32_bf16 v[166:169], v[116:119], v[198:201], v[166:169]
	s_setprio 0
	s_setprio 1
	v_mfma_f32_16x16x32_bf16 v[8:11], v[120:123], v[178:181], v[8:11]
	v_mfma_f32_16x16x32_bf16 v[8:11], v[124:127], v[182:185], v[8:11]
	v_mfma_f32_16x16x32_bf16 v[12:15], v[170:173], v[178:181], v[12:15]
	v_mfma_f32_16x16x32_bf16 v[12:15], v[174:177], v[182:185], v[12:15]
	v_mfma_f32_16x16x32_bf16 v[24:27], v[120:123], v[186:189], v[60:63]
	v_mfma_f32_16x16x32_bf16 v[24:27], v[124:127], v[190:193], v[24:27]
	v_mfma_f32_16x16x32_bf16 v[28:31], v[170:173], v[186:189], v[100:103]
	v_mfma_f32_16x16x32_bf16 v[28:31], v[174:177], v[190:193], v[28:31]
	v_mfma_f32_16x16x32_bf16 v[60:63], v[120:123], v[194:197], v[104:107]
	v_mfma_f32_16x16x32_bf16 v[60:63], v[124:127], v[198:201], v[60:63]
	v_mfma_f32_16x16x32_bf16 v[100:103], v[170:173], v[194:197], v[108:111]
	v_mfma_f32_16x16x32_bf16 v[100:103], v[174:177], v[198:201], v[100:103]
	v_mfma_f32_16x16x32_bf16 v[16:19], v[120:123], v[202:205], v[16:19]
	v_mfma_f32_16x16x32_bf16 v[16:19], v[124:127], v[206:209], v[16:19]
	v_mfma_f32_16x16x32_bf16 v[20:23], v[170:173], v[202:205], v[20:23]
	v_mfma_f32_16x16x32_bf16 v[20:23], v[174:177], v[206:209], v[20:23]
	s_setprio 0
	s_barrier
	ds_read_b128 v[104:107], v143
	ds_read_b128 v[108:111], v143 offset:1024
	ds_read_b128 v[112:115], v143 offset:2048
	ds_read_b128 v[116:119], v143 offset:3072
	ds_read_b128 v[120:123], v144
	ds_read_b128 v[124:127], v144 offset:1024
	ds_read_b128 v[170:173], v144 offset:2048
	ds_read_b128 v[174:177], v144 offset:3072
	s_add_u32 s38, s38, 0x10180
	s_addc_u32 s39, s39, 0
	s_mov_b32 m0, s24
	v_lshl_add_u64 v[210:211], s[38:39], 0, v[134:135]
	ds_read_b128 v[178:181], v145
	ds_read_b128 v[182:185], v145 offset:1024
	ds_read_b128 v[186:189], v145 offset:2048
	ds_read_b128 v[190:193], v145 offset:3072
	ds_read_b128 v[194:197], v145 offset:4096
	ds_read_b128 v[198:201], v145 offset:5120
	ds_read_b128 v[202:205], v145 offset:6144
	ds_read_b128 v[206:209], v145 offset:7168
	global_load_lds_dwordx4 v[210:211], off
	v_lshl_add_u64 v[210:211], s[38:39], 0, v[130:131]
	s_mov_b32 m0, s49
	s_nop 0
	global_load_lds_dwordx4 v[210:211], off
	s_waitcnt vmcnt(8)
	s_waitcnt lgkmcnt(0)
	s_barrier
	s_setprio 1
	s_waitcnt lgkmcnt(0)
	v_mfma_f32_16x16x32_bf16 v[64:67], v[104:107], v[178:181], v[64:67]
	v_mfma_f32_16x16x32_bf16 v[64:67], v[108:111], v[182:185], v[64:67]
	v_mfma_f32_16x16x32_bf16 v[68:71], v[112:115], v[178:181], v[68:71]
	v_mfma_f32_16x16x32_bf16 v[68:71], v[116:119], v[182:185], v[68:71]
	v_mfma_f32_16x16x32_bf16 v[72:75], v[104:107], v[186:189], v[72:75]
	v_mfma_f32_16x16x32_bf16 v[72:75], v[108:111], v[190:193], v[72:75]
	v_mfma_f32_16x16x32_bf16 v[76:79], v[112:115], v[186:189], v[76:79]
	v_mfma_f32_16x16x32_bf16 v[76:79], v[116:119], v[190:193], v[76:79]
	v_mfma_f32_16x16x32_bf16 v[80:83], v[104:107], v[194:197], v[80:83]
	v_mfma_f32_16x16x32_bf16 v[80:83], v[108:111], v[198:201], v[80:83]
	v_mfma_f32_16x16x32_bf16 v[84:87], v[112:115], v[194:197], v[84:87]
	v_mfma_f32_16x16x32_bf16 v[84:87], v[116:119], v[198:201], v[84:87]
	v_mfma_f32_16x16x32_bf16 v[88:91], v[104:107], v[202:205], v[88:91]
	v_mfma_f32_16x16x32_bf16 v[88:91], v[108:111], v[206:209], v[88:91]
	v_mfma_f32_16x16x32_bf16 v[92:95], v[112:115], v[202:205], v[92:95]
	v_mfma_f32_16x16x32_bf16 v[92:95], v[116:119], v[206:209], v[92:95]
	s_setprio 0
	s_setprio 1
	v_mfma_f32_16x16x32_bf16 v[32:35], v[170:173], v[178:181], v[32:35]
	v_mfma_f32_16x16x32_bf16 v[96:99], v[120:123], v[178:181], v[96:99]
	v_mfma_f32_16x16x32_bf16 v[178:181], v[174:177], v[182:185], v[32:35]
	v_mfma_f32_16x16x32_bf16 v[32:35], v[120:123], v[186:189], v[36:39]
	v_mfma_f32_16x16x32_bf16 v[210:213], v[124:127], v[182:185], v[96:99]
	v_mfma_f32_16x16x32_bf16 v[182:185], v[124:127], v[190:193], v[32:35]
	v_mfma_f32_16x16x32_bf16 v[32:35], v[170:173], v[186:189], v[40:43]
	v_mfma_f32_16x16x32_bf16 v[40:43], v[174:177], v[190:193], v[32:35]
	v_mfma_f32_16x16x32_bf16 v[32:35], v[120:123], v[194:197], v[44:47]
	v_mfma_f32_16x16x32_bf16 v[44:47], v[124:127], v[198:201], v[32:35]
	v_mfma_f32_16x16x32_bf16 v[32:35], v[170:173], v[194:197], v[48:51]
	v_mfma_f32_16x16x32_bf16 v[48:51], v[174:177], v[198:201], v[32:35]
	v_mfma_f32_16x16x32_bf16 v[32:35], v[120:123], v[202:205], v[52:55]
	v_mfma_f32_16x16x32_bf16 v[52:55], v[124:127], v[206:209], v[32:35]
	v_mfma_f32_16x16x32_bf16 v[32:35], v[170:173], v[202:205], v[56:59]
	v_mfma_f32_16x16x32_bf16 v[56:59], v[174:177], v[206:209], v[32:35]
	s_setprio 0
	s_barrier
	s_mov_b32 m0, s50
	v_lshl_add_u64 v[246:247], s[42:43], 0, v[132:133]
	s_add_u32 s38, s42, 0x10000
	s_nop 1
	ds_read_b128 v[32:35], v145 offset:16384
	ds_read_b128 v[36:39], v145 offset:17408
	ds_read_b128 v[96:99], v145 offset:18432
	ds_read_b128 v[186:189], v145 offset:19456
	ds_read_b128 v[190:193], v145 offset:20480
	ds_read_b128 v[194:197], v145 offset:21504
	ds_read_b128 v[198:201], v145 offset:22528
	ds_read_b128 v[202:205], v145 offset:23552
	global_load_lds_dwordx4 v[246:247], off
	v_lshl_add_u64 v[248:249], s[42:43], 0, v[128:129]
	s_mov_b32 m0, s51
	s_addc_u32 s39, s43, 0
	global_load_lds_dwordx4 v[248:249], off
	v_lshl_add_u64 v[206:207], s[38:39], 0, v[132:133]
	s_mov_b32 m0, s52
	v_lshl_add_u64 v[250:251], s[44:45], 0, v[134:135]
	global_load_lds_dwordx4 v[206:207], off
	v_lshl_add_u64 v[206:207], s[38:39], 0, v[128:129]
	s_mov_b32 m0, s53
	v_lshl_add_u64 v[252:253], s[44:45], 0, v[130:131]
	global_load_lds_dwordx4 v[206:207], off
	s_mov_b32 m0, s19
	s_nop 0
	global_load_lds_dwordx4 v[250:251], off
	s_mov_b32 m0, s36
	s_nop 0
	global_load_lds_dwordx4 v[252:253], off
	s_waitcnt vmcnt(8)
	s_waitcnt lgkmcnt(0)
	s_barrier
	s_setprio 1
	s_waitcnt lgkmcnt(0)
	v_mfma_f32_16x16x32_bf16 v[0:3], v[104:107], v[198:201], v[0:3]
	v_mfma_f32_16x16x32_bf16 v[0:3], v[108:111], v[202:205], v[0:3]
	v_mfma_f32_16x16x32_bf16 v[4:7], v[112:115], v[198:201], v[4:7]
	v_mfma_f32_16x16x32_bf16 v[4:7], v[116:119], v[202:205], v[4:7]
	v_mfma_f32_16x16x32_bf16 v[146:149], v[104:107], v[32:35], v[146:149]
	v_mfma_f32_16x16x32_bf16 v[146:149], v[108:111], v[36:39], v[146:149]
	v_mfma_f32_16x16x32_bf16 v[150:153], v[112:115], v[32:35], v[150:153]
	v_mfma_f32_16x16x32_bf16 v[150:153], v[116:119], v[36:39], v[150:153]
	v_mfma_f32_16x16x32_bf16 v[154:157], v[104:107], v[96:99], v[154:157]
	v_mfma_f32_16x16x32_bf16 v[154:157], v[108:111], v[186:189], v[154:157]
	v_mfma_f32_16x16x32_bf16 v[158:161], v[112:115], v[96:99], v[158:161]
	v_mfma_f32_16x16x32_bf16 v[158:161], v[116:119], v[186:189], v[158:161]
	v_mfma_f32_16x16x32_bf16 v[162:165], v[104:107], v[190:193], v[162:165]
	v_mfma_f32_16x16x32_bf16 v[162:165], v[108:111], v[194:197], v[162:165]
	v_mfma_f32_16x16x32_bf16 v[166:169], v[112:115], v[190:193], v[166:169]
	v_mfma_f32_16x16x32_bf16 v[166:169], v[116:119], v[194:197], v[166:169]
	s_setprio 0
	s_setprio 1
	v_mfma_f32_16x16x32_bf16 v[8:11], v[120:123], v[32:35], v[8:11]
	v_mfma_f32_16x16x32_bf16 v[12:15], v[170:173], v[32:35], v[12:15]
	v_mfma_f32_16x16x32_bf16 v[24:27], v[120:123], v[96:99], v[24:27]
	v_mfma_f32_16x16x32_bf16 v[28:31], v[170:173], v[96:99], v[28:31]
	v_mfma_f32_16x16x32_bf16 v[32:35], v[120:123], v[190:193], v[60:63]
	v_mfma_f32_16x16x32_bf16 v[24:27], v[124:127], v[186:189], v[24:27]
	v_mfma_f32_16x16x32_bf16 v[28:31], v[174:177], v[186:189], v[28:31]
	v_mfma_f32_16x16x32_bf16 v[186:189], v[124:127], v[194:197], v[32:35]
	v_mfma_f32_16x16x32_bf16 v[32:35], v[170:173], v[190:193], v[100:103]
	v_mfma_f32_16x16x32_bf16 v[16:19], v[120:123], v[198:201], v[16:19]
	v_mfma_f32_16x16x32_bf16 v[8:11], v[124:127], v[36:39], v[8:11]
	v_mfma_f32_16x16x32_bf16 v[12:15], v[174:177], v[36:39], v[12:15]
	v_mfma_f32_16x16x32_bf16 v[190:193], v[174:177], v[194:197], v[32:35]
	v_mfma_f32_16x16x32_bf16 v[194:197], v[124:127], v[202:205], v[16:19]
	v_mfma_f32_16x16x32_bf16 v[16:19], v[170:173], v[198:201], v[20:23]
	v_mfma_f32_16x16x32_bf16 v[170:173], v[174:177], v[202:205], v[16:19]
	s_setprio 0
	s_barrier
	ds_read_b128 v[60:63], v220
	ds_read_b128 v[174:177], v220 offset:1024
	ds_read_b128 v[198:201], v220 offset:2048
	ds_read_b128 v[202:205], v220 offset:3072
	ds_read_b128 v[206:209], v222
	ds_read_b128 v[214:217], v222 offset:1024
	ds_read_b128 v[218:221], v222 offset:2048
	ds_read_b128 v[222:225], v222 offset:3072
	s_add_u32 s38, s44, 0x10000
	s_addc_u32 s39, s45, 0
	s_mov_b32 m0, s37
	v_lshl_add_u64 v[32:33], s[38:39], 0, v[134:135]
	ds_read_b128 v[16:19], v145 offset:32768
	ds_read_b128 v[20:23], v145 offset:33792
	ds_read_b128 v[108:111], v145 offset:34816
	ds_read_b128 v[226:229], v145 offset:35840
	ds_read_b128 v[230:233], v145 offset:36864
	ds_read_b128 v[234:237], v145 offset:37888
	ds_read_b128 v[238:241], v145 offset:38912
	ds_read_b128 v[242:245], v145 offset:39936
	global_load_lds_dwordx4 v[32:33], off
	v_lshl_add_u64 v[32:33], s[38:39], 0, v[130:131]
	s_mov_b32 m0, s46
	s_nop 0
	global_load_lds_dwordx4 v[32:33], off
	s_waitcnt vmcnt(8)
	s_waitcnt lgkmcnt(0)
	s_barrier
	s_setprio 1
	s_waitcnt lgkmcnt(0)
	v_mfma_f32_16x16x32_bf16 v[32:35], v[60:63], v[16:19], v[64:67]
	v_mfma_f32_16x16x32_bf16 v[112:115], v[174:177], v[20:23], v[32:35]
	v_mfma_f32_16x16x32_bf16 v[32:35], v[198:201], v[16:19], v[68:71]
	v_mfma_f32_16x16x32_bf16 v[116:119], v[202:205], v[20:23], v[32:35]
	v_mfma_f32_16x16x32_bf16 v[32:35], v[60:63], v[108:111], v[72:75]
	v_mfma_f32_16x16x32_bf16 v[96:99], v[174:177], v[226:229], v[32:35]
	v_mfma_f32_16x16x32_bf16 v[32:35], v[198:201], v[108:111], v[76:79]
	v_mfma_f32_16x16x32_bf16 v[100:103], v[202:205], v[226:229], v[32:35]
	v_mfma_f32_16x16x32_bf16 v[32:35], v[60:63], v[230:233], v[80:83]
	v_mfma_f32_16x16x32_bf16 v[64:67], v[174:177], v[234:237], v[32:35]
	v_mfma_f32_16x16x32_bf16 v[32:35], v[198:201], v[230:233], v[84:87]
	v_mfma_f32_16x16x32_bf16 v[68:71], v[202:205], v[234:237], v[32:35]
	v_mfma_f32_16x16x32_bf16 v[32:35], v[60:63], v[238:241], v[88:91]
	v_mfma_f32_16x16x32_bf16 v[36:39], v[198:201], v[238:241], v[92:95]
	v_mfma_f32_16x16x32_bf16 v[32:35], v[174:177], v[242:245], v[32:35]
	v_mfma_f32_16x16x32_bf16 v[36:39], v[202:205], v[242:245], v[36:39]
	s_setprio 0
	s_setprio 1
	v_mfma_f32_16x16x32_bf16 v[72:75], v[206:209], v[16:19], v[210:213]
	v_mfma_f32_16x16x32_bf16 v[16:19], v[218:221], v[16:19], v[178:181]
	v_mfma_f32_16x16x32_bf16 v[124:127], v[222:225], v[20:23], v[16:19]
	v_mfma_f32_16x16x32_bf16 v[16:19], v[206:209], v[108:111], v[182:185]
	v_mfma_f32_16x16x32_bf16 v[104:107], v[214:217], v[226:229], v[16:19]
	v_mfma_f32_16x16x32_bf16 v[16:19], v[218:221], v[108:111], v[40:43]
	v_mfma_f32_16x16x32_bf16 v[108:111], v[222:225], v[226:229], v[16:19]
	v_mfma_f32_16x16x32_bf16 v[16:19], v[206:209], v[230:233], v[44:47]
	v_mfma_f32_16x16x32_bf16 v[120:123], v[214:217], v[20:23], v[72:75]
	v_mfma_f32_16x16x32_bf16 v[72:75], v[214:217], v[234:237], v[16:19]
	v_mfma_f32_16x16x32_bf16 v[16:19], v[218:221], v[230:233], v[48:51]
	v_mfma_f32_16x16x32_bf16 v[76:79], v[222:225], v[234:237], v[16:19]
	v_mfma_f32_16x16x32_bf16 v[16:19], v[206:209], v[238:241], v[52:55]
	v_mfma_f32_16x16x32_bf16 v[40:43], v[214:217], v[242:245], v[16:19]
	v_mfma_f32_16x16x32_bf16 v[16:19], v[218:221], v[238:241], v[56:59]
	v_mfma_f32_16x16x32_bf16 v[44:47], v[222:225], v[242:245], v[16:19]
	s_setprio 0
	s_barrier
	s_mov_b32 m0, s55
	s_nop 3
	v_lshl_add_u64 v[16:17], v[246:247], 0, s[8:9]
	s_add_u32 s38, s42, 0x10080
	ds_read_b128 v[56:59], v145 offset:49152
	ds_read_b128 v[92:95], v145 offset:50176
	ds_read_b128 v[178:181], v145 offset:51200
	ds_read_b128 v[182:185], v145 offset:52224
	ds_read_b128 v[210:213], v145 offset:53248
	ds_read_b128 v[226:229], v145 offset:54272
	ds_read_b128 v[230:233], v145 offset:55296
	ds_read_b128 v[234:237], v145 offset:56320
	global_load_lds_dwordx4 v[16:17], off
	v_lshl_add_u64 v[16:17], v[248:249], 0, s[8:9]
	s_mov_b32 m0, s21
	s_addc_u32 s39, s43, 0
	global_load_lds_dwordx4 v[16:17], off
	v_lshl_add_u64 v[16:17], s[38:39], 0, v[132:133]
	s_mov_b32 m0, s23
	s_nop 0
	global_load_lds_dwordx4 v[16:17], off
	v_lshl_add_u64 v[16:17], s[38:39], 0, v[128:129]
	s_mov_b32 m0, s40
	s_nop 0
	global_load_lds_dwordx4 v[16:17], off
	v_lshl_add_u64 v[16:17], v[250:251], 0, s[8:9]
	s_mov_b32 m0, s47
	s_nop 0
	global_load_lds_dwordx4 v[16:17], off
	v_lshl_add_u64 v[16:17], v[252:253], 0, s[8:9]
	s_mov_b32 m0, s48
	s_nop 0
	global_load_lds_dwordx4 v[16:17], off
	s_waitcnt vmcnt(8)
	s_waitcnt lgkmcnt(0)
	s_barrier
	s_setprio 1
	s_waitcnt lgkmcnt(0)
	v_mfma_f32_16x16x32_bf16 v[16:19], v[60:63], v[56:59], v[146:149]
	v_mfma_f32_16x16x32_bf16 v[80:83], v[174:177], v[92:95], v[16:19]
	v_mfma_f32_16x16x32_bf16 v[16:19], v[198:201], v[56:59], v[150:153]
	v_mfma_f32_16x16x32_bf16 v[84:87], v[202:205], v[92:95], v[16:19]
	v_mfma_f32_16x16x32_bf16 v[16:19], v[60:63], v[178:181], v[154:157]
	v_mfma_f32_16x16x32_bf16 v[48:51], v[174:177], v[182:185], v[16:19]
	v_mfma_f32_16x16x32_bf16 v[16:19], v[198:201], v[178:181], v[158:161]
	v_mfma_f32_16x16x32_bf16 v[52:55], v[202:205], v[182:185], v[16:19]
	v_mfma_f32_16x16x32_bf16 v[16:19], v[60:63], v[210:213], v[162:165]
	v_mfma_f32_16x16x32_bf16 v[20:23], v[198:201], v[210:213], v[166:169]
	v_mfma_f32_16x16x32_bf16 v[0:3], v[60:63], v[230:233], v[0:3]
	v_mfma_f32_16x16x32_bf16 v[4:7], v[198:201], v[230:233], v[4:7]
	v_mfma_f32_16x16x32_bf16 v[16:19], v[174:177], v[226:229], v[16:19]
	v_mfma_f32_16x16x32_bf16 v[20:23], v[202:205], v[226:229], v[20:23]
	v_mfma_f32_16x16x32_bf16 v[0:3], v[174:177], v[234:237], v[0:3]
	v_mfma_f32_16x16x32_bf16 v[4:7], v[202:205], v[234:237], v[4:7]
	s_setprio 0
	s_setprio 1
	v_mfma_f32_16x16x32_bf16 v[8:11], v[206:209], v[56:59], v[8:11]
	v_mfma_f32_16x16x32_bf16 v[88:91], v[214:217], v[92:95], v[8:11]
	v_mfma_f32_16x16x32_bf16 v[8:11], v[218:221], v[56:59], v[12:15]
	v_mfma_f32_16x16x32_bf16 v[92:95], v[222:225], v[92:95], v[8:11]
	v_mfma_f32_16x16x32_bf16 v[8:11], v[206:209], v[178:181], v[24:27]
	v_mfma_f32_16x16x32_bf16 v[56:59], v[214:217], v[182:185], v[8:11]
	v_mfma_f32_16x16x32_bf16 v[8:11], v[218:221], v[178:181], v[28:31]
	v_mfma_f32_16x16x32_bf16 v[60:63], v[222:225], v[182:185], v[8:11]
	v_mfma_f32_16x16x32_bf16 v[8:11], v[206:209], v[210:213], v[186:189]
	v_mfma_f32_16x16x32_bf16 v[24:27], v[214:217], v[226:229], v[8:11]
	v_mfma_f32_16x16x32_bf16 v[8:11], v[218:221], v[210:213], v[190:193]
	v_mfma_f32_16x16x32_bf16 v[28:31], v[222:225], v[226:229], v[8:11]
	v_mfma_f32_16x16x32_bf16 v[8:11], v[206:209], v[230:233], v[194:197]
	v_mfma_f32_16x16x32_bf16 v[12:15], v[218:221], v[230:233], v[170:173]
	v_mfma_f32_16x16x32_bf16 v[8:11], v[214:217], v[234:237], v[8:11]
	v_mfma_f32_16x16x32_bf16 v[12:15], v[222:225], v[234:237], v[12:15]
	s_setprio 0
	s_barrier
	s_andn2_b64 vcc, exec, s[10:11]
	s_cbranch_vccnz .LBB0_944
	s_barrier

.LBB0_1014:
	ds_read_b128 v[144:147], v155
	ds_read_b128 v[148:151], v155 offset:1024
	ds_read_b128 v[160:163], v155 offset:2048
	ds_read_b128 v[164:167], v155 offset:3072
	ds_read_b128 v[168:171], v156
	ds_read_b128 v[172:175], v156 offset:1024
	ds_read_b128 v[176:179], v156 offset:2048
	ds_read_b128 v[180:183], v156 offset:3072
	s_add_u32 s28, s20, 0xfffc0080
	s_addc_u32 s29, s21, -1
	s_cmp_eq_u32 s53, 12
	s_cselect_b32 s31, s19, s29
	s_cselect_b32 s30, s49, s28
	s_cselect_b32 s29, s17, s52
	s_cselect_b32 s28, s50, s51
	v_lshl_add_u64 v[216:217], s[20:21], 0, v[136:137]
	s_add_i32 m0, s27, 0xc000
	ds_read_b128 v[184:187], v157
	ds_read_b128 v[188:191], v157 offset:1024
	ds_read_b128 v[192:195], v157 offset:2048
	ds_read_b128 v[196:199], v157 offset:3072
	ds_read_b128 v[200:203], v157 offset:4096
	ds_read_b128 v[204:207], v157 offset:5120
	ds_read_b128 v[208:211], v157 offset:6144
	ds_read_b128 v[212:215], v157 offset:7168
	global_load_lds_dwordx4 v[216:217], off
	v_lshl_add_u64 v[216:217], s[20:21], 0, v[138:139]
	s_add_i32 m0, s27, 0xe000
	s_nop 0
	global_load_lds_dwordx4 v[216:217], off
	s_waitcnt vmcnt(8)
	s_waitcnt lgkmcnt(0)
	s_barrier
	s_setprio 1
	s_waitcnt lgkmcnt(0)
	v_mfma_f32_16x16x32_bf16 v[124:127], v[144:147], v[184:187], v[124:127]
	v_mfma_f32_16x16x32_bf16 v[124:127], v[148:151], v[188:191], v[124:127]
	v_mfma_f32_16x16x32_bf16 v[120:123], v[160:163], v[184:187], v[120:123]
	v_mfma_f32_16x16x32_bf16 v[120:123], v[164:167], v[188:191], v[120:123]
	v_mfma_f32_16x16x32_bf16 v[108:111], v[144:147], v[192:195], v[108:111]
	v_mfma_f32_16x16x32_bf16 v[108:111], v[148:151], v[196:199], v[108:111]
	v_mfma_f32_16x16x32_bf16 v[104:107], v[160:163], v[192:195], v[104:107]
	v_mfma_f32_16x16x32_bf16 v[104:107], v[164:167], v[196:199], v[104:107]
	v_mfma_f32_16x16x32_bf16 v[92:95], v[144:147], v[200:203], v[92:95]
	v_mfma_f32_16x16x32_bf16 v[92:95], v[148:151], v[204:207], v[92:95]
	v_mfma_f32_16x16x32_bf16 v[88:91], v[160:163], v[200:203], v[88:91]
	v_mfma_f32_16x16x32_bf16 v[88:91], v[164:167], v[204:207], v[88:91]
	v_mfma_f32_16x16x32_bf16 v[76:79], v[144:147], v[208:211], v[76:79]
	v_mfma_f32_16x16x32_bf16 v[76:79], v[148:151], v[212:215], v[76:79]
	v_mfma_f32_16x16x32_bf16 v[72:75], v[160:163], v[208:211], v[72:75]
	v_mfma_f32_16x16x32_bf16 v[72:75], v[164:167], v[212:215], v[72:75]
	s_setprio 0
	s_setprio 1
	v_mfma_f32_16x16x32_bf16 v[116:119], v[168:171], v[184:187], v[116:119]
	v_mfma_f32_16x16x32_bf16 v[116:119], v[172:175], v[188:191], v[116:119]
	v_mfma_f32_16x16x32_bf16 v[112:115], v[176:179], v[184:187], v[112:115]
	v_mfma_f32_16x16x32_bf16 v[112:115], v[180:183], v[188:191], v[112:115]
	v_mfma_f32_16x16x32_bf16 v[100:103], v[168:171], v[192:195], v[100:103]
	v_mfma_f32_16x16x32_bf16 v[100:103], v[172:175], v[196:199], v[100:103]
	v_mfma_f32_16x16x32_bf16 v[96:99], v[176:179], v[192:195], v[96:99]
	v_mfma_f32_16x16x32_bf16 v[96:99], v[180:183], v[196:199], v[96:99]
	v_mfma_f32_16x16x32_bf16 v[84:87], v[168:171], v[200:203], v[84:87]
	v_mfma_f32_16x16x32_bf16 v[84:87], v[172:175], v[204:207], v[84:87]
	v_mfma_f32_16x16x32_bf16 v[80:83], v[176:179], v[200:203], v[80:83]
	v_mfma_f32_16x16x32_bf16 v[80:83], v[180:183], v[204:207], v[80:83]
	v_mfma_f32_16x16x32_bf16 v[68:71], v[168:171], v[208:211], v[68:71]
	v_mfma_f32_16x16x32_bf16 v[68:71], v[172:175], v[212:215], v[68:71]
	v_mfma_f32_16x16x32_bf16 v[64:67], v[176:179], v[208:211], v[64:67]
	v_mfma_f32_16x16x32_bf16 v[64:67], v[180:183], v[212:215], v[64:67]
	s_setprio 0
	s_barrier
	s_add_i32 s54, s45, s35
	v_lshl_add_u64 v[216:217], s[28:29], 0, v[132:133]
	s_mov_b32 m0, s54
	ds_read_b128 v[184:187], v157 offset:16384
	ds_read_b128 v[188:191], v157 offset:17408
	ds_read_b128 v[192:195], v157 offset:18432
	ds_read_b128 v[196:199], v157 offset:19456
	ds_read_b128 v[200:203], v157 offset:20480
	ds_read_b128 v[204:207], v157 offset:21504
	ds_read_b128 v[208:211], v157 offset:22528
	ds_read_b128 v[212:215], v157 offset:23552
	global_load_lds_dwordx4 v[216:217], off
	s_add_i32 m0, s54, 0x2000
	s_add_u32 s54, s28, 0x40000
	v_lshl_add_u64 v[218:219], s[28:29], 0, v[128:129]
	s_addc_u32 s55, s29, 0
	s_add_i32 s56, s46, s35
	global_load_lds_dwordx4 v[218:219], off
	v_lshl_add_u64 v[220:221], s[54:55], 0, v[132:133]
	s_mov_b32 m0, s56
	v_lshl_add_u64 v[222:223], s[30:31], 0, v[130:131]
	global_load_lds_dwordx4 v[220:221], off
	v_lshl_add_u64 v[220:221], s[54:55], 0, v[128:129]
	s_add_i32 m0, s56, 0x2000
	s_nop 0
	global_load_lds_dwordx4 v[220:221], off
	v_lshl_add_u64 v[220:221], s[30:31], 0, v[134:135]
	s_mov_b32 m0, s27
	s_nop 0
	global_load_lds_dwordx4 v[220:221], off
	s_mov_b32 m0, s38
	s_nop 0
	global_load_lds_dwordx4 v[222:223], off
	s_waitcnt vmcnt(8)
	s_waitcnt lgkmcnt(0)
	s_barrier
	s_setprio 1
	s_waitcnt lgkmcnt(0)
	v_mfma_f32_16x16x32_bf16 v[60:63], v[144:147], v[184:187], v[60:63]
	v_mfma_f32_16x16x32_bf16 v[60:63], v[148:151], v[188:191], v[60:63]
	v_mfma_f32_16x16x32_bf16 v[56:59], v[160:163], v[184:187], v[56:59]
	v_mfma_f32_16x16x32_bf16 v[56:59], v[164:167], v[188:191], v[56:59]
	v_mfma_f32_16x16x32_bf16 v[44:47], v[144:147], v[192:195], v[44:47]
	v_mfma_f32_16x16x32_bf16 v[44:47], v[148:151], v[196:199], v[44:47]
	v_mfma_f32_16x16x32_bf16 v[40:43], v[160:163], v[192:195], v[40:43]
	v_mfma_f32_16x16x32_bf16 v[40:43], v[164:167], v[196:199], v[40:43]
	v_mfma_f32_16x16x32_bf16 v[28:31], v[144:147], v[200:203], v[28:31]
	v_mfma_f32_16x16x32_bf16 v[28:31], v[148:151], v[204:207], v[28:31]
	v_mfma_f32_16x16x32_bf16 v[24:27], v[160:163], v[200:203], v[24:27]
	v_mfma_f32_16x16x32_bf16 v[24:27], v[164:167], v[204:207], v[24:27]
	v_mfma_f32_16x16x32_bf16 v[12:15], v[144:147], v[208:211], v[12:15]
	v_mfma_f32_16x16x32_bf16 v[12:15], v[148:151], v[212:215], v[12:15]
	v_mfma_f32_16x16x32_bf16 v[8:11], v[160:163], v[208:211], v[8:11]
	v_mfma_f32_16x16x32_bf16 v[8:11], v[164:167], v[212:215], v[8:11]
	s_setprio 0
	s_setprio 1
	v_mfma_f32_16x16x32_bf16 v[52:55], v[168:171], v[184:187], v[52:55]
	v_mfma_f32_16x16x32_bf16 v[52:55], v[172:175], v[188:191], v[52:55]
	v_mfma_f32_16x16x32_bf16 v[48:51], v[176:179], v[184:187], v[48:51]
	v_mfma_f32_16x16x32_bf16 v[48:51], v[180:183], v[188:191], v[48:51]
	v_mfma_f32_16x16x32_bf16 v[36:39], v[168:171], v[192:195], v[36:39]
	v_mfma_f32_16x16x32_bf16 v[36:39], v[172:175], v[196:199], v[36:39]
	v_mfma_f32_16x16x32_bf16 v[32:35], v[176:179], v[192:195], v[32:35]
	v_mfma_f32_16x16x32_bf16 v[32:35], v[180:183], v[196:199], v[32:35]
	v_mfma_f32_16x16x32_bf16 v[20:23], v[168:171], v[200:203], v[20:23]
	v_mfma_f32_16x16x32_bf16 v[20:23], v[172:175], v[204:207], v[20:23]
	v_mfma_f32_16x16x32_bf16 v[16:19], v[176:179], v[200:203], v[16:19]
	v_mfma_f32_16x16x32_bf16 v[16:19], v[180:183], v[204:207], v[16:19]
	v_mfma_f32_16x16x32_bf16 v[4:7], v[168:171], v[208:211], v[4:7]
	v_mfma_f32_16x16x32_bf16 v[4:7], v[172:175], v[212:215], v[4:7]
	v_mfma_f32_16x16x32_bf16 v[0:3], v[176:179], v[208:211], v[0:3]
	v_mfma_f32_16x16x32_bf16 v[0:3], v[180:183], v[212:215], v[0:3]
	s_setprio 0
	s_barrier
	s_add_i32 s54, 0, 0x18000
	v_add_u32_e32 v159, s54, v153
	s_add_i32 s55, 0, 0x1c000
	ds_read_b128 v[144:147], v159
	ds_read_b128 v[148:151], v159 offset:1024
	ds_read_b128 v[160:163], v159 offset:2048
	ds_read_b128 v[164:167], v159 offset:3072
	v_add_u32_e32 v159, s55, v153
	ds_read_b128 v[168:171], v159
	ds_read_b128 v[172:175], v159 offset:1024
	ds_read_b128 v[176:179], v159 offset:2048
	ds_read_b128 v[180:183], v159 offset:3072
	s_add_u32 s30, s30, 0x40000
	s_addc_u32 s31, s31, 0
	s_mov_b32 m0, s39
	v_lshl_add_u64 v[224:225], s[30:31], 0, v[134:135]
	ds_read_b128 v[184:187], v157 offset:32768
	ds_read_b128 v[188:191], v157 offset:33792
	ds_read_b128 v[192:195], v157 offset:34816
	ds_read_b128 v[196:199], v157 offset:35840
	ds_read_b128 v[200:203], v157 offset:36864
	ds_read_b128 v[204:207], v157 offset:37888
	ds_read_b128 v[208:211], v157 offset:38912
	ds_read_b128 v[212:215], v157 offset:39936
	global_load_lds_dwordx4 v[224:225], off
	v_lshl_add_u64 v[224:225], s[30:31], 0, v[130:131]
	s_mov_b32 m0, s40
	s_nop 0
	global_load_lds_dwordx4 v[224:225], off
	s_waitcnt vmcnt(8)
	s_waitcnt lgkmcnt(0)
	s_barrier
	s_setprio 1
	s_waitcnt lgkmcnt(0)
	v_mfma_f32_16x16x32_bf16 v[124:127], v[144:147], v[184:187], v[124:127]
	v_mfma_f32_16x16x32_bf16 v[124:127], v[148:151], v[188:191], v[124:127]
	v_mfma_f32_16x16x32_bf16 v[120:123], v[160:163], v[184:187], v[120:123]
	v_mfma_f32_16x16x32_bf16 v[120:123], v[164:167], v[188:191], v[120:123]
	v_mfma_f32_16x16x32_bf16 v[108:111], v[144:147], v[192:195], v[108:111]
	v_mfma_f32_16x16x32_bf16 v[108:111], v[148:151], v[196:199], v[108:111]
	v_mfma_f32_16x16x32_bf16 v[104:107], v[160:163], v[192:195], v[104:107]
	v_mfma_f32_16x16x32_bf16 v[104:107], v[164:167], v[196:199], v[104:107]
	v_mfma_f32_16x16x32_bf16 v[92:95], v[144:147], v[200:203], v[92:95]
	v_mfma_f32_16x16x32_bf16 v[92:95], v[148:151], v[204:207], v[92:95]
	v_mfma_f32_16x16x32_bf16 v[88:91], v[160:163], v[200:203], v[88:91]
	v_mfma_f32_16x16x32_bf16 v[88:91], v[164:167], v[204:207], v[88:91]
	v_mfma_f32_16x16x32_bf16 v[76:79], v[144:147], v[208:211], v[76:79]
	v_mfma_f32_16x16x32_bf16 v[76:79], v[148:151], v[212:215], v[76:79]
	v_mfma_f32_16x16x32_bf16 v[72:75], v[160:163], v[208:211], v[72:75]
	v_mfma_f32_16x16x32_bf16 v[72:75], v[164:167], v[212:215], v[72:75]
	s_setprio 0
	s_setprio 1
	v_mfma_f32_16x16x32_bf16 v[116:119], v[168:171], v[184:187], v[116:119]
	v_mfma_f32_16x16x32_bf16 v[116:119], v[172:175], v[188:191], v[116:119]
	v_mfma_f32_16x16x32_bf16 v[112:115], v[176:179], v[184:187], v[112:115]
	v_mfma_f32_16x16x32_bf16 v[112:115], v[180:183], v[188:191], v[112:115]
	v_mfma_f32_16x16x32_bf16 v[100:103], v[168:171], v[192:195], v[100:103]
	v_mfma_f32_16x16x32_bf16 v[100:103], v[172:175], v[196:199], v[100:103]
	v_mfma_f32_16x16x32_bf16 v[96:99], v[176:179], v[192:195], v[96:99]
	v_mfma_f32_16x16x32_bf16 v[96:99], v[180:183], v[196:199], v[96:99]
	v_mfma_f32_16x16x32_bf16 v[84:87], v[168:171], v[200:203], v[84:87]
	v_mfma_f32_16x16x32_bf16 v[84:87], v[172:175], v[204:207], v[84:87]
	v_mfma_f32_16x16x32_bf16 v[80:83], v[176:179], v[200:203], v[80:83]
	v_mfma_f32_16x16x32_bf16 v[80:83], v[180:183], v[204:207], v[80:83]
	v_mfma_f32_16x16x32_bf16 v[68:71], v[168:171], v[208:211], v[68:71]
	v_mfma_f32_16x16x32_bf16 v[68:71], v[172:175], v[212:215], v[68:71]
	v_mfma_f32_16x16x32_bf16 v[64:67], v[176:179], v[208:211], v[64:67]
	v_mfma_f32_16x16x32_bf16 v[64:67], v[180:183], v[212:215], v[64:67]
	s_setprio 0
	s_barrier
	s_add_i32 s30, s54, s35
	v_lshl_add_u64 v[216:217], v[216:217], 0, s[10:11]
	s_mov_b32 m0, s30
	ds_read_b128 v[184:187], v157 offset:49152
	ds_read_b128 v[188:191], v157 offset:50176
	ds_read_b128 v[192:195], v157 offset:51200
	ds_read_b128 v[196:199], v157 offset:52224
	ds_read_b128 v[200:203], v157 offset:53248
	ds_read_b128 v[204:207], v157 offset:54272
	ds_read_b128 v[208:211], v157 offset:55296
	ds_read_b128 v[212:215], v157 offset:56320
	global_load_lds_dwordx4 v[216:217], off
	s_add_i32 m0, s30, 0x2000
	s_add_u32 s28, s28, 0x40080
	v_lshl_add_u64 v[216:217], v[218:219], 0, s[10:11]
	s_addc_u32 s29, s29, 0
	s_add_i32 s30, s55, s35
	global_load_lds_dwordx4 v[216:217], off
	v_lshl_add_u64 v[216:217], s[28:29], 0, v[132:133]
	s_mov_b32 m0, s30
	s_nop 0
	global_load_lds_dwordx4 v[216:217], off
	v_lshl_add_u64 v[216:217], s[28:29], 0, v[128:129]
	s_add_i32 m0, s30, 0x2000
	s_nop 0
	global_load_lds_dwordx4 v[216:217], off
	v_lshl_add_u64 v[216:217], v[220:221], 0, s[10:11]
	s_mov_b32 m0, s42
	s_nop 0
	global_load_lds_dwordx4 v[216:217], off
	v_lshl_add_u64 v[216:217], v[222:223], 0, s[10:11]
	s_mov_b32 m0, s43
	s_nop 0
	global_load_lds_dwordx4 v[216:217], off
	s_waitcnt vmcnt(8)
	s_waitcnt lgkmcnt(0)
	s_barrier
	s_setprio 1
	s_waitcnt lgkmcnt(0)
	v_mfma_f32_16x16x32_bf16 v[60:63], v[144:147], v[184:187], v[60:63]
	v_mfma_f32_16x16x32_bf16 v[60:63], v[148:151], v[188:191], v[60:63]
	v_mfma_f32_16x16x32_bf16 v[56:59], v[160:163], v[184:187], v[56:59]
	v_mfma_f32_16x16x32_bf16 v[56:59], v[164:167], v[188:191], v[56:59]
	v_mfma_f32_16x16x32_bf16 v[44:47], v[144:147], v[192:195], v[44:47]
	v_mfma_f32_16x16x32_bf16 v[44:47], v[148:151], v[196:199], v[44:47]
	v_mfma_f32_16x16x32_bf16 v[40:43], v[160:163], v[192:195], v[40:43]
	v_mfma_f32_16x16x32_bf16 v[40:43], v[164:167], v[196:199], v[40:43]
	v_mfma_f32_16x16x32_bf16 v[28:31], v[144:147], v[200:203], v[28:31]
	v_mfma_f32_16x16x32_bf16 v[28:31], v[148:151], v[204:207], v[28:31]
	v_mfma_f32_16x16x32_bf16 v[24:27], v[160:163], v[200:203], v[24:27]
	v_mfma_f32_16x16x32_bf16 v[24:27], v[164:167], v[204:207], v[24:27]
	v_mfma_f32_16x16x32_bf16 v[12:15], v[144:147], v[208:211], v[12:15]
	v_mfma_f32_16x16x32_bf16 v[12:15], v[148:151], v[212:215], v[12:15]
	v_mfma_f32_16x16x32_bf16 v[8:11], v[160:163], v[208:211], v[8:11]
	v_mfma_f32_16x16x32_bf16 v[8:11], v[164:167], v[212:215], v[8:11]
	s_setprio 0
	s_setprio 1
	v_mfma_f32_16x16x32_bf16 v[52:55], v[168:171], v[184:187], v[52:55]
	v_mfma_f32_16x16x32_bf16 v[52:55], v[172:175], v[188:191], v[52:55]
	v_mfma_f32_16x16x32_bf16 v[48:51], v[176:179], v[184:187], v[48:51]
	v_mfma_f32_16x16x32_bf16 v[48:51], v[180:183], v[188:191], v[48:51]
	v_mfma_f32_16x16x32_bf16 v[36:39], v[168:171], v[192:195], v[36:39]
	v_mfma_f32_16x16x32_bf16 v[36:39], v[172:175], v[196:199], v[36:39]
	v_mfma_f32_16x16x32_bf16 v[32:35], v[176:179], v[192:195], v[32:35]
	v_mfma_f32_16x16x32_bf16 v[32:35], v[180:183], v[196:199], v[32:35]
	v_mfma_f32_16x16x32_bf16 v[20:23], v[168:171], v[200:203], v[20:23]
	v_mfma_f32_16x16x32_bf16 v[20:23], v[172:175], v[204:207], v[20:23]
	v_mfma_f32_16x16x32_bf16 v[16:19], v[176:179], v[200:203], v[16:19]
	v_mfma_f32_16x16x32_bf16 v[16:19], v[180:183], v[204:207], v[16:19]
	v_mfma_f32_16x16x32_bf16 v[4:7], v[168:171], v[208:211], v[4:7]
	v_mfma_f32_16x16x32_bf16 v[4:7], v[172:175], v[212:215], v[4:7]
	v_mfma_f32_16x16x32_bf16 v[0:3], v[176:179], v[208:211], v[0:3]
	v_mfma_f32_16x16x32_bf16 v[0:3], v[180:183], v[212:215], v[0:3]
	s_setprio 0
	s_barrier
	s_add_i32 s53, s53, 2
	s_add_u32 s20, s20, 0x100
	s_addc_u32 s21, s21, 0
	s_add_u32 s51, s51, 0x100
	s_addc_u32 s52, s52, 0
	s_cmp_gt_u32 s53, 13
	s_cbranch_scc0 .LBB0_1014
	s_and_b64 vcc, exec, s[14:15]
	s_cbranch_vccz .LBB0_1017
	s_barrier
